# input-projection epilogue 16-byte stores written through (sc1) to shorten the IN seam L2 writeback
# baseline (speedup 1.0000x reference)
; __device__ __forceinline__ unsigned cvt_pk_bf16(float lo, float hi) { unsigned r; asm volatile("v_cvt_pk_bf16_f32 %0, %1, %2" : "=v"(r) : "v"(lo), "v"(hi)); return r; }
; __device__ __forceinline__ f32x4 gelu4(f32x4 v) { f32x2 a = gelu_pk((f32x2){v[0], v[1]}), b = gelu_pk((f32x2){v[2], v[3]}); return (f32x4){a.x, a.y, b.x, b.y}; }
;     __device__ __forceinline__ void operator()(const f32x4 (&acc)[2][2][4][2], const Unit& u, int wr, int wc, int fr, int fq, int ui) const {
;     ...
;                 for (int bj = 0; bj < 2; ++bj) {
;                     f32x4 v0 = acc[ai][bj][m][0] * rs, v1 = acc[ai][bj][m][1] * rs;
;                     if (sect == 2) { v0 = pg8::gelu4(v0); v1 = pg8::gelu4(v1); }
;                     else {
;                         if (rot) {
;                             f32x4 p0, p1;
; #pragma unroll
;                             for (int i = 0; i < 4; ++i) { p0[i] = __shfl_xor(v0[i], 16); p1[i] = __shfl_xor(v1[i], 16); }
;                             if (fq < 2) { v0 = v0 * c0 + p0 * s0 * sgn; v1 = v1 * c1 + p1 * s1 * sgn; }
;                         }
;                         v0 = v0 * osc; v1 = v1 * osc;
;                     }
;                     u32x4 w; w.x = cvt_pk_bf16(v0[0], v0[1]); w.y = cvt_pk_bf16(v0[2], v0[3]); w.z = cvt_pk_bf16(v1[0], v1[1]); w.w = cvt_pk_bf16(v1[2], v1[3]);
;                     const int cc = colt + bj * 128;
;                     if (sect == 2) *(u32x4*)(base + (size_t)r * DH + cc) = w;
;                     else *(u32x4*)(base + ((size_t)((r >> 13) * 8 + (cc >> 6)) * SEQ + (r & (SEQ - 1))) * 64 + (cc & 63)) = w;
.LBB0_618:
	s_ashr_i32 s51, s50, 31
	s_lshl_b64 s[20:21], s[50:51], 24
	s_add_u32 s82, s12, s20
	s_addc_u32 s83, s13, s21
	s_lshl_b32 s5, s19, 8
	s_and_b32 s5, s5, 0x100
	s_or_b32 s19, s5, s15
	v_bitop3_b32 v0, s19, 56, v183 bitop3:0xc8
	v_lshlrev_b32_e32 v0, 1, v0
	v_lshl_add_u64 v[148:149], s[82:83], 0, v[0:1]
	v_lshlrev_b32_e32 v0, 7, v173
	s_ashr_i32 s5, s4, 10
	v_lshl_add_u64 v[152:153], v[148:149], 0, v[0:1]
	s_and_b32 s20, s5, -8
	s_mov_b64 s[50:51], -1
	s_and_b64 vcc, exec, s[52:53]
	v_cvt_pk_bf16_f32 v138, v146, v147
	v_cvt_pk_bf16_f32 v139, v174, v175
	v_cvt_pk_bf16_f32 v140, v150, v151
	v_cvt_pk_bf16_f32 v141, v176, v177
	s_cbranch_vccz .LBB0_620
	s_lshr_b32 s5, s19, 6
	s_or_b32 s22, s20, s5
	s_ashr_i32 s23, s22, 31
	s_lshl_b64 s[22:23], s[22:23], 20
	v_lshl_add_u64 v[142:143], v[152:153], 0, s[22:23]
	global_store_dwordx4 v[142:143], v[138:141], off sc1
	s_mov_b64 s[50:51], 0
.LBB0_620:
	v_or_b32_e32 v150, s4, v182
	v_ashrrev_i32_e32 v151, 31, v150
	v_or_b32_e32 v0, s19, v183
	v_lshlrev_b64 v[142:143], 10, v[150:151]
	v_lshl_add_u64 v[174:175], s[82:83], 0, v[142:143]
	s_andn2_b64 vcc, exec, s[50:51]
	v_lshlrev_b32_e32 v146, 1, v0
	s_cbranch_vccnz .LBB0_622
	v_mov_b32_e32 v147, v1
	v_lshl_add_u64 v[142:143], v[174:175], 0, v[146:147]
	global_store_dwordx4 v[142:143], v[138:141], off sc1

; __device__ __forceinline__ unsigned cvt_pk_bf16(float lo, float hi) { unsigned r; asm volatile("v_cvt_pk_bf16_f32 %0, %1, %2" : "=v"(r) : "v"(lo), "v"(hi)); return r; }
; __device__ __forceinline__ f32x4 gelu4(f32x4 v) { f32x2 a = gelu_pk((f32x2){v[0], v[1]}), b = gelu_pk((f32x2){v[2], v[3]}); return (f32x4){a.x, a.y, b.x, b.y}; }
;     __device__ __forceinline__ void operator()(const f32x4 (&acc)[2][2][4][2], const Unit& u, int wr, int wc, int fr, int fq, int ui) const {
;     ...
;                 for (int bj = 0; bj < 2; ++bj) {
;                     f32x4 v0 = acc[ai][bj][m][0] * rs, v1 = acc[ai][bj][m][1] * rs;
;                     if (sect == 2) { v0 = pg8::gelu4(v0); v1 = pg8::gelu4(v1); }
;                     else {
;                         if (rot) {
;                             f32x4 p0, p1;
; #pragma unroll
;                             for (int i = 0; i < 4; ++i) { p0[i] = __shfl_xor(v0[i], 16); p1[i] = __shfl_xor(v1[i], 16); }
;                             if (fq < 2) { v0 = v0 * c0 + p0 * s0 * sgn; v1 = v1 * c1 + p1 * s1 * sgn; }
;                         }
;                         v0 = v0 * osc; v1 = v1 * osc;
;                     }
;                     u32x4 w; w.x = cvt_pk_bf16(v0[0], v0[1]); w.y = cvt_pk_bf16(v0[2], v0[3]); w.z = cvt_pk_bf16(v1[0], v1[1]); w.w = cvt_pk_bf16(v1[2], v1[3]);
;                     const int cc = colt + bj * 128;
;                     if (sect == 2) *(u32x4*)(base + (size_t)r * DH + cc) = w;
;                     else *(u32x4*)(base + ((size_t)((r >> 13) * 8 + (cc >> 6)) * SEQ + (r & (SEQ - 1))) * 64 + (cc & 63)) = w;
.LBB0_630:
	v_or_b32_e32 v0, 0x80, v0
	v_lshrrev_b32_e32 v151, 6, v0
	v_cvt_pk_bf16_f32 v130, v138, v139
	s_mov_b64 s[52:53], -1
	s_and_b64 vcc, exec, s[50:51]
	v_or_b32_e32 v138, s20, v151
	v_cvt_pk_bf16_f32 v131, v172, v173
	v_cvt_pk_bf16_f32 v132, v142, v143
	v_cvt_pk_bf16_f32 v133, v140, v141
	s_cbranch_vccnz .LBB0_632
	v_ashrrev_i32_e32 v139, 31, v138
	v_lshlrev_b64 v[134:135], 20, v[138:139]
	v_lshl_add_u64 v[134:135], v[152:153], 0, v[134:135]
	s_mov_b64 s[52:53], 0
	global_store_dwordx4 v[134:135], v[130:133], off sc1
.LBB0_632:
	s_andn2_b64 vcc, exec, s[52:53]
	s_cbranch_vccnz .LBB0_634
	v_mov_b32_e32 v147, v1
	v_lshl_add_u64 v[134:135], v[174:175], 0, v[146:147]
	global_store_dwordx4 v[134:135], v[130:133], off offset:256 sc1

; __device__ __forceinline__ unsigned cvt_pk_bf16(float lo, float hi) { unsigned r; asm volatile("v_cvt_pk_bf16_f32 %0, %1, %2" : "=v"(r) : "v"(lo), "v"(hi)); return r; }
; __device__ __forceinline__ f32x4 gelu4(f32x4 v) { f32x2 a = gelu_pk((f32x2){v[0], v[1]}), b = gelu_pk((f32x2){v[2], v[3]}); return (f32x4){a.x, a.y, b.x, b.y}; }
;     __device__ __forceinline__ void operator()(const f32x4 (&acc)[2][2][4][2], const Unit& u, int wr, int wc, int fr, int fq, int ui) const {
;     ...
;                 for (int bj = 0; bj < 2; ++bj) {
;                     f32x4 v0 = acc[ai][bj][m][0] * rs, v1 = acc[ai][bj][m][1] * rs;
;                     if (sect == 2) { v0 = pg8::gelu4(v0); v1 = pg8::gelu4(v1); }
;                     else {
;                         if (rot) {
;                             f32x4 p0, p1;
; #pragma unroll
;                             for (int i = 0; i < 4; ++i) { p0[i] = __shfl_xor(v0[i], 16); p1[i] = __shfl_xor(v1[i], 16); }
;                             if (fq < 2) { v0 = v0 * c0 + p0 * s0 * sgn; v1 = v1 * c1 + p1 * s1 * sgn; }
;                         }
;                         v0 = v0 * osc; v1 = v1 * osc;
;                     }
;                     u32x4 w; w.x = cvt_pk_bf16(v0[0], v0[1]); w.y = cvt_pk_bf16(v0[2], v0[3]); w.z = cvt_pk_bf16(v1[0], v1[1]); w.w = cvt_pk_bf16(v1[2], v1[3]);
;                     const int cc = colt + bj * 128;
;                     if (sect == 2) *(u32x4*)(base + (size_t)r * DH + cc) = w;
;                     else *(u32x4*)(base + ((size_t)((r >> 13) * 8 + (cc >> 6)) * SEQ + (r & (SEQ - 1))) * 64 + (cc & 63)) = w;
.LBB0_644:
	v_lshlrev_b32_e32 v0, 7, v0
	v_lshl_add_u64 v[130:131], v[148:149], 0, v[0:1]
	s_and_b64 vcc, exec, s[50:51]
	s_mov_b64 s[52:53], -1
	v_cvt_pk_bf16_f32 v122, v132, v133
	v_cvt_pk_bf16_f32 v123, v142, v143
	v_cvt_pk_bf16_f32 v124, v134, v135
	v_cvt_pk_bf16_f32 v125, v136, v137
	s_cbranch_vccnz .LBB0_646
	s_lshr_b32 s4, s19, 6
	s_or_b32 s4, s20, s4
	s_ashr_i32 s5, s4, 31
	s_lshl_b64 s[4:5], s[4:5], 20
	v_lshl_add_u64 v[126:127], v[130:131], 0, s[4:5]
	s_mov_b64 s[52:53], 0
	global_store_dwordx4 v[126:127], v[122:125], off sc1
.LBB0_646:
	v_or_b32_e32 v126, 16, v150
	v_ashrrev_i32_e32 v127, 31, v126
	v_lshlrev_b64 v[126:127], 10, v[126:127]
	s_andn2_b64 vcc, exec, s[52:53]
	v_lshl_add_u64 v[132:133], s[82:83], 0, v[126:127]
	s_cbranch_vccnz .LBB0_648
	v_mov_b32_e32 v147, v1
	v_lshl_add_u64 v[126:127], v[132:133], 0, v[146:147]
	global_store_dwordx4 v[126:127], v[122:125], off sc1

; __device__ __forceinline__ unsigned cvt_pk_bf16(float lo, float hi) { unsigned r; asm volatile("v_cvt_pk_bf16_f32 %0, %1, %2" : "=v"(r) : "v"(lo), "v"(hi)); return r; }
; __device__ __forceinline__ f32x4 gelu4(f32x4 v) { f32x2 a = gelu_pk((f32x2){v[0], v[1]}), b = gelu_pk((f32x2){v[2], v[3]}); return (f32x4){a.x, a.y, b.x, b.y}; }
;     __device__ __forceinline__ void operator()(const f32x4 (&acc)[2][2][4][2], const Unit& u, int wr, int wc, int fr, int fq, int ui) const {
;     ...
;                 for (int bj = 0; bj < 2; ++bj) {
;                     f32x4 v0 = acc[ai][bj][m][0] * rs, v1 = acc[ai][bj][m][1] * rs;
;                     if (sect == 2) { v0 = pg8::gelu4(v0); v1 = pg8::gelu4(v1); }
;                     else {
;                         if (rot) {
;                             f32x4 p0, p1;
; #pragma unroll
;                             for (int i = 0; i < 4; ++i) { p0[i] = __shfl_xor(v0[i], 16); p1[i] = __shfl_xor(v1[i], 16); }
;                             if (fq < 2) { v0 = v0 * c0 + p0 * s0 * sgn; v1 = v1 * c1 + p1 * s1 * sgn; }
;                         }
;                         v0 = v0 * osc; v1 = v1 * osc;
;                     }
;                     u32x4 w; w.x = cvt_pk_bf16(v0[0], v0[1]); w.y = cvt_pk_bf16(v0[2], v0[3]); w.z = cvt_pk_bf16(v1[0], v1[1]); w.w = cvt_pk_bf16(v1[2], v1[3]);
;                     const int cc = colt + bj * 128;
;                     if (sect == 2) *(u32x4*)(base + (size_t)r * DH + cc) = w;
;                     else *(u32x4*)(base + ((size_t)((r >> 13) * 8 + (cc >> 6)) * SEQ + (r & (SEQ - 1))) * 64 + (cc & 63)) = w;
.LBB0_656:
	s_and_b64 vcc, exec, s[50:51]
	s_mov_b64 s[52:53], -1
	v_cvt_pk_bf16_f32 v114, v122, v123
	v_cvt_pk_bf16_f32 v115, v134, v135
	v_cvt_pk_bf16_f32 v116, v126, v127
	v_cvt_pk_bf16_f32 v117, v124, v125
	s_cbranch_vccnz .LBB0_658
	v_ashrrev_i32_e32 v139, 31, v138
	v_lshlrev_b64 v[118:119], 20, v[138:139]
	v_lshl_add_u64 v[118:119], v[130:131], 0, v[118:119]
	s_mov_b64 s[52:53], 0
	global_store_dwordx4 v[118:119], v[114:117], off sc1
.LBB0_658:
	s_andn2_b64 vcc, exec, s[52:53]
	s_cbranch_vccnz .LBB0_660
	v_mov_b32_e32 v147, v1
	v_lshl_add_u64 v[118:119], v[132:133], 0, v[146:147]
	global_store_dwordx4 v[118:119], v[114:117], off offset:256 sc1

; __device__ __forceinline__ unsigned cvt_pk_bf16(float lo, float hi) { unsigned r; asm volatile("v_cvt_pk_bf16_f32 %0, %1, %2" : "=v"(r) : "v"(lo), "v"(hi)); return r; }
; __device__ __forceinline__ f32x4 gelu4(f32x4 v) { f32x2 a = gelu_pk((f32x2){v[0], v[1]}), b = gelu_pk((f32x2){v[2], v[3]}); return (f32x4){a.x, a.y, b.x, b.y}; }
;     __device__ __forceinline__ void operator()(const f32x4 (&acc)[2][2][4][2], const Unit& u, int wr, int wc, int fr, int fq, int ui) const {
;     ...
;                 for (int bj = 0; bj < 2; ++bj) {
;                     f32x4 v0 = acc[ai][bj][m][0] * rs, v1 = acc[ai][bj][m][1] * rs;
;                     if (sect == 2) { v0 = pg8::gelu4(v0); v1 = pg8::gelu4(v1); }
;                     else {
;                         if (rot) {
;                             f32x4 p0, p1;
; #pragma unroll
;                             for (int i = 0; i < 4; ++i) { p0[i] = __shfl_xor(v0[i], 16); p1[i] = __shfl_xor(v1[i], 16); }
;                             if (fq < 2) { v0 = v0 * c0 + p0 * s0 * sgn; v1 = v1 * c1 + p1 * s1 * sgn; }
;                         }
;                         v0 = v0 * osc; v1 = v1 * osc;
;                     }
;                     u32x4 w; w.x = cvt_pk_bf16(v0[0], v0[1]); w.y = cvt_pk_bf16(v0[2], v0[3]); w.z = cvt_pk_bf16(v1[0], v1[1]); w.w = cvt_pk_bf16(v1[2], v1[3]);
;                     const int cc = colt + bj * 128;
;                     if (sect == 2) *(u32x4*)(base + (size_t)r * DH + cc) = w;
;                     else *(u32x4*)(base + ((size_t)((r >> 13) * 8 + (cc >> 6)) * SEQ + (r & (SEQ - 1))) * 64 + (cc & 63)) = w;
.LBB0_670:
	v_lshlrev_b32_e32 v0, 7, v0
	v_lshl_add_u64 v[114:115], v[148:149], 0, v[0:1]
	s_and_b64 vcc, exec, s[50:51]
	s_mov_b64 s[52:53], -1
	v_cvt_pk_bf16_f32 v106, v116, v117
	v_cvt_pk_bf16_f32 v107, v124, v125
	v_cvt_pk_bf16_f32 v108, v118, v119
	v_cvt_pk_bf16_f32 v109, v120, v121
	s_cbranch_vccnz .LBB0_672
	s_lshr_b32 s4, s19, 6
	s_or_b32 s4, s20, s4
	s_ashr_i32 s5, s4, 31
	s_lshl_b64 s[4:5], s[4:5], 20
	v_lshl_add_u64 v[110:111], v[114:115], 0, s[4:5]
	s_mov_b64 s[52:53], 0
	global_store_dwordx4 v[110:111], v[106:109], off sc1
.LBB0_672:
	v_or_b32_e32 v110, 32, v150
	v_ashrrev_i32_e32 v111, 31, v110
	v_lshlrev_b64 v[110:111], 10, v[110:111]
	s_andn2_b64 vcc, exec, s[52:53]
	v_lshl_add_u64 v[116:117], s[82:83], 0, v[110:111]
	s_cbranch_vccnz .LBB0_674
	v_mov_b32_e32 v147, v1
	v_lshl_add_u64 v[110:111], v[116:117], 0, v[146:147]
	global_store_dwordx4 v[110:111], v[106:109], off sc1

; __device__ __forceinline__ unsigned cvt_pk_bf16(float lo, float hi) { unsigned r; asm volatile("v_cvt_pk_bf16_f32 %0, %1, %2" : "=v"(r) : "v"(lo), "v"(hi)); return r; }
; __device__ __forceinline__ f32x4 gelu4(f32x4 v) { f32x2 a = gelu_pk((f32x2){v[0], v[1]}), b = gelu_pk((f32x2){v[2], v[3]}); return (f32x4){a.x, a.y, b.x, b.y}; }
;     __device__ __forceinline__ void operator()(const f32x4 (&acc)[2][2][4][2], const Unit& u, int wr, int wc, int fr, int fq, int ui) const {
;     ...
;                 for (int bj = 0; bj < 2; ++bj) {
;                     f32x4 v0 = acc[ai][bj][m][0] * rs, v1 = acc[ai][bj][m][1] * rs;
;                     if (sect == 2) { v0 = pg8::gelu4(v0); v1 = pg8::gelu4(v1); }
;                     else {
;                         if (rot) {
;                             f32x4 p0, p1;
; #pragma unroll
;                             for (int i = 0; i < 4; ++i) { p0[i] = __shfl_xor(v0[i], 16); p1[i] = __shfl_xor(v1[i], 16); }
;                             if (fq < 2) { v0 = v0 * c0 + p0 * s0 * sgn; v1 = v1 * c1 + p1 * s1 * sgn; }
;                         }
;                         v0 = v0 * osc; v1 = v1 * osc;
;                     }
;                     u32x4 w; w.x = cvt_pk_bf16(v0[0], v0[1]); w.y = cvt_pk_bf16(v0[2], v0[3]); w.z = cvt_pk_bf16(v1[0], v1[1]); w.w = cvt_pk_bf16(v1[2], v1[3]);
;                     const int cc = colt + bj * 128;
;                     if (sect == 2) *(u32x4*)(base + (size_t)r * DH + cc) = w;
;                     else *(u32x4*)(base + ((size_t)((r >> 13) * 8 + (cc >> 6)) * SEQ + (r & (SEQ - 1))) * 64 + (cc & 63)) = w;
.LBB0_682:
	s_and_b64 vcc, exec, s[50:51]
	s_mov_b64 s[52:53], -1
	v_cvt_pk_bf16_f32 v98, v106, v107
	v_cvt_pk_bf16_f32 v99, v118, v119
	v_cvt_pk_bf16_f32 v100, v110, v111
	v_cvt_pk_bf16_f32 v101, v108, v109
	s_cbranch_vccnz .LBB0_684
	v_ashrrev_i32_e32 v139, 31, v138
	v_lshlrev_b64 v[102:103], 20, v[138:139]
	v_lshl_add_u64 v[102:103], v[114:115], 0, v[102:103]
	s_mov_b64 s[52:53], 0
	global_store_dwordx4 v[102:103], v[98:101], off sc1
.LBB0_684:
	s_andn2_b64 vcc, exec, s[52:53]
	s_cbranch_vccnz .LBB0_686
	v_mov_b32_e32 v147, v1
	v_lshl_add_u64 v[102:103], v[116:117], 0, v[146:147]
	global_store_dwordx4 v[102:103], v[98:101], off offset:256 sc1

; __device__ __forceinline__ unsigned cvt_pk_bf16(float lo, float hi) { unsigned r; asm volatile("v_cvt_pk_bf16_f32 %0, %1, %2" : "=v"(r) : "v"(lo), "v"(hi)); return r; }
; __device__ __forceinline__ f32x4 gelu4(f32x4 v) { f32x2 a = gelu_pk((f32x2){v[0], v[1]}), b = gelu_pk((f32x2){v[2], v[3]}); return (f32x4){a.x, a.y, b.x, b.y}; }
;     __device__ __forceinline__ void operator()(const f32x4 (&acc)[2][2][4][2], const Unit& u, int wr, int wc, int fr, int fq, int ui) const {
;     ...
;                 for (int bj = 0; bj < 2; ++bj) {
;                     f32x4 v0 = acc[ai][bj][m][0] * rs, v1 = acc[ai][bj][m][1] * rs;
;                     if (sect == 2) { v0 = pg8::gelu4(v0); v1 = pg8::gelu4(v1); }
;                     else {
;                         if (rot) {
;                             f32x4 p0, p1;
; #pragma unroll
;                             for (int i = 0; i < 4; ++i) { p0[i] = __shfl_xor(v0[i], 16); p1[i] = __shfl_xor(v1[i], 16); }
;                             if (fq < 2) { v0 = v0 * c0 + p0 * s0 * sgn; v1 = v1 * c1 + p1 * s1 * sgn; }
;                         }
;                         v0 = v0 * osc; v1 = v1 * osc;
;                     }
;                     u32x4 w; w.x = cvt_pk_bf16(v0[0], v0[1]); w.y = cvt_pk_bf16(v0[2], v0[3]); w.z = cvt_pk_bf16(v1[0], v1[1]); w.w = cvt_pk_bf16(v1[2], v1[3]);
;                     const int cc = colt + bj * 128;
;                     if (sect == 2) *(u32x4*)(base + (size_t)r * DH + cc) = w;
;                     else *(u32x4*)(base + ((size_t)((r >> 13) * 8 + (cc >> 6)) * SEQ + (r & (SEQ - 1))) * 64 + (cc & 63)) = w;
.LBB0_696:
	v_lshlrev_b32_e32 v0, 7, v0
	v_lshl_add_u64 v[98:99], v[148:149], 0, v[0:1]
	s_and_b64 vcc, exec, s[50:51]
	s_mov_b64 s[52:53], -1
	v_cvt_pk_bf16_f32 v90, v100, v101
	v_cvt_pk_bf16_f32 v91, v108, v109
	v_cvt_pk_bf16_f32 v92, v102, v103
	v_cvt_pk_bf16_f32 v93, v104, v105
	s_cbranch_vccnz .LBB0_698
	s_lshr_b32 s4, s19, 6
	s_or_b32 s4, s20, s4
	s_ashr_i32 s5, s4, 31
	s_lshl_b64 s[4:5], s[4:5], 20
	v_lshl_add_u64 v[94:95], v[98:99], 0, s[4:5]
	s_mov_b64 s[52:53], 0
	global_store_dwordx4 v[94:95], v[90:93], off sc1
.LBB0_698:
	v_or_b32_e32 v94, 48, v150
	v_ashrrev_i32_e32 v95, 31, v94
	v_lshlrev_b64 v[94:95], 10, v[94:95]
	s_andn2_b64 vcc, exec, s[52:53]
	v_lshl_add_u64 v[100:101], s[82:83], 0, v[94:95]
	s_cbranch_vccnz .LBB0_700
	v_mov_b32_e32 v147, v1
	v_lshl_add_u64 v[94:95], v[100:101], 0, v[146:147]
	global_store_dwordx4 v[94:95], v[90:93], off sc1

; __device__ __forceinline__ unsigned cvt_pk_bf16(float lo, float hi) { unsigned r; asm volatile("v_cvt_pk_bf16_f32 %0, %1, %2" : "=v"(r) : "v"(lo), "v"(hi)); return r; }
; __device__ __forceinline__ f32x4 gelu4(f32x4 v) { f32x2 a = gelu_pk((f32x2){v[0], v[1]}), b = gelu_pk((f32x2){v[2], v[3]}); return (f32x4){a.x, a.y, b.x, b.y}; }
;     __device__ __forceinline__ void operator()(const f32x4 (&acc)[2][2][4][2], const Unit& u, int wr, int wc, int fr, int fq, int ui) const {
;     ...
;                 for (int bj = 0; bj < 2; ++bj) {
;                     f32x4 v0 = acc[ai][bj][m][0] * rs, v1 = acc[ai][bj][m][1] * rs;
;                     if (sect == 2) { v0 = pg8::gelu4(v0); v1 = pg8::gelu4(v1); }
;                     else {
;                         if (rot) {
;                             f32x4 p0, p1;
; #pragma unroll
;                             for (int i = 0; i < 4; ++i) { p0[i] = __shfl_xor(v0[i], 16); p1[i] = __shfl_xor(v1[i], 16); }
;                             if (fq < 2) { v0 = v0 * c0 + p0 * s0 * sgn; v1 = v1 * c1 + p1 * s1 * sgn; }
;                         }
;                         v0 = v0 * osc; v1 = v1 * osc;
;                     }
;                     u32x4 w; w.x = cvt_pk_bf16(v0[0], v0[1]); w.y = cvt_pk_bf16(v0[2], v0[3]); w.z = cvt_pk_bf16(v1[0], v1[1]); w.w = cvt_pk_bf16(v1[2], v1[3]);
;                     const int cc = colt + bj * 128;
;                     if (sect == 2) *(u32x4*)(base + (size_t)r * DH + cc) = w;
;                     else *(u32x4*)(base + ((size_t)((r >> 13) * 8 + (cc >> 6)) * SEQ + (r & (SEQ - 1))) * 64 + (cc & 63)) = w;
.LBB0_708:
	s_and_b64 vcc, exec, s[50:51]
	s_mov_b64 s[52:53], -1
	v_cvt_pk_bf16_f32 v82, v90, v91
	v_cvt_pk_bf16_f32 v83, v102, v103
	v_cvt_pk_bf16_f32 v84, v94, v95
	v_cvt_pk_bf16_f32 v85, v92, v93
	s_cbranch_vccnz .LBB0_710
	v_ashrrev_i32_e32 v139, 31, v138
	v_lshlrev_b64 v[86:87], 20, v[138:139]
	v_lshl_add_u64 v[86:87], v[98:99], 0, v[86:87]
	s_mov_b64 s[52:53], 0
	global_store_dwordx4 v[86:87], v[82:85], off sc1
.LBB0_710:
	s_andn2_b64 vcc, exec, s[52:53]
	s_cbranch_vccnz .LBB0_712
	v_mov_b32_e32 v147, v1
	v_lshl_add_u64 v[86:87], v[100:101], 0, v[146:147]
	global_store_dwordx4 v[86:87], v[82:85], off offset:256 sc1

; __device__ __forceinline__ unsigned cvt_pk_bf16(float lo, float hi) { unsigned r; asm volatile("v_cvt_pk_bf16_f32 %0, %1, %2" : "=v"(r) : "v"(lo), "v"(hi)); return r; }
; __device__ __forceinline__ f32x4 gelu4(f32x4 v) { f32x2 a = gelu_pk((f32x2){v[0], v[1]}), b = gelu_pk((f32x2){v[2], v[3]}); return (f32x4){a.x, a.y, b.x, b.y}; }
;     __device__ __forceinline__ void operator()(const f32x4 (&acc)[2][2][4][2], const Unit& u, int wr, int wc, int fr, int fq, int ui) const {
;     ...
;                 for (int bj = 0; bj < 2; ++bj) {
;                     f32x4 v0 = acc[ai][bj][m][0] * rs, v1 = acc[ai][bj][m][1] * rs;
;                     if (sect == 2) { v0 = pg8::gelu4(v0); v1 = pg8::gelu4(v1); }
;                     else {
;                         if (rot) {
;                             f32x4 p0, p1;
; #pragma unroll
;                             for (int i = 0; i < 4; ++i) { p0[i] = __shfl_xor(v0[i], 16); p1[i] = __shfl_xor(v1[i], 16); }
;                             if (fq < 2) { v0 = v0 * c0 + p0 * s0 * sgn; v1 = v1 * c1 + p1 * s1 * sgn; }
;                         }
;                         v0 = v0 * osc; v1 = v1 * osc;
;                     }
;                     u32x4 w; w.x = cvt_pk_bf16(v0[0], v0[1]); w.y = cvt_pk_bf16(v0[2], v0[3]); w.z = cvt_pk_bf16(v1[0], v1[1]); w.w = cvt_pk_bf16(v1[2], v1[3]);
;                     const int cc = colt + bj * 128;
;                     if (sect == 2) *(u32x4*)(base + (size_t)r * DH + cc) = w;
;                     else *(u32x4*)(base + ((size_t)((r >> 13) * 8 + (cc >> 6)) * SEQ + (r & (SEQ - 1))) * 64 + (cc & 63)) = w;
.LBB0_722:
	v_lshlrev_b32_e32 v0, 7, v0
	v_lshl_add_u64 v[82:83], v[148:149], 0, v[0:1]
	v_ashrrev_i32_e32 v0, 10, v90
	v_and_b32_e32 v96, -8, v0
	s_and_b64 vcc, exec, s[50:51]
	s_mov_b64 s[52:53], -1
	v_cvt_pk_bf16_f32 v74, v84, v85
	v_cvt_pk_bf16_f32 v75, v94, v95
	v_cvt_pk_bf16_f32 v76, v86, v87
	v_cvt_pk_bf16_f32 v77, v88, v89
	s_cbranch_vccnz .LBB0_724
	s_lshr_b32 s4, s19, 6
	v_or_b32_e32 v78, s4, v96
	v_ashrrev_i32_e32 v79, 31, v78
	v_lshlrev_b64 v[78:79], 20, v[78:79]
	v_lshl_add_u64 v[78:79], v[82:83], 0, v[78:79]
	s_mov_b64 s[52:53], 0
	global_store_dwordx4 v[78:79], v[74:77], off sc1
.LBB0_724:
	v_ashrrev_i32_e32 v91, 31, v90
	v_lshlrev_b64 v[78:79], 10, v[90:91]
	s_andn2_b64 vcc, exec, s[52:53]
	v_lshl_add_u64 v[84:85], s[82:83], 0, v[78:79]
	s_cbranch_vccnz .LBB0_726
	v_mov_b32_e32 v147, v1
	v_lshl_add_u64 v[78:79], v[84:85], 0, v[146:147]
	global_store_dwordx4 v[78:79], v[74:77], off sc1

; __device__ __forceinline__ unsigned cvt_pk_bf16(float lo, float hi) { unsigned r; asm volatile("v_cvt_pk_bf16_f32 %0, %1, %2" : "=v"(r) : "v"(lo), "v"(hi)); return r; }
; __device__ __forceinline__ f32x4 gelu4(f32x4 v) { f32x2 a = gelu_pk((f32x2){v[0], v[1]}), b = gelu_pk((f32x2){v[2], v[3]}); return (f32x4){a.x, a.y, b.x, b.y}; }
;     __device__ __forceinline__ void operator()(const f32x4 (&acc)[2][2][4][2], const Unit& u, int wr, int wc, int fr, int fq, int ui) const {
;     ...
;                 for (int bj = 0; bj < 2; ++bj) {
;                     f32x4 v0 = acc[ai][bj][m][0] * rs, v1 = acc[ai][bj][m][1] * rs;
;                     if (sect == 2) { v0 = pg8::gelu4(v0); v1 = pg8::gelu4(v1); }
;                     else {
;                         if (rot) {
;                             f32x4 p0, p1;
; #pragma unroll
;                             for (int i = 0; i < 4; ++i) { p0[i] = __shfl_xor(v0[i], 16); p1[i] = __shfl_xor(v1[i], 16); }
;                             if (fq < 2) { v0 = v0 * c0 + p0 * s0 * sgn; v1 = v1 * c1 + p1 * s1 * sgn; }
;                         }
;                         v0 = v0 * osc; v1 = v1 * osc;
;                     }
;                     u32x4 w; w.x = cvt_pk_bf16(v0[0], v0[1]); w.y = cvt_pk_bf16(v0[2], v0[3]); w.z = cvt_pk_bf16(v1[0], v1[1]); w.w = cvt_pk_bf16(v1[2], v1[3]);
;                     const int cc = colt + bj * 128;
;                     if (sect == 2) *(u32x4*)(base + (size_t)r * DH + cc) = w;
;                     else *(u32x4*)(base + ((size_t)((r >> 13) * 8 + (cc >> 6)) * SEQ + (r & (SEQ - 1))) * 64 + (cc & 63)) = w;
.LBB0_734:
	v_cvt_pk_bf16_f32 v66, v74, v75
	s_mov_b64 s[52:53], -1
	s_and_b64 vcc, exec, s[50:51]
	v_or_b32_e32 v74, v96, v151
	v_cvt_pk_bf16_f32 v67, v86, v87
	v_cvt_pk_bf16_f32 v68, v78, v79
	v_cvt_pk_bf16_f32 v69, v76, v77
	s_cbranch_vccnz .LBB0_736
	v_ashrrev_i32_e32 v75, 31, v74
	v_lshlrev_b64 v[70:71], 20, v[74:75]
	v_lshl_add_u64 v[70:71], v[82:83], 0, v[70:71]
	s_mov_b64 s[52:53], 0
	global_store_dwordx4 v[70:71], v[66:69], off sc1
.LBB0_736:
	s_andn2_b64 vcc, exec, s[52:53]
	s_cbranch_vccnz .LBB0_738
	v_mov_b32_e32 v147, v1
	v_lshl_add_u64 v[70:71], v[84:85], 0, v[146:147]
	global_store_dwordx4 v[70:71], v[66:69], off offset:256 sc1

; __device__ __forceinline__ unsigned cvt_pk_bf16(float lo, float hi) { unsigned r; asm volatile("v_cvt_pk_bf16_f32 %0, %1, %2" : "=v"(r) : "v"(lo), "v"(hi)); return r; }
; __device__ __forceinline__ f32x4 gelu4(f32x4 v) { f32x2 a = gelu_pk((f32x2){v[0], v[1]}), b = gelu_pk((f32x2){v[2], v[3]}); return (f32x4){a.x, a.y, b.x, b.y}; }
;     __device__ __forceinline__ void operator()(const f32x4 (&acc)[2][2][4][2], const Unit& u, int wr, int wc, int fr, int fq, int ui) const {
;     ...
;                 for (int bj = 0; bj < 2; ++bj) {
;                     f32x4 v0 = acc[ai][bj][m][0] * rs, v1 = acc[ai][bj][m][1] * rs;
;                     if (sect == 2) { v0 = pg8::gelu4(v0); v1 = pg8::gelu4(v1); }
;                     else {
;                         if (rot) {
;                             f32x4 p0, p1;
; #pragma unroll
;                             for (int i = 0; i < 4; ++i) { p0[i] = __shfl_xor(v0[i], 16); p1[i] = __shfl_xor(v1[i], 16); }
;                             if (fq < 2) { v0 = v0 * c0 + p0 * s0 * sgn; v1 = v1 * c1 + p1 * s1 * sgn; }
;                         }
;                         v0 = v0 * osc; v1 = v1 * osc;
;                     }
;                     u32x4 w; w.x = cvt_pk_bf16(v0[0], v0[1]); w.y = cvt_pk_bf16(v0[2], v0[3]); w.z = cvt_pk_bf16(v1[0], v1[1]); w.w = cvt_pk_bf16(v1[2], v1[3]);
;                     const int cc = colt + bj * 128;
;                     if (sect == 2) *(u32x4*)(base + (size_t)r * DH + cc) = w;
;                     else *(u32x4*)(base + ((size_t)((r >> 13) * 8 + (cc >> 6)) * SEQ + (r & (SEQ - 1))) * 64 + (cc & 63)) = w;
.LBB0_748:
	v_lshlrev_b32_e32 v0, 7, v0
	v_lshl_add_u64 v[66:67], v[148:149], 0, v[0:1]
	s_and_b64 vcc, exec, s[50:51]
	s_mov_b64 s[52:53], -1
	v_cvt_pk_bf16_f32 v58, v68, v69
	v_cvt_pk_bf16_f32 v59, v78, v79
	v_cvt_pk_bf16_f32 v60, v70, v71
	v_cvt_pk_bf16_f32 v61, v72, v73
	s_cbranch_vccnz .LBB0_750
	s_lshr_b32 s4, s19, 6
	v_or_b32_e32 v62, s4, v96
	v_ashrrev_i32_e32 v63, 31, v62
	v_lshlrev_b64 v[62:63], 20, v[62:63]
	v_lshl_add_u64 v[62:63], v[66:67], 0, v[62:63]
	s_mov_b64 s[52:53], 0
	global_store_dwordx4 v[62:63], v[58:61], off sc1
.LBB0_750:
	v_or_b32_e32 v62, 16, v90
	v_ashrrev_i32_e32 v63, 31, v62
	v_lshlrev_b64 v[62:63], 10, v[62:63]
	s_andn2_b64 vcc, exec, s[52:53]
	v_lshl_add_u64 v[68:69], s[82:83], 0, v[62:63]
	s_cbranch_vccnz .LBB0_752
	v_mov_b32_e32 v147, v1
	v_lshl_add_u64 v[62:63], v[68:69], 0, v[146:147]
	global_store_dwordx4 v[62:63], v[58:61], off sc1

; __device__ __forceinline__ unsigned cvt_pk_bf16(float lo, float hi) { unsigned r; asm volatile("v_cvt_pk_bf16_f32 %0, %1, %2" : "=v"(r) : "v"(lo), "v"(hi)); return r; }
; __device__ __forceinline__ f32x4 gelu4(f32x4 v) { f32x2 a = gelu_pk((f32x2){v[0], v[1]}), b = gelu_pk((f32x2){v[2], v[3]}); return (f32x4){a.x, a.y, b.x, b.y}; }
;     __device__ __forceinline__ void operator()(const f32x4 (&acc)[2][2][4][2], const Unit& u, int wr, int wc, int fr, int fq, int ui) const {
;     ...
;                 for (int bj = 0; bj < 2; ++bj) {
;                     f32x4 v0 = acc[ai][bj][m][0] * rs, v1 = acc[ai][bj][m][1] * rs;
;                     if (sect == 2) { v0 = pg8::gelu4(v0); v1 = pg8::gelu4(v1); }
;                     else {
;                         if (rot) {
;                             f32x4 p0, p1;
; #pragma unroll
;                             for (int i = 0; i < 4; ++i) { p0[i] = __shfl_xor(v0[i], 16); p1[i] = __shfl_xor(v1[i], 16); }
;                             if (fq < 2) { v0 = v0 * c0 + p0 * s0 * sgn; v1 = v1 * c1 + p1 * s1 * sgn; }
;                         }
;                         v0 = v0 * osc; v1 = v1 * osc;
;                     }
;                     u32x4 w; w.x = cvt_pk_bf16(v0[0], v0[1]); w.y = cvt_pk_bf16(v0[2], v0[3]); w.z = cvt_pk_bf16(v1[0], v1[1]); w.w = cvt_pk_bf16(v1[2], v1[3]);
;                     const int cc = colt + bj * 128;
;                     if (sect == 2) *(u32x4*)(base + (size_t)r * DH + cc) = w;
;                     else *(u32x4*)(base + ((size_t)((r >> 13) * 8 + (cc >> 6)) * SEQ + (r & (SEQ - 1))) * 64 + (cc & 63)) = w;
.LBB0_760:
	s_and_b64 vcc, exec, s[50:51]
	s_mov_b64 s[52:53], -1
	v_cvt_pk_bf16_f32 v50, v58, v59
	v_cvt_pk_bf16_f32 v51, v70, v71
	v_cvt_pk_bf16_f32 v52, v62, v63
	v_cvt_pk_bf16_f32 v53, v60, v61
	s_cbranch_vccnz .LBB0_762
	v_ashrrev_i32_e32 v75, 31, v74
	v_lshlrev_b64 v[54:55], 20, v[74:75]
	v_lshl_add_u64 v[54:55], v[66:67], 0, v[54:55]
	s_mov_b64 s[52:53], 0
	global_store_dwordx4 v[54:55], v[50:53], off sc1
.LBB0_762:
	s_andn2_b64 vcc, exec, s[52:53]
	s_cbranch_vccnz .LBB0_764
	v_mov_b32_e32 v147, v1
	v_lshl_add_u64 v[54:55], v[68:69], 0, v[146:147]
	global_store_dwordx4 v[54:55], v[50:53], off offset:256 sc1

; __device__ __forceinline__ unsigned cvt_pk_bf16(float lo, float hi) { unsigned r; asm volatile("v_cvt_pk_bf16_f32 %0, %1, %2" : "=v"(r) : "v"(lo), "v"(hi)); return r; }
; __device__ __forceinline__ f32x4 gelu4(f32x4 v) { f32x2 a = gelu_pk((f32x2){v[0], v[1]}), b = gelu_pk((f32x2){v[2], v[3]}); return (f32x4){a.x, a.y, b.x, b.y}; }
;     __device__ __forceinline__ void operator()(const f32x4 (&acc)[2][2][4][2], const Unit& u, int wr, int wc, int fr, int fq, int ui) const {
;     ...
;                 for (int bj = 0; bj < 2; ++bj) {
;                     f32x4 v0 = acc[ai][bj][m][0] * rs, v1 = acc[ai][bj][m][1] * rs;
;                     if (sect == 2) { v0 = pg8::gelu4(v0); v1 = pg8::gelu4(v1); }
;                     else {
;                         if (rot) {
;                             f32x4 p0, p1;
; #pragma unroll
;                             for (int i = 0; i < 4; ++i) { p0[i] = __shfl_xor(v0[i], 16); p1[i] = __shfl_xor(v1[i], 16); }
;                             if (fq < 2) { v0 = v0 * c0 + p0 * s0 * sgn; v1 = v1 * c1 + p1 * s1 * sgn; }
;                         }
;                         v0 = v0 * osc; v1 = v1 * osc;
;                     }
;                     u32x4 w; w.x = cvt_pk_bf16(v0[0], v0[1]); w.y = cvt_pk_bf16(v0[2], v0[3]); w.z = cvt_pk_bf16(v1[0], v1[1]); w.w = cvt_pk_bf16(v1[2], v1[3]);
;                     const int cc = colt + bj * 128;
;                     if (sect == 2) *(u32x4*)(base + (size_t)r * DH + cc) = w;
;                     else *(u32x4*)(base + ((size_t)((r >> 13) * 8 + (cc >> 6)) * SEQ + (r & (SEQ - 1))) * 64 + (cc & 63)) = w;
.LBB0_774:
	v_lshlrev_b32_e32 v0, 7, v0
	v_lshl_add_u64 v[50:51], v[148:149], 0, v[0:1]
	s_and_b64 vcc, exec, s[50:51]
	s_mov_b64 s[52:53], -1
	v_cvt_pk_bf16_f32 v42, v52, v53
	v_cvt_pk_bf16_f32 v43, v60, v61
	v_cvt_pk_bf16_f32 v44, v54, v55
	v_cvt_pk_bf16_f32 v45, v56, v57
	s_cbranch_vccnz .LBB0_776
	s_lshr_b32 s4, s19, 6
	v_or_b32_e32 v46, s4, v96
	v_ashrrev_i32_e32 v47, 31, v46
	v_lshlrev_b64 v[46:47], 20, v[46:47]
	v_lshl_add_u64 v[46:47], v[50:51], 0, v[46:47]
	s_mov_b64 s[52:53], 0
	global_store_dwordx4 v[46:47], v[42:45], off sc1
.LBB0_776:
	v_or_b32_e32 v46, 32, v90
	v_ashrrev_i32_e32 v47, 31, v46
	v_lshlrev_b64 v[46:47], 10, v[46:47]
	s_andn2_b64 vcc, exec, s[52:53]
	v_lshl_add_u64 v[52:53], s[82:83], 0, v[46:47]
	s_cbranch_vccnz .LBB0_778
	v_mov_b32_e32 v147, v1
	v_lshl_add_u64 v[46:47], v[52:53], 0, v[146:147]
	global_store_dwordx4 v[46:47], v[42:45], off sc1

; __device__ __forceinline__ unsigned cvt_pk_bf16(float lo, float hi) { unsigned r; asm volatile("v_cvt_pk_bf16_f32 %0, %1, %2" : "=v"(r) : "v"(lo), "v"(hi)); return r; }
; __device__ __forceinline__ f32x4 gelu4(f32x4 v) { f32x2 a = gelu_pk((f32x2){v[0], v[1]}), b = gelu_pk((f32x2){v[2], v[3]}); return (f32x4){a.x, a.y, b.x, b.y}; }
;     __device__ __forceinline__ void operator()(const f32x4 (&acc)[2][2][4][2], const Unit& u, int wr, int wc, int fr, int fq, int ui) const {
;     ...
;                 for (int bj = 0; bj < 2; ++bj) {
;                     f32x4 v0 = acc[ai][bj][m][0] * rs, v1 = acc[ai][bj][m][1] * rs;
;                     if (sect == 2) { v0 = pg8::gelu4(v0); v1 = pg8::gelu4(v1); }
;                     else {
;                         if (rot) {
;                             f32x4 p0, p1;
; #pragma unroll
;                             for (int i = 0; i < 4; ++i) { p0[i] = __shfl_xor(v0[i], 16); p1[i] = __shfl_xor(v1[i], 16); }
;                             if (fq < 2) { v0 = v0 * c0 + p0 * s0 * sgn; v1 = v1 * c1 + p1 * s1 * sgn; }
;                         }
;                         v0 = v0 * osc; v1 = v1 * osc;
;                     }
;                     u32x4 w; w.x = cvt_pk_bf16(v0[0], v0[1]); w.y = cvt_pk_bf16(v0[2], v0[3]); w.z = cvt_pk_bf16(v1[0], v1[1]); w.w = cvt_pk_bf16(v1[2], v1[3]);
;                     const int cc = colt + bj * 128;
;                     if (sect == 2) *(u32x4*)(base + (size_t)r * DH + cc) = w;
;                     else *(u32x4*)(base + ((size_t)((r >> 13) * 8 + (cc >> 6)) * SEQ + (r & (SEQ - 1))) * 64 + (cc & 63)) = w;
.LBB0_786:
	s_and_b64 vcc, exec, s[50:51]
	s_mov_b64 s[52:53], -1
	v_cvt_pk_bf16_f32 v34, v42, v43
	v_cvt_pk_bf16_f32 v35, v54, v55
	v_cvt_pk_bf16_f32 v36, v46, v47
	v_cvt_pk_bf16_f32 v37, v44, v45
	s_cbranch_vccnz .LBB0_788
	v_ashrrev_i32_e32 v75, 31, v74
	v_lshlrev_b64 v[38:39], 20, v[74:75]
	v_lshl_add_u64 v[38:39], v[50:51], 0, v[38:39]
	s_mov_b64 s[52:53], 0
	global_store_dwordx4 v[38:39], v[34:37], off sc1
.LBB0_788:
	s_andn2_b64 vcc, exec, s[52:53]
	s_cbranch_vccnz .LBB0_790
	v_mov_b32_e32 v147, v1
	v_lshl_add_u64 v[38:39], v[52:53], 0, v[146:147]
	global_store_dwordx4 v[38:39], v[34:37], off offset:256 sc1

; __device__ __forceinline__ unsigned cvt_pk_bf16(float lo, float hi) { unsigned r; asm volatile("v_cvt_pk_bf16_f32 %0, %1, %2" : "=v"(r) : "v"(lo), "v"(hi)); return r; }
; __device__ __forceinline__ f32x4 gelu4(f32x4 v) { f32x2 a = gelu_pk((f32x2){v[0], v[1]}), b = gelu_pk((f32x2){v[2], v[3]}); return (f32x4){a.x, a.y, b.x, b.y}; }
;     __device__ __forceinline__ void operator()(const f32x4 (&acc)[2][2][4][2], const Unit& u, int wr, int wc, int fr, int fq, int ui) const {
;     ...
;                 for (int bj = 0; bj < 2; ++bj) {
;                     f32x4 v0 = acc[ai][bj][m][0] * rs, v1 = acc[ai][bj][m][1] * rs;
;                     if (sect == 2) { v0 = pg8::gelu4(v0); v1 = pg8::gelu4(v1); }
;                     else {
;                         if (rot) {
;                             f32x4 p0, p1;
; #pragma unroll
;                             for (int i = 0; i < 4; ++i) { p0[i] = __shfl_xor(v0[i], 16); p1[i] = __shfl_xor(v1[i], 16); }
;                             if (fq < 2) { v0 = v0 * c0 + p0 * s0 * sgn; v1 = v1 * c1 + p1 * s1 * sgn; }
;                         }
;                         v0 = v0 * osc; v1 = v1 * osc;
;                     }
;                     u32x4 w; w.x = cvt_pk_bf16(v0[0], v0[1]); w.y = cvt_pk_bf16(v0[2], v0[3]); w.z = cvt_pk_bf16(v1[0], v1[1]); w.w = cvt_pk_bf16(v1[2], v1[3]);
;                     const int cc = colt + bj * 128;
;                     if (sect == 2) *(u32x4*)(base + (size_t)r * DH + cc) = w;
;                     else *(u32x4*)(base + ((size_t)((r >> 13) * 8 + (cc >> 6)) * SEQ + (r & (SEQ - 1))) * 64 + (cc & 63)) = w;
.LBB0_800:
	v_lshlrev_b32_e32 v0, 7, v0
	v_lshl_add_u64 v[34:35], v[148:149], 0, v[0:1]
	s_and_b64 vcc, exec, s[50:51]
	s_mov_b64 s[52:53], -1
	v_cvt_pk_bf16_f32 v10, v36, v37
	v_cvt_pk_bf16_f32 v11, v44, v45
	v_cvt_pk_bf16_f32 v12, v38, v39
	v_cvt_pk_bf16_f32 v13, v40, v41
	s_cbranch_vccnz .LBB0_802
	s_lshr_b32 s4, s19, 6
	v_or_b32_e32 v14, s4, v96
	v_ashrrev_i32_e32 v15, 31, v14
	v_lshlrev_b64 v[14:15], 20, v[14:15]
	v_lshl_add_u64 v[14:15], v[34:35], 0, v[14:15]
	s_mov_b64 s[52:53], 0
	global_store_dwordx4 v[14:15], v[10:13], off sc1
.LBB0_802:
	v_or_b32_e32 v14, 48, v90
	v_ashrrev_i32_e32 v15, 31, v14
	v_lshlrev_b64 v[14:15], 10, v[14:15]
	s_andn2_b64 vcc, exec, s[52:53]
	v_lshl_add_u64 v[36:37], s[82:83], 0, v[14:15]
	s_cbranch_vccnz .LBB0_804
	v_mov_b32_e32 v147, v1
	v_lshl_add_u64 v[14:15], v[36:37], 0, v[146:147]
	global_store_dwordx4 v[14:15], v[10:13], off sc1

; __device__ __forceinline__ unsigned cvt_pk_bf16(float lo, float hi) { unsigned r; asm volatile("v_cvt_pk_bf16_f32 %0, %1, %2" : "=v"(r) : "v"(lo), "v"(hi)); return r; }
; __device__ __forceinline__ f32x4 gelu4(f32x4 v) { f32x2 a = gelu_pk((f32x2){v[0], v[1]}), b = gelu_pk((f32x2){v[2], v[3]}); return (f32x4){a.x, a.y, b.x, b.y}; }
;     __device__ __forceinline__ void operator()(const f32x4 (&acc)[2][2][4][2], const Unit& u, int wr, int wc, int fr, int fq, int ui) const {
;     ...
;                 for (int bj = 0; bj < 2; ++bj) {
;                     f32x4 v0 = acc[ai][bj][m][0] * rs, v1 = acc[ai][bj][m][1] * rs;
;                     if (sect == 2) { v0 = pg8::gelu4(v0); v1 = pg8::gelu4(v1); }
;                     else {
;                         if (rot) {
;                             f32x4 p0, p1;
; #pragma unroll
;                             for (int i = 0; i < 4; ++i) { p0[i] = __shfl_xor(v0[i], 16); p1[i] = __shfl_xor(v1[i], 16); }
;                             if (fq < 2) { v0 = v0 * c0 + p0 * s0 * sgn; v1 = v1 * c1 + p1 * s1 * sgn; }
;                         }
;                         v0 = v0 * osc; v1 = v1 * osc;
;                     }
;                     u32x4 w; w.x = cvt_pk_bf16(v0[0], v0[1]); w.y = cvt_pk_bf16(v0[2], v0[3]); w.z = cvt_pk_bf16(v1[0], v1[1]); w.w = cvt_pk_bf16(v1[2], v1[3]);
;                     const int cc = colt + bj * 128;
;                     if (sect == 2) *(u32x4*)(base + (size_t)r * DH + cc) = w;
;                     else *(u32x4*)(base + ((size_t)((r >> 13) * 8 + (cc >> 6)) * SEQ + (r & (SEQ - 1))) * 64 + (cc & 63)) = w;
.LBB0_815:
	v_ashrrev_i32_e32 v75, 31, v74
	v_lshlrev_b64 v[6:7], 20, v[74:75]
	v_lshl_add_u64 v[6:7], v[34:35], 0, v[6:7]
	global_store_dwordx4 v[6:7], v[2:5], off sc1
	s_cbranch_execnz .LBB0_814
.LBB0_816:
	v_mov_b32_e32 v147, v1
	v_lshl_add_u64 v[6:7], v[36:37], 0, v[146:147]
	global_store_dwordx4 v[6:7], v[2:5], off offset:256 sc1
	s_andn2_b64 vcc, exec, s[46:47]
	s_mov_b64 s[46:47], -1
	s_cbranch_vccnz .LBB0_601

; __device__ __forceinline__ unsigned cvt_pk_bf16(float lo, float hi) { unsigned r; asm volatile("v_cvt_pk_bf16_f32 %0, %1, %2" : "=v"(r) : "v"(lo), "v"(hi)); return r; }
; __device__ __forceinline__ f32x4 gelu4(f32x4 v) { f32x2 a = gelu_pk((f32x2){v[0], v[1]}), b = gelu_pk((f32x2){v[2], v[3]}); return (f32x4){a.x, a.y, b.x, b.y}; }
; __device__ __forceinline__ f32x2 gelu_pk(f32x2 v) {
;     const f32x2 av = __builtin_elementwise_abs(v), d = av * 0.2316418882f + 1.0f;
;     f32x2 t; t.x = __builtin_amdgcn_rcpf(d.x); t.y = __builtin_amdgcn_rcpf(d.y);
;     f32x2 q = t * 0.5307027145f + (-0.7265760135f); q = q * t + 0.7107068705f; q = q * t + (-0.142248368f); q = q * t + 0.127414796f; q = q * t;
;     const f32x2 s = (v * v) * (-0.72134752044f);
;     f32x2 e; e.x = __builtin_amdgcn_exp2f(s.x); e.y = __builtin_amdgcn_exp2f(s.y);
;     const f32x2 m = v * (q * e), r = v - m;
;     f32x2 o; o.x = v.x < 0.f ? m.x : r.x; o.y = v.y < 0.f ? m.y : r.y; return o;
; }
;     __device__ __forceinline__ void operator()(const f32x4 (&acc)[2][2][4][2], const Unit& u, int wr, int wc, int fr, int fq, int ui) const {
;     ...
;                 f32x4 sm0 = (f32x4){0.f, 0.f, 0.f, 0.f}, sm1 = sm0, sq0 = sm0, sq1 = sm0;
; #pragma unroll
;                 for (int ai = 0; ai < 2; ++ai)
; #pragma unroll
;                     for (int m = 0; m < 4; ++m) {
;                         const int ch = ch0 + ai * 128 + m * 16;
;                         const f32x4 v0 = pg8::gelu4(acc[ai][bj][m][0] * rs0), v1 = pg8::gelu4(acc[ai][bj][m][1] * rs1);
;                         sm0 = sm0 + v0; sm1 = sm1 + v1; sq0 = sq0 + v0 * v0; sq1 = sq1 + v1 * v1;
;                         u32x4 w; w.x = cvt_pk_bf16(v0[0], v0[1]); w.y = cvt_pk_bf16(v0[2], v0[3]); w.z = cvt_pk_bf16(v1[0], v1[1]); w.w = cvt_pk_bf16(v1[2], v1[3]);
;                         *(u32x4*)(Gt + ((size_t)(tok >> 3) * 512 + ch) * 8) = w;
;                     }
.LBB0_846:
	s_lshl_b32 s4, s23, 8
	s_and_b32 s36, s4, 0x100
	s_lshl_b32 s4, s20, 8
	s_or_b32 s21, s4, s16
	s_lshl_b32 s4, s19, 10
	v_add_u32_e32 v231, s4, v215
	ds_read_b128 v[126:129], v231
	ds_read_b128 v[122:125], v231 offset:16
	s_add_i32 s36, s36, s15
	v_or_b32_e32 v166, s36, v147
	s_cmp_gt_u32 s23, 1
	v_or_b32_e32 v164, 16, v166
	v_or_b32_e32 v162, 32, v166
	v_or_b32_e32 v168, s21, v149
	s_cselect_b64 s[52:53], -1, 0
	s_cmp_lt_u32 s23, 2
	s_mov_b64 s[54:55], -1
	v_ashrrev_i32_e32 v167, 31, v166
	s_waitcnt lgkmcnt(0)
	v_pk_mul_f32 v[170:171], v[134:135], v[126:127]
	v_pk_mul_f32 v[172:173], v[130:131], v[122:123]
	v_pk_mul_f32 v[130:131], v[118:119], v[126:127]
	v_pk_mul_f32 v[134:135], v[114:115], v[122:123]
	v_ashrrev_i32_e32 v165, 31, v164
	v_pk_mul_f32 v[114:115], v[110:111], v[126:127]
	v_pk_mul_f32 v[118:119], v[106:107], v[122:123]
	v_ashrrev_i32_e32 v163, 31, v162
	v_or_b32_e32 v106, 48, v166
	v_pk_mul_f32 v[102:103], v[102:103], v[126:127]
	v_pk_mul_f32 v[110:111], v[98:99], v[122:123]
	v_pk_mul_f32 v[98:99], v[94:95], v[126:127]
	s_cbranch_scc1 .LBB0_856
	v_and_b32_e32 v175, 0x7fffffff, v171
	v_and_b32_e32 v174, 0x7fffffff, v170
	v_pk_fma_f32 v[174:175], v[174:175], s[86:87], 1.0 op_sel_hi:[1,0,0]
	v_mov_b64_e32 v[176:177], s[62:63]
	v_rcp_f32_e32 v174, v174
	v_rcp_f32_e32 v175, v175
	v_pk_mul_f32 v[182:183], v[170:171], v[170:171]
	v_ashrrev_i32_e32 v94, 3, v168
	v_pk_mul_f32 v[182:183], v[182:183], s[84:85] op_sel_hi:[1,0]
	v_pk_fma_f32 v[180:181], v[174:175], s[60:61], v[176:177] op_sel_hi:[1,0,0]
	v_exp_f32_e32 v182, v182
	v_pk_fma_f32 v[180:181], v[174:175], v[180:181], s[64:65] op_sel_hi:[1,1,0]
	v_exp_f32_e32 v183, v183
	v_pk_fma_f32 v[180:181], v[174:175], v[180:181], s[66:67] op_sel_hi:[1,1,0]
	v_ashrrev_i32_e32 v95, 31, v94
	v_pk_fma_f32 v[180:181], v[174:175], v[180:181], s[24:25] op_sel_hi:[1,1,0]
	v_cmp_gt_f32_e32 vcc, 0, v170
	v_pk_mul_f32 v[174:175], v[174:175], v[180:181]
	v_lshlrev_b64 v[178:179], 13, v[94:95]
	v_pk_mul_f32 v[174:175], v[182:183], v[174:175]
	v_pk_mul_f32 v[94:95], v[136:137], v[128:129]
	v_pk_mul_f32 v[182:183], v[170:171], v[174:175]
	v_pk_fma_f32 v[174:175], v[170:171], v[174:175], v[170:171] neg_lo:[1,0,0] neg_hi:[1,0,0]
	v_pk_mul_f32 v[180:181], v[94:95], v[94:95]
	v_cndmask_b32_e32 v184, v174, v182, vcc
	v_cmp_gt_f32_e32 vcc, 0, v171
	v_and_b32_e32 v174, 0x7fffffff, v94
	v_pk_mul_f32 v[180:181], v[180:181], s[84:85] op_sel_hi:[1,0]
	v_cndmask_b32_e32 v185, v175, v183, vcc
	v_and_b32_e32 v175, 0x7fffffff, v95
	v_pk_fma_f32 v[174:175], v[174:175], s[86:87], 1.0 op_sel_hi:[1,0,0]
	v_exp_f32_e32 v180, v180
	v_rcp_f32_e32 v174, v174
	v_rcp_f32_e32 v175, v175
	v_exp_f32_e32 v181, v181
	v_cmp_gt_f32_e32 vcc, 0, v94
	v_pk_mul_f32 v[186:187], v[172:173], v[172:173]
	v_pk_fma_f32 v[182:183], v[174:175], s[60:61], v[176:177] op_sel_hi:[1,0,0]
	v_pk_mul_f32 v[186:187], v[186:187], s[84:85] op_sel_hi:[1,0]
	v_pk_fma_f32 v[182:183], v[174:175], v[182:183], s[64:65] op_sel_hi:[1,1,0]
	v_exp_f32_e32 v186, v186
	v_pk_fma_f32 v[182:183], v[174:175], v[182:183], s[66:67] op_sel_hi:[1,1,0]
	v_exp_f32_e32 v187, v187
	v_pk_fma_f32 v[182:183], v[174:175], v[182:183], s[24:25] op_sel_hi:[1,1,0]
	v_lshl_add_u64 v[192:193], s[80:81], 0, v[178:179]
	v_pk_mul_f32 v[174:175], v[174:175], v[182:183]
	v_cvt_pk_bf16_f32 v194, v184, v185
	v_pk_mul_f32 v[178:179], v[120:121], v[128:129]
	v_pk_mul_f32 v[174:175], v[180:181], v[174:175]
	v_pk_mul_f32 v[200:201], v[134:135], v[134:135]
	v_pk_mul_f32 v[180:181], v[94:95], v[174:175]
	v_pk_fma_f32 v[174:175], v[94:95], v[174:175], v[94:95] neg_lo:[1,0,0] neg_hi:[1,0,0]
	v_pk_mul_f32 v[200:201], v[200:201], s[84:85] op_sel_hi:[1,0]
	v_cndmask_b32_e32 v94, v174, v180, vcc
	v_cmp_gt_f32_e32 vcc, 0, v95
	v_and_b32_e32 v180, 0x7fffffff, v172
	v_exp_f32_e32 v200, v200
	v_cndmask_b32_e32 v95, v175, v181, vcc
	v_and_b32_e32 v181, 0x7fffffff, v173
	v_pk_fma_f32 v[180:181], v[180:181], s[86:87], 1.0 op_sel_hi:[1,0,0]
	v_cmp_gt_f32_e32 vcc, 0, v172
	v_rcp_f32_e32 v180, v180
	v_rcp_f32_e32 v181, v181
	v_pk_mul_f32 v[174:175], v[132:133], v[124:125]
	v_cvt_pk_bf16_f32 v195, v94, v95
	v_exp_f32_e32 v201, v201
	v_pk_fma_f32 v[182:183], v[180:181], s[60:61], v[176:177] op_sel_hi:[1,0,0]
	v_pk_mul_f32 v[208:209], v[110:111], v[110:111]
	v_pk_fma_f32 v[182:183], v[180:181], v[182:183], s[64:65] op_sel_hi:[1,1,0]
	v_pk_mul_f32 v[208:209], v[208:209], s[84:85] op_sel_hi:[1,0]
	v_pk_fma_f32 v[182:183], v[180:181], v[182:183], s[66:67] op_sel_hi:[1,1,0]
	v_exp_f32_e32 v208, v208
	v_pk_fma_f32 v[182:183], v[180:181], v[182:183], s[24:25] op_sel_hi:[1,1,0]
	v_exp_f32_e32 v209, v209
	v_pk_mul_f32 v[180:181], v[180:181], v[182:183]
	v_pk_mul_f32 v[182:183], v[174:175], v[174:175]
	v_pk_mul_f32 v[180:181], v[186:187], v[180:181]
	v_pk_mul_f32 v[182:183], v[182:183], s[84:85] op_sel_hi:[1,0]
	v_pk_mul_f32 v[186:187], v[172:173], v[180:181]
	v_pk_fma_f32 v[180:181], v[172:173], v[180:181], v[172:173] neg_lo:[1,0,0] neg_hi:[1,0,0]
	v_exp_f32_e32 v182, v182
	v_cndmask_b32_e32 v186, v180, v186, vcc
	v_cmp_gt_f32_e32 vcc, 0, v173
	v_and_b32_e32 v180, 0x7fffffff, v174
	v_exp_f32_e32 v183, v183
	v_cndmask_b32_e32 v187, v181, v187, vcc
	v_and_b32_e32 v181, 0x7fffffff, v175
	v_pk_fma_f32 v[180:181], v[180:181], s[86:87], 1.0 op_sel_hi:[1,0,0]
	v_cmp_gt_f32_e32 vcc, 0, v174
	v_rcp_f32_e32 v180, v180
	v_rcp_f32_e32 v181, v181
	v_cvt_pk_bf16_f32 v196, v186, v187
	v_pk_add_f32 v[190:191], v[186:187], 0 op_sel_hi:[1,0]
	v_ashrrev_i32_e32 v107, 31, v106
	v_pk_fma_f32 v[188:189], v[180:181], s[60:61], v[176:177] op_sel_hi:[1,0,0]
	v_and_b32_e32 v0, 64, v238
	v_pk_fma_f32 v[188:189], v[180:181], v[188:189], s[64:65] op_sel_hi:[1,1,0]
; __device__ __forceinline__ unsigned cvt_pk_bf16(float lo, float hi) { unsigned r; asm volatile("v_cvt_pk_bf16_f32 %0, %1, %2" : "=v"(r) : "v"(lo), "v"(hi)); return r; }
; __device__ __forceinline__ f32x4 gelu4(f32x4 v) { f32x2 a = gelu_pk((f32x2){v[0], v[1]}), b = gelu_pk((f32x2){v[2], v[3]}); return (f32x4){a.x, a.y, b.x, b.y}; }
; __device__ __forceinline__ f32x2 gelu_pk(f32x2 v) {
;     const f32x2 av = __builtin_elementwise_abs(v), d = av * 0.2316418882f + 1.0f;
;     f32x2 t; t.x = __builtin_amdgcn_rcpf(d.x); t.y = __builtin_amdgcn_rcpf(d.y);
;     f32x2 q = t * 0.5307027145f + (-0.7265760135f); q = q * t + 0.7107068705f; q = q * t + (-0.142248368f); q = q * t + 0.127414796f; q = q * t;
;     const f32x2 s = (v * v) * (-0.72134752044f);
;     f32x2 e; e.x = __builtin_amdgcn_exp2f(s.x); e.y = __builtin_amdgcn_exp2f(s.y);
;     const f32x2 m = v * (q * e), r = v - m;
;     f32x2 o; o.x = v.x < 0.f ? m.x : r.x; o.y = v.y < 0.f ? m.y : r.y; return o;
; }
;     __device__ __forceinline__ void operator()(const f32x4 (&acc)[2][2][4][2], const Unit& u, int wr, int wc, int fr, int fq, int ui) const {
;     ...
;                 f32x4 sm0 = (f32x4){0.f, 0.f, 0.f, 0.f}, sm1 = sm0, sq0 = sm0, sq1 = sm0;
; #pragma unroll
;                 for (int ai = 0; ai < 2; ++ai)
; #pragma unroll
;                     for (int m = 0; m < 4; ++m) {
;                         const int ch = ch0 + ai * 128 + m * 16;
;                         const f32x4 v0 = pg8::gelu4(acc[ai][bj][m][0] * rs0), v1 = pg8::gelu4(acc[ai][bj][m][1] * rs1);
;                         sm0 = sm0 + v0; sm1 = sm1 + v1; sq0 = sq0 + v0 * v0; sq1 = sq1 + v1 * v1;
;                         u32x4 w; w.x = cvt_pk_bf16(v0[0], v0[1]); w.y = cvt_pk_bf16(v0[2], v0[3]); w.z = cvt_pk_bf16(v1[0], v1[1]); w.w = cvt_pk_bf16(v1[2], v1[3]);
;                         *(u32x4*)(Gt + ((size_t)(tok >> 3) * 512 + ch) * 8) = w;
;                     }
	v_ashrrev_i32_e32 v169, 31, v168
	v_pk_fma_f32 v[188:189], v[180:181], v[188:189], s[66:67] op_sel_hi:[1,1,0]
	s_nop 0
	v_pk_fma_f32 v[188:189], v[180:181], v[188:189], s[24:25] op_sel_hi:[1,1,0]
	s_nop 0
	v_pk_mul_f32 v[180:181], v[180:181], v[188:189]
	v_pk_add_f32 v[188:189], v[184:185], 0 op_sel_hi:[1,0]
	v_pk_mul_f32 v[180:181], v[182:183], v[180:181]
	s_nop 0
	v_pk_mul_f32 v[182:183], v[174:175], v[180:181]
	v_pk_fma_f32 v[180:181], v[174:175], v[180:181], v[174:175] neg_lo:[1,0,0] neg_hi:[1,0,0]
	s_nop 0
	v_cndmask_b32_e32 v174, v180, v182, vcc
	v_cmp_gt_f32_e32 vcc, 0, v175
	v_and_b32_e32 v182, 0x7fffffff, v130
	s_nop 0
	v_cndmask_b32_e32 v175, v181, v183, vcc
	v_and_b32_e32 v183, 0x7fffffff, v131
	v_pk_fma_f32 v[182:183], v[182:183], s[86:87], 1.0 op_sel_hi:[1,0,0]
	v_cvt_pk_bf16_f32 v197, v174, v175
	v_lshl_add_u64 v[180:181], v[166:167], 4, v[192:193]
	v_rcp_f32_e32 v182, v182
	v_rcp_f32_e32 v183, v183
	global_store_dwordx4 v[180:181], v[194:197], off sc1
	v_cmp_gt_f32_e32 vcc, 0, v130
	s_nop 0
	v_pk_mul_f32 v[196:197], v[130:131], v[130:131]
	v_pk_fma_f32 v[194:195], v[182:183], s[60:61], v[176:177] op_sel_hi:[1,0,0]
	v_pk_mul_f32 v[196:197], v[196:197], s[84:85] op_sel_hi:[1,0]
	v_pk_fma_f32 v[194:195], v[182:183], v[194:195], s[64:65] op_sel_hi:[1,1,0]
	v_exp_f32_e32 v196, v196
	v_exp_f32_e32 v197, v197
	v_pk_fma_f32 v[194:195], v[182:183], v[194:195], s[66:67] op_sel_hi:[1,1,0]
	s_nop 0
	v_pk_fma_f32 v[194:195], v[182:183], v[194:195], s[24:25] op_sel_hi:[1,1,0]
	s_nop 0
	v_pk_mul_f32 v[182:183], v[182:183], v[194:195]
	v_pk_mul_f32 v[194:195], v[178:179], v[178:179]
	v_pk_mul_f32 v[182:183], v[196:197], v[182:183]
	v_pk_mul_f32 v[194:195], v[194:195], s[84:85] op_sel_hi:[1,0]
	v_pk_mul_f32 v[196:197], v[130:131], v[182:183]
	v_pk_fma_f32 v[182:183], v[130:131], v[182:183], v[130:131] neg_lo:[1,0,0] neg_hi:[1,0,0]
	v_exp_f32_e32 v194, v194
	v_cndmask_b32_e32 v198, v182, v196, vcc
	v_cmp_gt_f32_e32 vcc, 0, v131
	v_and_b32_e32 v182, 0x7fffffff, v178
	v_exp_f32_e32 v195, v195
	v_cndmask_b32_e32 v199, v183, v197, vcc
	v_and_b32_e32 v183, 0x7fffffff, v179
	v_pk_fma_f32 v[182:183], v[182:183], s[86:87], 1.0 op_sel_hi:[1,0,0]
	v_cmp_gt_f32_e32 vcc, 0, v178
	v_rcp_f32_e32 v182, v182
	v_rcp_f32_e32 v183, v183
	v_pk_add_f32 v[188:189], v[198:199], v[188:189]
	v_pk_fma_f32 v[196:197], v[182:183], s[60:61], v[176:177] op_sel_hi:[1,0,0]
	s_nop 0
	v_pk_fma_f32 v[196:197], v[182:183], v[196:197], s[64:65] op_sel_hi:[1,1,0]
	s_nop 0
	v_pk_fma_f32 v[196:197], v[182:183], v[196:197], s[66:67] op_sel_hi:[1,1,0]
	s_nop 0
	v_pk_fma_f32 v[196:197], v[182:183], v[196:197], s[24:25] op_sel_hi:[1,1,0]
	s_nop 0
	v_pk_mul_f32 v[182:183], v[182:183], v[196:197]
	s_nop 0
	v_pk_mul_f32 v[182:183], v[194:195], v[182:183]
	s_nop 0
	v_pk_mul_f32 v[194:195], v[178:179], v[182:183]
	v_pk_fma_f32 v[182:183], v[178:179], v[182:183], v[178:179] neg_lo:[1,0,0] neg_hi:[1,0,0]
	s_nop 0
	v_cndmask_b32_e32 v178, v182, v194, vcc
	v_cmp_gt_f32_e32 vcc, 0, v179
	v_and_b32_e32 v194, 0x7fffffff, v134
	s_nop 0
	v_cndmask_b32_e32 v179, v183, v195, vcc
	v_and_b32_e32 v195, 0x7fffffff, v135
	v_pk_fma_f32 v[194:195], v[194:195], s[86:87], 1.0 op_sel_hi:[1,0,0]
	v_cmp_gt_f32_e32 vcc, 0, v134
	v_rcp_f32_e32 v194, v194
	v_rcp_f32_e32 v195, v195
	v_pk_mul_f32 v[182:183], v[116:117], v[124:125]
	v_pk_fma_f32 v[196:197], v[194:195], s[60:61], v[176:177] op_sel_hi:[1,0,0]
	s_nop 0
	v_pk_fma_f32 v[196:197], v[194:195], v[196:197], s[64:65] op_sel_hi:[1,1,0]
	s_nop 0
	v_pk_fma_f32 v[196:197], v[194:195], v[196:197], s[66:67] op_sel_hi:[1,1,0]
	s_nop 0
	v_pk_fma_f32 v[196:197], v[194:195], v[196:197], s[24:25] op_sel_hi:[1,1,0]
	s_nop 0
	v_pk_mul_f32 v[194:195], v[194:195], v[196:197]
	v_pk_mul_f32 v[196:197], v[182:183], v[182:183]
	v_pk_mul_f32 v[194:195], v[200:201], v[194:195]
	v_pk_mul_f32 v[196:197], v[196:197], s[84:85] op_sel_hi:[1,0]
	v_pk_mul_f32 v[200:201], v[134:135], v[194:195]
	v_pk_fma_f32 v[194:195], v[134:135], v[194:195], v[134:135] neg_lo:[1,0,0] neg_hi:[1,0,0]
	v_exp_f32_e32 v196, v196
	v_cndmask_b32_e32 v200, v194, v200, vcc
	v_cmp_gt_f32_e32 vcc, 0, v135
	v_and_b32_e32 v194, 0x7fffffff, v182
	v_exp_f32_e32 v197, v197
	v_cndmask_b32_e32 v201, v195, v201, vcc
	v_and_b32_e32 v195, 0x7fffffff, v183
	v_pk_fma_f32 v[194:195], v[194:195], s[86:87], 1.0 op_sel_hi:[1,0,0]
	v_cmp_gt_f32_e32 vcc, 0, v182
	v_rcp_f32_e32 v194, v194
	v_rcp_f32_e32 v195, v195
	v_pk_add_f32 v[190:191], v[200:201], v[190:191]
	v_pk_fma_f32 v[202:203], v[194:195], s[60:61], v[176:177] op_sel_hi:[1,0,0]
	s_nop 0
	v_pk_fma_f32 v[202:203], v[194:195], v[202:203], s[64:65] op_sel_hi:[1,1,0]
	s_nop 0
	v_pk_fma_f32 v[202:203], v[194:195], v[202:203], s[66:67] op_sel_hi:[1,1,0]
	s_nop 0
	v_pk_fma_f32 v[202:203], v[194:195], v[202:203], s[24:25] op_sel_hi:[1,1,0]
	s_nop 0
	v_pk_mul_f32 v[194:195], v[194:195], v[202:203]
	v_pk_mul_f32 v[202:203], v[118:119], v[118:119]
	v_pk_mul_f32 v[194:195], v[196:197], v[194:195]
	v_pk_mul_f32 v[202:203], v[202:203], s[84:85] op_sel_hi:[1,0]
	v_pk_mul_f32 v[196:197], v[182:183], v[194:195]
	v_pk_fma_f32 v[194:195], v[182:183], v[194:195], v[182:183] neg_lo:[1,0,0] neg_hi:[1,0,0]
	v_exp_f32_e32 v202, v202
	v_cndmask_b32_e32 v182, v194, v196, vcc
	v_cmp_gt_f32_e32 vcc, 0, v183
	v_exp_f32_e32 v203, v203
	s_nop 0
	v_cndmask_b32_e32 v183, v195, v197, vcc
	v_pk_mul_f32 v[194:195], v[198:199], v[198:199]
	v_cmp_gt_f32_e32 vcc, 0, v114
	v_pk_fma_f32 v[194:195], v[184:185], v[184:185], v[194:195]
	v_pk_mul_f32 v[184:185], v[200:201], v[200:201]
	s_nop 0
	v_pk_fma_f32 v[196:197], v[186:187], v[186:187], v[184:185]
	v_cvt_pk_bf16_f32 v184, v198, v199
	v_cvt_pk_bf16_f32 v185, v178, v179
; __device__ __forceinline__ unsigned cvt_pk_bf16(float lo, float hi) { unsigned r; asm volatile("v_cvt_pk_bf16_f32 %0, %1, %2" : "=v"(r) : "v"(lo), "v"(hi)); return r; }
; __device__ __forceinline__ f32x4 gelu4(f32x4 v) { f32x2 a = gelu_pk((f32x2){v[0], v[1]}), b = gelu_pk((f32x2){v[2], v[3]}); return (f32x4){a.x, a.y, b.x, b.y}; }
; __device__ __forceinline__ f32x2 gelu_pk(f32x2 v) {
;     const f32x2 av = __builtin_elementwise_abs(v), d = av * 0.2316418882f + 1.0f;
;     f32x2 t; t.x = __builtin_amdgcn_rcpf(d.x); t.y = __builtin_amdgcn_rcpf(d.y);
;     f32x2 q = t * 0.5307027145f + (-0.7265760135f); q = q * t + 0.7107068705f; q = q * t + (-0.142248368f); q = q * t + 0.127414796f; q = q * t;
;     const f32x2 s = (v * v) * (-0.72134752044f);
;     f32x2 e; e.x = __builtin_amdgcn_exp2f(s.x); e.y = __builtin_amdgcn_exp2f(s.y);
;     const f32x2 m = v * (q * e), r = v - m;
;     f32x2 o; o.x = v.x < 0.f ? m.x : r.x; o.y = v.y < 0.f ? m.y : r.y; return o;
; }
;     __device__ __forceinline__ void operator()(const f32x4 (&acc)[2][2][4][2], const Unit& u, int wr, int wc, int fr, int fq, int ui) const {
;     ...
;                 f32x4 sm0 = (f32x4){0.f, 0.f, 0.f, 0.f}, sm1 = sm0, sq0 = sm0, sq1 = sm0;
; #pragma unroll
;                 for (int ai = 0; ai < 2; ++ai)
; #pragma unroll
;                     for (int m = 0; m < 4; ++m) {
;                         const int ch = ch0 + ai * 128 + m * 16;
;                         const f32x4 v0 = pg8::gelu4(acc[ai][bj][m][0] * rs0), v1 = pg8::gelu4(acc[ai][bj][m][1] * rs1);
;                         sm0 = sm0 + v0; sm1 = sm1 + v1; sq0 = sq0 + v0 * v0; sq1 = sq1 + v1 * v1;
;                         u32x4 w; w.x = cvt_pk_bf16(v0[0], v0[1]); w.y = cvt_pk_bf16(v0[2], v0[3]); w.z = cvt_pk_bf16(v1[0], v1[1]); w.w = cvt_pk_bf16(v1[2], v1[3]);
;                         *(u32x4*)(Gt + ((size_t)(tok >> 3) * 512 + ch) * 8) = w;
;                     }
	v_cvt_pk_bf16_f32 v186, v200, v201
	v_cvt_pk_bf16_f32 v187, v182, v183
	v_lshl_add_u64 v[198:199], v[164:165], 4, v[192:193]
	global_store_dwordx4 v[198:199], v[184:187], off sc1
	v_pk_mul_f32 v[200:201], v[114:115], v[114:115]
	s_nop 0
	v_and_b32_e32 v187, 0x7fffffff, v115
	v_and_b32_e32 v186, 0x7fffffff, v114
	v_pk_fma_f32 v[186:187], v[186:187], s[86:87], 1.0 op_sel_hi:[1,0,0]
	v_pk_mul_f32 v[200:201], v[200:201], s[84:85] op_sel_hi:[1,0]
	v_rcp_f32_e32 v186, v186
	v_rcp_f32_e32 v187, v187
	v_exp_f32_e32 v200, v200
	v_exp_f32_e32 v201, v201
	v_pk_mul_f32 v[184:185], v[112:113], v[128:129]
	v_pk_fma_f32 v[198:199], v[186:187], s[60:61], v[176:177] op_sel_hi:[1,0,0]
	s_nop 0
	v_pk_fma_f32 v[198:199], v[186:187], v[198:199], s[64:65] op_sel_hi:[1,1,0]
	s_nop 0
	v_pk_fma_f32 v[198:199], v[186:187], v[198:199], s[66:67] op_sel_hi:[1,1,0]
	s_nop 0
	v_pk_fma_f32 v[198:199], v[186:187], v[198:199], s[24:25] op_sel_hi:[1,1,0]
	s_nop 0
	v_pk_mul_f32 v[186:187], v[186:187], v[198:199]
	v_pk_mul_f32 v[198:199], v[184:185], v[184:185]
	v_pk_mul_f32 v[186:187], v[200:201], v[186:187]
	v_pk_mul_f32 v[198:199], v[198:199], s[84:85] op_sel_hi:[1,0]
	v_pk_mul_f32 v[200:201], v[114:115], v[186:187]
	v_pk_fma_f32 v[186:187], v[114:115], v[186:187], v[114:115] neg_lo:[1,0,0] neg_hi:[1,0,0]
	v_exp_f32_e32 v198, v198
	v_cndmask_b32_e32 v204, v186, v200, vcc
	v_cmp_gt_f32_e32 vcc, 0, v115
	v_and_b32_e32 v186, 0x7fffffff, v184
	v_exp_f32_e32 v199, v199
	v_cndmask_b32_e32 v205, v187, v201, vcc
	v_and_b32_e32 v187, 0x7fffffff, v185
	v_pk_fma_f32 v[186:187], v[186:187], s[86:87], 1.0 op_sel_hi:[1,0,0]
	v_cmp_gt_f32_e32 vcc, 0, v184
	v_rcp_f32_e32 v186, v186
	v_rcp_f32_e32 v187, v187
	v_pk_fma_f32 v[194:195], v[204:205], v[204:205], v[194:195]
	v_pk_fma_f32 v[200:201], v[186:187], s[60:61], v[176:177] op_sel_hi:[1,0,0]
	s_nop 0
	v_pk_fma_f32 v[200:201], v[186:187], v[200:201], s[64:65] op_sel_hi:[1,1,0]
	s_nop 0
	v_pk_fma_f32 v[200:201], v[186:187], v[200:201], s[66:67] op_sel_hi:[1,1,0]
	s_nop 0
	v_pk_fma_f32 v[200:201], v[186:187], v[200:201], s[24:25] op_sel_hi:[1,1,0]
	s_nop 0
	v_pk_mul_f32 v[186:187], v[186:187], v[200:201]
	s_nop 0
	v_pk_mul_f32 v[186:187], v[198:199], v[186:187]
	s_nop 0
	v_pk_mul_f32 v[198:199], v[184:185], v[186:187]
	v_pk_fma_f32 v[186:187], v[184:185], v[186:187], v[184:185] neg_lo:[1,0,0] neg_hi:[1,0,0]
	s_nop 0
	v_cndmask_b32_e32 v184, v186, v198, vcc
	v_cmp_gt_f32_e32 vcc, 0, v185
	v_and_b32_e32 v198, 0x7fffffff, v118
	s_nop 0
	v_cndmask_b32_e32 v185, v187, v199, vcc
	v_and_b32_e32 v199, 0x7fffffff, v119
	v_pk_fma_f32 v[198:199], v[198:199], s[86:87], 1.0 op_sel_hi:[1,0,0]
	v_cmp_gt_f32_e32 vcc, 0, v118
	v_rcp_f32_e32 v198, v198
	v_rcp_f32_e32 v199, v199
	v_pk_mul_f32 v[186:187], v[108:109], v[124:125]
	v_pk_fma_f32 v[200:201], v[198:199], s[60:61], v[176:177] op_sel_hi:[1,0,0]
	s_nop 0
	v_pk_fma_f32 v[200:201], v[198:199], v[200:201], s[64:65] op_sel_hi:[1,1,0]
	s_nop 0
	v_pk_fma_f32 v[200:201], v[198:199], v[200:201], s[66:67] op_sel_hi:[1,1,0]
	s_nop 0
	v_pk_fma_f32 v[200:201], v[198:199], v[200:201], s[24:25] op_sel_hi:[1,1,0]
	s_nop 0
	v_pk_mul_f32 v[198:199], v[198:199], v[200:201]
	v_pk_mul_f32 v[200:201], v[186:187], v[186:187]
	v_pk_mul_f32 v[198:199], v[202:203], v[198:199]
	v_pk_mul_f32 v[200:201], v[200:201], s[84:85] op_sel_hi:[1,0]
	v_pk_mul_f32 v[202:203], v[118:119], v[198:199]
	v_pk_fma_f32 v[198:199], v[118:119], v[198:199], v[118:119] neg_lo:[1,0,0] neg_hi:[1,0,0]
	v_exp_f32_e32 v200, v200
	v_cndmask_b32_e32 v206, v198, v202, vcc
	v_cmp_gt_f32_e32 vcc, 0, v119
	v_and_b32_e32 v198, 0x7fffffff, v186
	v_exp_f32_e32 v201, v201
	v_cndmask_b32_e32 v207, v199, v203, vcc
	v_and_b32_e32 v199, 0x7fffffff, v187
	v_pk_fma_f32 v[198:199], v[198:199], s[86:87], 1.0 op_sel_hi:[1,0,0]
	v_cmp_gt_f32_e32 vcc, 0, v186
	v_rcp_f32_e32 v198, v198
	v_rcp_f32_e32 v199, v199
	s_nop 0
	v_pk_fma_f32 v[202:203], v[198:199], s[60:61], v[176:177] op_sel_hi:[1,0,0]
	s_nop 0
	v_pk_fma_f32 v[202:203], v[198:199], v[202:203], s[64:65] op_sel_hi:[1,1,0]
	s_nop 0
	v_pk_fma_f32 v[202:203], v[198:199], v[202:203], s[66:67] op_sel_hi:[1,1,0]
	s_nop 0
	v_pk_fma_f32 v[202:203], v[198:199], v[202:203], s[24:25] op_sel_hi:[1,1,0]
	s_nop 0
	v_pk_mul_f32 v[198:199], v[198:199], v[202:203]
	v_pk_fma_f32 v[202:203], v[206:207], v[206:207], v[196:197]
	v_pk_mul_f32 v[198:199], v[200:201], v[198:199]
	v_lshl_add_u64 v[196:197], v[162:163], 4, v[192:193]
	v_pk_mul_f32 v[200:201], v[186:187], v[198:199]
	v_pk_fma_f32 v[198:199], v[186:187], v[198:199], v[186:187] neg_lo:[1,0,0] neg_hi:[1,0,0]
	v_lshl_add_u64 v[192:193], v[106:107], 4, v[192:193]
	v_cndmask_b32_e32 v186, v198, v200, vcc
	v_cmp_gt_f32_e32 vcc, 0, v187
	s_nop 1
	v_cndmask_b32_e32 v187, v199, v201, vcc
	v_pk_add_f32 v[198:199], v[204:205], v[188:189]
	v_pk_add_f32 v[200:201], v[206:207], v[190:191]
	v_cvt_pk_bf16_f32 v188, v204, v205
	v_cvt_pk_bf16_f32 v189, v184, v185
	v_cvt_pk_bf16_f32 v190, v206, v207
	v_cvt_pk_bf16_f32 v191, v186, v187
	global_store_dwordx4 v[196:197], v[188:191], off sc1
	v_pk_mul_f32 v[204:205], v[102:103], v[102:103]
	v_cmp_gt_f32_e32 vcc, 0, v102
	v_and_b32_e32 v191, 0x7fffffff, v103
	v_and_b32_e32 v190, 0x7fffffff, v102
	v_pk_fma_f32 v[190:191], v[190:191], s[86:87], 1.0 op_sel_hi:[1,0,0]
	v_pk_mul_f32 v[204:205], v[204:205], s[84:85] op_sel_hi:[1,0]
	v_rcp_f32_e32 v190, v190
	v_rcp_f32_e32 v191, v191
	v_exp_f32_e32 v204, v204
	v_exp_f32_e32 v205, v205
	v_pk_mul_f32 v[188:189], v[104:105], v[128:129]
	v_pk_fma_f32 v[196:197], v[190:191], s[60:61], v[176:177] op_sel_hi:[1,0,0]
	s_nop 0
	v_pk_fma_f32 v[196:197], v[190:191], v[196:197], s[64:65] op_sel_hi:[1,1,0]
	s_nop 0
; __device__ __forceinline__ unsigned cvt_pk_bf16(float lo, float hi) { unsigned r; asm volatile("v_cvt_pk_bf16_f32 %0, %1, %2" : "=v"(r) : "v"(lo), "v"(hi)); return r; }
; __device__ __forceinline__ f32x4 gelu4(f32x4 v) { f32x2 a = gelu_pk((f32x2){v[0], v[1]}), b = gelu_pk((f32x2){v[2], v[3]}); return (f32x4){a.x, a.y, b.x, b.y}; }
; __device__ __forceinline__ f32x2 gelu_pk(f32x2 v) {
;     const f32x2 av = __builtin_elementwise_abs(v), d = av * 0.2316418882f + 1.0f;
;     f32x2 t; t.x = __builtin_amdgcn_rcpf(d.x); t.y = __builtin_amdgcn_rcpf(d.y);
;     f32x2 q = t * 0.5307027145f + (-0.7265760135f); q = q * t + 0.7107068705f; q = q * t + (-0.142248368f); q = q * t + 0.127414796f; q = q * t;
;     const f32x2 s = (v * v) * (-0.72134752044f);
;     f32x2 e; e.x = __builtin_amdgcn_exp2f(s.x); e.y = __builtin_amdgcn_exp2f(s.y);
;     const f32x2 m = v * (q * e), r = v - m;
;     f32x2 o; o.x = v.x < 0.f ? m.x : r.x; o.y = v.y < 0.f ? m.y : r.y; return o;
; }
;     __device__ __forceinline__ void operator()(const f32x4 (&acc)[2][2][4][2], const Unit& u, int wr, int wc, int fr, int fq, int ui) const {
;     ...
;                 f32x4 sm0 = (f32x4){0.f, 0.f, 0.f, 0.f}, sm1 = sm0, sq0 = sm0, sq1 = sm0;
; #pragma unroll
;                 for (int ai = 0; ai < 2; ++ai)
; #pragma unroll
;                     for (int m = 0; m < 4; ++m) {
;                         const int ch = ch0 + ai * 128 + m * 16;
;                         const f32x4 v0 = pg8::gelu4(acc[ai][bj][m][0] * rs0), v1 = pg8::gelu4(acc[ai][bj][m][1] * rs1);
;                         sm0 = sm0 + v0; sm1 = sm1 + v1; sq0 = sq0 + v0 * v0; sq1 = sq1 + v1 * v1;
;                         u32x4 w; w.x = cvt_pk_bf16(v0[0], v0[1]); w.y = cvt_pk_bf16(v0[2], v0[3]); w.z = cvt_pk_bf16(v1[0], v1[1]); w.w = cvt_pk_bf16(v1[2], v1[3]);
;                         *(u32x4*)(Gt + ((size_t)(tok >> 3) * 512 + ch) * 8) = w;
;                     }
	v_pk_fma_f32 v[196:197], v[190:191], v[196:197], s[66:67] op_sel_hi:[1,1,0]
	s_nop 0
	v_pk_fma_f32 v[196:197], v[190:191], v[196:197], s[24:25] op_sel_hi:[1,1,0]
	s_nop 0
	v_pk_mul_f32 v[190:191], v[190:191], v[196:197]
	v_pk_mul_f32 v[196:197], v[188:189], v[188:189]
	v_pk_mul_f32 v[190:191], v[204:205], v[190:191]
	v_pk_mul_f32 v[196:197], v[196:197], s[84:85] op_sel_hi:[1,0]
	v_pk_mul_f32 v[204:205], v[102:103], v[190:191]
	v_pk_fma_f32 v[190:191], v[102:103], v[190:191], v[102:103] neg_lo:[1,0,0] neg_hi:[1,0,0]
	v_exp_f32_e32 v196, v196
	v_cndmask_b32_e32 v204, v190, v204, vcc
	v_cmp_gt_f32_e32 vcc, 0, v103
	v_and_b32_e32 v190, 0x7fffffff, v188
	v_exp_f32_e32 v197, v197
	v_cndmask_b32_e32 v205, v191, v205, vcc
	v_and_b32_e32 v191, 0x7fffffff, v189
	v_pk_fma_f32 v[190:191], v[190:191], s[86:87], 1.0 op_sel_hi:[1,0,0]
	v_cmp_gt_f32_e32 vcc, 0, v188
	v_rcp_f32_e32 v190, v190
	v_rcp_f32_e32 v191, v191
	s_nop 0
	v_pk_fma_f32 v[206:207], v[190:191], s[60:61], v[176:177] op_sel_hi:[1,0,0]
	s_nop 0
	v_pk_fma_f32 v[206:207], v[190:191], v[206:207], s[64:65] op_sel_hi:[1,1,0]
	s_nop 0
	v_pk_fma_f32 v[206:207], v[190:191], v[206:207], s[66:67] op_sel_hi:[1,1,0]
	s_nop 0
	v_pk_fma_f32 v[206:207], v[190:191], v[206:207], s[24:25] op_sel_hi:[1,1,0]
	s_nop 0
	v_pk_mul_f32 v[190:191], v[190:191], v[206:207]
	s_nop 0
	v_pk_mul_f32 v[190:191], v[196:197], v[190:191]
	s_nop 0
	v_pk_mul_f32 v[196:197], v[188:189], v[190:191]
	v_pk_fma_f32 v[190:191], v[188:189], v[190:191], v[188:189] neg_lo:[1,0,0] neg_hi:[1,0,0]
	s_nop 0
	v_cndmask_b32_e32 v188, v190, v196, vcc
	v_cmp_gt_f32_e32 vcc, 0, v189
	v_and_b32_e32 v196, 0x7fffffff, v110
	s_nop 0
	v_cndmask_b32_e32 v189, v191, v197, vcc
	v_and_b32_e32 v197, 0x7fffffff, v111
	v_pk_fma_f32 v[196:197], v[196:197], s[86:87], 1.0 op_sel_hi:[1,0,0]
	v_cmp_gt_f32_e32 vcc, 0, v110
	v_rcp_f32_e32 v196, v196
	v_rcp_f32_e32 v197, v197
	v_pk_mul_f32 v[190:191], v[100:101], v[124:125]
	v_pk_fma_f32 v[206:207], v[196:197], s[60:61], v[176:177] op_sel_hi:[1,0,0]
	s_nop 0
	v_pk_fma_f32 v[206:207], v[196:197], v[206:207], s[64:65] op_sel_hi:[1,1,0]
	s_nop 0
	v_pk_fma_f32 v[206:207], v[196:197], v[206:207], s[66:67] op_sel_hi:[1,1,0]
	s_nop 0
	v_pk_fma_f32 v[206:207], v[196:197], v[206:207], s[24:25] op_sel_hi:[1,1,0]
	s_nop 0
	v_pk_mul_f32 v[196:197], v[196:197], v[206:207]
	v_pk_mul_f32 v[206:207], v[190:191], v[190:191]
	v_pk_mul_f32 v[196:197], v[208:209], v[196:197]
	v_pk_mul_f32 v[206:207], v[206:207], s[84:85] op_sel_hi:[1,0]
	v_pk_mul_f32 v[208:209], v[110:111], v[196:197]
	v_pk_fma_f32 v[196:197], v[110:111], v[196:197], v[110:111] neg_lo:[1,0,0] neg_hi:[1,0,0]
	v_exp_f32_e32 v206, v206
	v_cndmask_b32_e32 v208, v196, v208, vcc
	v_cmp_gt_f32_e32 vcc, 0, v111
	v_and_b32_e32 v196, 0x7fffffff, v190
	v_exp_f32_e32 v207, v207
	v_cndmask_b32_e32 v209, v197, v209, vcc
	v_and_b32_e32 v197, 0x7fffffff, v191
	v_pk_fma_f32 v[196:197], v[196:197], s[86:87], 1.0 op_sel_hi:[1,0,0]
	v_cmp_gt_f32_e32 vcc, 0, v190
	v_rcp_f32_e32 v196, v196
	v_rcp_f32_e32 v197, v197
	v_pk_fma_f32 v[202:203], v[208:209], v[208:209], v[202:203]
	v_pk_fma_f32 v[224:225], v[196:197], s[60:61], v[176:177] op_sel_hi:[1,0,0]
	s_nop 0
	v_pk_fma_f32 v[224:225], v[196:197], v[224:225], s[64:65] op_sel_hi:[1,1,0]
	s_nop 0
	v_pk_fma_f32 v[224:225], v[196:197], v[224:225], s[66:67] op_sel_hi:[1,1,0]
	s_nop 0
	v_pk_fma_f32 v[224:225], v[196:197], v[224:225], s[24:25] op_sel_hi:[1,1,0]
	s_nop 0
	v_pk_mul_f32 v[196:197], v[196:197], v[224:225]
	s_nop 0
	v_pk_mul_f32 v[196:197], v[206:207], v[196:197]
	s_nop 0
	v_pk_mul_f32 v[206:207], v[190:191], v[196:197]
	v_pk_fma_f32 v[196:197], v[190:191], v[196:197], v[190:191] neg_lo:[1,0,0] neg_hi:[1,0,0]
	s_nop 0
	v_cndmask_b32_e32 v190, v196, v206, vcc
	v_cmp_gt_f32_e32 vcc, 0, v191
	s_nop 1
	v_cndmask_b32_e32 v191, v197, v207, vcc
	v_pk_add_f32 v[196:197], v[204:205], v[198:199]
	v_pk_add_f32 v[198:199], v[208:209], v[200:201]
	v_pk_fma_f32 v[200:201], v[204:205], v[204:205], v[194:195]
	v_and_b32_e32 v195, 0x7fffffff, v99
	v_and_b32_e32 v194, 0x7fffffff, v98
	v_pk_fma_f32 v[194:195], v[194:195], s[86:87], 1.0 op_sel_hi:[1,0,0]
	v_cvt_pk_bf16_f32 v204, v204, v205
	v_cvt_pk_bf16_f32 v205, v188, v189
	v_cvt_pk_bf16_f32 v206, v208, v209
	v_cvt_pk_bf16_f32 v207, v190, v191
	global_store_dwordx4 v[192:193], v[204:207], off sc1
	v_rcp_f32_e32 v194, v194
	v_rcp_f32_e32 v195, v195
	v_pk_mul_f32 v[206:207], v[98:99], v[98:99]
	v_cmp_gt_f32_e32 vcc, 0, v98
	v_pk_mul_f32 v[206:207], v[206:207], s[84:85] op_sel_hi:[1,0]
	v_pk_fma_f32 v[204:205], v[194:195], s[60:61], v[176:177] op_sel_hi:[1,0,0]
	v_exp_f32_e32 v206, v206
	v_pk_fma_f32 v[204:205], v[194:195], v[204:205], s[64:65] op_sel_hi:[1,1,0]
	v_exp_f32_e32 v207, v207
	v_pk_fma_f32 v[204:205], v[194:195], v[204:205], s[66:67] op_sel_hi:[1,1,0]
	v_pk_mul_f32 v[192:193], v[96:97], v[128:129]
	v_pk_fma_f32 v[204:205], v[194:195], v[204:205], s[24:25] op_sel_hi:[1,1,0]
	s_nop 0
	v_pk_mul_f32 v[194:195], v[194:195], v[204:205]
	v_pk_mul_f32 v[204:205], v[192:193], v[192:193]
	v_pk_mul_f32 v[194:195], v[206:207], v[194:195]
	v_pk_mul_f32 v[204:205], v[204:205], s[84:85] op_sel_hi:[1,0]
	v_pk_mul_f32 v[206:207], v[98:99], v[194:195]
	v_pk_fma_f32 v[194:195], v[98:99], v[194:195], v[98:99] neg_lo:[1,0,0] neg_hi:[1,0,0]
	v_exp_f32_e32 v204, v204
	v_cndmask_b32_e32 v208, v194, v206, vcc
	v_cmp_gt_f32_e32 vcc, 0, v99
	v_and_b32_e32 v194, 0x7fffffff, v192
	v_exp_f32_e32 v205, v205
	v_cndmask_b32_e32 v209, v195, v207, vcc
	v_and_b32_e32 v195, 0x7fffffff, v193
	v_pk_fma_f32 v[194:195], v[194:195], s[86:87], 1.0 op_sel_hi:[1,0,0]
	v_cmp_gt_f32_e32 vcc, 0, v192
	v_rcp_f32_e32 v194, v194
; __device__ __forceinline__ unsigned cvt_pk_bf16(float lo, float hi) { unsigned r; asm volatile("v_cvt_pk_bf16_f32 %0, %1, %2" : "=v"(r) : "v"(lo), "v"(hi)); return r; }
; __device__ __forceinline__ f32x4 gelu4(f32x4 v) { f32x2 a = gelu_pk((f32x2){v[0], v[1]}), b = gelu_pk((f32x2){v[2], v[3]}); return (f32x4){a.x, a.y, b.x, b.y}; }
; __device__ __forceinline__ f32x2 gelu_pk(f32x2 v) {
;     const f32x2 av = __builtin_elementwise_abs(v), d = av * 0.2316418882f + 1.0f;
;     f32x2 t; t.x = __builtin_amdgcn_rcpf(d.x); t.y = __builtin_amdgcn_rcpf(d.y);
;     f32x2 q = t * 0.5307027145f + (-0.7265760135f); q = q * t + 0.7107068705f; q = q * t + (-0.142248368f); q = q * t + 0.127414796f; q = q * t;
;     const f32x2 s = (v * v) * (-0.72134752044f);
;     f32x2 e; e.x = __builtin_amdgcn_exp2f(s.x); e.y = __builtin_amdgcn_exp2f(s.y);
;     const f32x2 m = v * (q * e), r = v - m;
;     f32x2 o; o.x = v.x < 0.f ? m.x : r.x; o.y = v.y < 0.f ? m.y : r.y; return o;
; }
;     __device__ __forceinline__ void operator()(const f32x4 (&acc)[2][2][4][2], const Unit& u, int wr, int wc, int fr, int fq, int ui) const {
;     ...
;                 for (int ai = 0; ai < 2; ++ai)
; #pragma unroll
;                     for (int m = 0; m < 4; ++m) {
;                         const int ch = ch0 + ai * 128 + m * 16;
;                         const f32x4 v0 = pg8::gelu4(acc[ai][bj][m][0] * rs0), v1 = pg8::gelu4(acc[ai][bj][m][1] * rs1);
;                         sm0 = sm0 + v0; sm1 = sm1 + v1; sq0 = sq0 + v0 * v0; sq1 = sq1 + v1 * v1;
;                         u32x4 w; w.x = cvt_pk_bf16(v0[0], v0[1]); w.y = cvt_pk_bf16(v0[2], v0[3]); w.z = cvt_pk_bf16(v1[0], v1[1]); w.w = cvt_pk_bf16(v1[2], v1[3]);
;                         *(u32x4*)(Gt + ((size_t)(tok >> 3) * 512 + ch) * 8) = w;
;                     }
	v_rcp_f32_e32 v195, v195
	v_pk_fma_f32 v[200:201], v[208:209], v[208:209], v[200:201]
	v_pk_fma_f32 v[206:207], v[194:195], s[60:61], v[176:177] op_sel_hi:[1,0,0]
	s_nop 0
	v_pk_fma_f32 v[206:207], v[194:195], v[206:207], s[64:65] op_sel_hi:[1,1,0]
	s_nop 0
	v_pk_fma_f32 v[206:207], v[194:195], v[206:207], s[66:67] op_sel_hi:[1,1,0]
	s_nop 0
	v_pk_fma_f32 v[206:207], v[194:195], v[206:207], s[24:25] op_sel_hi:[1,1,0]
	s_nop 0
	v_pk_mul_f32 v[194:195], v[194:195], v[206:207]
	s_nop 0
	v_pk_mul_f32 v[194:195], v[204:205], v[194:195]
	s_nop 0
	v_pk_mul_f32 v[204:205], v[192:193], v[194:195]
	v_pk_fma_f32 v[194:195], v[192:193], v[194:195], v[192:193] neg_lo:[1,0,0] neg_hi:[1,0,0]
	s_nop 0
	v_cndmask_b32_e32 v192, v194, v204, vcc
	v_cmp_gt_f32_e32 vcc, 0, v193
	s_nop 1
	v_cndmask_b32_e32 v193, v195, v205, vcc
	v_pk_mul_f32 v[204:205], v[90:91], v[122:123]
	v_pk_mul_f32 v[194:195], v[92:93], v[124:125]
	v_and_b32_e32 v207, 0x7fffffff, v205
	v_and_b32_e32 v206, 0x7fffffff, v204
	v_pk_fma_f32 v[206:207], v[206:207], s[86:87], 1.0 op_sel_hi:[1,0,0]
	v_pk_mul_f32 v[226:227], v[204:205], v[204:205]
	v_rcp_f32_e32 v206, v206
	v_rcp_f32_e32 v207, v207
	v_pk_mul_f32 v[226:227], v[226:227], s[84:85] op_sel_hi:[1,0]
	v_cmp_gt_f32_e32 vcc, 0, v204
	v_exp_f32_e32 v226, v226
	v_pk_fma_f32 v[224:225], v[206:207], s[60:61], v[176:177] op_sel_hi:[1,0,0]
	v_exp_f32_e32 v227, v227
	v_pk_fma_f32 v[224:225], v[206:207], v[224:225], s[64:65] op_sel_hi:[1,1,0]
	s_nop 0
	v_pk_fma_f32 v[224:225], v[206:207], v[224:225], s[66:67] op_sel_hi:[1,1,0]
	s_nop 0
	v_pk_fma_f32 v[224:225], v[206:207], v[224:225], s[24:25] op_sel_hi:[1,1,0]
	s_nop 0
	v_pk_mul_f32 v[206:207], v[206:207], v[224:225]
	v_pk_mul_f32 v[224:225], v[194:195], v[194:195]
	v_pk_mul_f32 v[206:207], v[226:227], v[206:207]
	s_nop 0
	v_pk_mul_f32 v[226:227], v[204:205], v[206:207]
	v_pk_fma_f32 v[206:207], v[204:205], v[206:207], v[204:205] neg_lo:[1,0,0] neg_hi:[1,0,0]
	v_and_b32_e32 v204, 0x7fffffff, v194
	v_cndmask_b32_e32 v226, v206, v226, vcc
	v_cmp_gt_f32_e32 vcc, 0, v205
	v_and_b32_e32 v205, 0x7fffffff, v195
	v_pk_fma_f32 v[204:205], v[204:205], s[86:87], 1.0 op_sel_hi:[1,0,0]
	v_cndmask_b32_e32 v227, v207, v227, vcc
	v_rcp_f32_e32 v204, v204
	v_rcp_f32_e32 v205, v205
	v_cmp_gt_f32_e32 vcc, 0, v194
	v_pk_fma_f32 v[202:203], v[226:227], v[226:227], v[202:203]
	v_pk_fma_f32 v[206:207], v[204:205], s[60:61], v[176:177] op_sel_hi:[1,0,0]
	s_nop 0
	v_pk_fma_f32 v[206:207], v[204:205], v[206:207], s[64:65] op_sel_hi:[1,1,0]
	s_nop 0
	v_pk_fma_f32 v[206:207], v[204:205], v[206:207], s[66:67] op_sel_hi:[1,1,0]
	s_nop 0
	v_pk_fma_f32 v[206:207], v[204:205], v[206:207], s[24:25] op_sel_hi:[1,1,0]
	s_nop 0
	v_pk_mul_f32 v[204:205], v[204:205], v[206:207]
	v_pk_mul_f32 v[206:207], v[224:225], s[84:85] op_sel_hi:[1,0]
	s_nop 0
	v_exp_f32_e32 v206, v206
	v_exp_f32_e32 v207, v207
	s_nop 0
	v_pk_mul_f32 v[204:205], v[206:207], v[204:205]
	s_nop 0
	v_pk_mul_f32 v[206:207], v[194:195], v[204:205]
	v_pk_fma_f32 v[204:205], v[194:195], v[204:205], v[194:195] neg_lo:[1,0,0] neg_hi:[1,0,0]
	s_nop 0
	v_cndmask_b32_e32 v194, v204, v206, vcc
	v_cmp_gt_f32_e32 vcc, 0, v195
	s_nop 1
	v_cndmask_b32_e32 v195, v205, v207, vcc
	v_pk_add_f32 v[204:205], v[208:209], v[196:197]
	v_pk_add_f32 v[206:207], v[226:227], v[198:199]
	v_cvt_pk_bf16_f32 v196, v208, v209
	v_cvt_pk_bf16_f32 v197, v192, v193
	v_cvt_pk_bf16_f32 v198, v226, v227
	v_cvt_pk_bf16_f32 v199, v194, v195
	global_store_dwordx4 v[180:181], v[196:199], off offset:2048 sc1
	s_nop 1
	v_pk_mul_f32 v[198:199], v[86:87], v[126:127]
	v_pk_mul_f32 v[196:197], v[88:89], v[128:129]
	v_and_b32_e32 v209, 0x7fffffff, v199
	v_and_b32_e32 v208, 0x7fffffff, v198
	v_pk_fma_f32 v[208:209], v[208:209], s[86:87], 1.0 op_sel_hi:[1,0,0]
	v_pk_mul_f32 v[226:227], v[198:199], v[198:199]
	v_rcp_f32_e32 v208, v208
	v_rcp_f32_e32 v209, v209
	v_pk_mul_f32 v[226:227], v[226:227], s[84:85] op_sel_hi:[1,0]
	v_cmp_gt_f32_e32 vcc, 0, v198
	v_exp_f32_e32 v226, v226
	v_pk_fma_f32 v[224:225], v[208:209], s[60:61], v[176:177] op_sel_hi:[1,0,0]
	v_exp_f32_e32 v227, v227
	v_pk_fma_f32 v[224:225], v[208:209], v[224:225], s[64:65] op_sel_hi:[1,1,0]
	s_nop 0
	v_pk_fma_f32 v[224:225], v[208:209], v[224:225], s[66:67] op_sel_hi:[1,1,0]
	s_nop 0
	v_pk_fma_f32 v[224:225], v[208:209], v[224:225], s[24:25] op_sel_hi:[1,1,0]
	s_nop 0
	v_pk_mul_f32 v[208:209], v[208:209], v[224:225]
	v_pk_mul_f32 v[224:225], v[196:197], v[196:197]
	v_pk_mul_f32 v[208:209], v[226:227], v[208:209]
	s_nop 0
	v_pk_mul_f32 v[226:227], v[198:199], v[208:209]
	v_pk_fma_f32 v[208:209], v[198:199], v[208:209], v[198:199] neg_lo:[1,0,0] neg_hi:[1,0,0]
	v_and_b32_e32 v198, 0x7fffffff, v196
	v_cndmask_b32_e32 v226, v208, v226, vcc
	v_cmp_gt_f32_e32 vcc, 0, v199
	v_and_b32_e32 v199, 0x7fffffff, v197
	v_pk_fma_f32 v[198:199], v[198:199], s[86:87], 1.0 op_sel_hi:[1,0,0]
	v_cndmask_b32_e32 v227, v209, v227, vcc
	v_rcp_f32_e32 v198, v198
	v_rcp_f32_e32 v199, v199
	v_cmp_gt_f32_e32 vcc, 0, v196
	v_pk_add_f32 v[204:205], v[226:227], v[204:205]
	v_pk_fma_f32 v[208:209], v[198:199], s[60:61], v[176:177] op_sel_hi:[1,0,0]
	s_nop 0
	v_pk_fma_f32 v[208:209], v[198:199], v[208:209], s[64:65] op_sel_hi:[1,1,0]
	s_nop 0
	v_pk_fma_f32 v[208:209], v[198:199], v[208:209], s[66:67] op_sel_hi:[1,1,0]
	s_nop 0
	v_pk_fma_f32 v[208:209], v[198:199], v[208:209], s[24:25] op_sel_hi:[1,1,0]
	s_nop 0
	v_pk_mul_f32 v[198:199], v[198:199], v[208:209]
	v_pk_mul_f32 v[208:209], v[224:225], s[84:85] op_sel_hi:[1,0]
	s_nop 0
	v_exp_f32_e32 v208, v208
	v_exp_f32_e32 v209, v209
	s_nop 0
	v_pk_mul_f32 v[198:199], v[208:209], v[198:199]
	s_nop 0
	v_pk_mul_f32 v[208:209], v[196:197], v[198:199]
; __device__ __forceinline__ unsigned cvt_pk_bf16(float lo, float hi) { unsigned r; asm volatile("v_cvt_pk_bf16_f32 %0, %1, %2" : "=v"(r) : "v"(lo), "v"(hi)); return r; }
; __device__ __forceinline__ f32x4 gelu4(f32x4 v) { f32x2 a = gelu_pk((f32x2){v[0], v[1]}), b = gelu_pk((f32x2){v[2], v[3]}); return (f32x4){a.x, a.y, b.x, b.y}; }
; __device__ __forceinline__ f32x2 gelu_pk(f32x2 v) {
;     const f32x2 av = __builtin_elementwise_abs(v), d = av * 0.2316418882f + 1.0f;
;     f32x2 t; t.x = __builtin_amdgcn_rcpf(d.x); t.y = __builtin_amdgcn_rcpf(d.y);
;     f32x2 q = t * 0.5307027145f + (-0.7265760135f); q = q * t + 0.7107068705f; q = q * t + (-0.142248368f); q = q * t + 0.127414796f; q = q * t;
;     const f32x2 s = (v * v) * (-0.72134752044f);
;     f32x2 e; e.x = __builtin_amdgcn_exp2f(s.x); e.y = __builtin_amdgcn_exp2f(s.y);
;     const f32x2 m = v * (q * e), r = v - m;
;     f32x2 o; o.x = v.x < 0.f ? m.x : r.x; o.y = v.y < 0.f ? m.y : r.y; return o;
; }
;     __device__ __forceinline__ void operator()(const f32x4 (&acc)[2][2][4][2], const Unit& u, int wr, int wc, int fr, int fq, int ui) const {
;     ...
;                 for (int ai = 0; ai < 2; ++ai)
; #pragma unroll
;                     for (int m = 0; m < 4; ++m) {
;                         const int ch = ch0 + ai * 128 + m * 16;
;                         const f32x4 v0 = pg8::gelu4(acc[ai][bj][m][0] * rs0), v1 = pg8::gelu4(acc[ai][bj][m][1] * rs1);
;                         sm0 = sm0 + v0; sm1 = sm1 + v1; sq0 = sq0 + v0 * v0; sq1 = sq1 + v1 * v1;
;                         u32x4 w; w.x = cvt_pk_bf16(v0[0], v0[1]); w.y = cvt_pk_bf16(v0[2], v0[3]); w.z = cvt_pk_bf16(v1[0], v1[1]); w.w = cvt_pk_bf16(v1[2], v1[3]);
;                         *(u32x4*)(Gt + ((size_t)(tok >> 3) * 512 + ch) * 8) = w;
;                     }
	v_pk_fma_f32 v[198:199], v[196:197], v[198:199], v[196:197] neg_lo:[1,0,0] neg_hi:[1,0,0]
	s_nop 0
	v_cndmask_b32_e32 v196, v198, v208, vcc
	v_cmp_gt_f32_e32 vcc, 0, v197
	s_nop 1
	v_cndmask_b32_e32 v197, v199, v209, vcc
	v_pk_mul_f32 v[208:209], v[82:83], v[122:123]
	v_pk_mul_f32 v[198:199], v[84:85], v[124:125]
	v_and_b32_e32 v225, 0x7fffffff, v209
	v_and_b32_e32 v224, 0x7fffffff, v208
	v_pk_fma_f32 v[224:225], v[224:225], s[86:87], 1.0 op_sel_hi:[1,0,0]
	v_pk_mul_f32 v[232:233], v[208:209], v[208:209]
	v_rcp_f32_e32 v224, v224
	v_rcp_f32_e32 v225, v225
	v_pk_mul_f32 v[232:233], v[232:233], s[84:85] op_sel_hi:[1,0]
	v_cmp_gt_f32_e32 vcc, 0, v208
	v_exp_f32_e32 v232, v232
	v_pk_fma_f32 v[228:229], v[224:225], s[60:61], v[176:177] op_sel_hi:[1,0,0]
	v_exp_f32_e32 v233, v233
	v_pk_fma_f32 v[228:229], v[224:225], v[228:229], s[64:65] op_sel_hi:[1,1,0]
	s_nop 0
	v_pk_fma_f32 v[228:229], v[224:225], v[228:229], s[66:67] op_sel_hi:[1,1,0]
	s_nop 0
	v_pk_fma_f32 v[228:229], v[224:225], v[228:229], s[24:25] op_sel_hi:[1,1,0]
	s_nop 0
	v_pk_mul_f32 v[224:225], v[224:225], v[228:229]
	v_pk_mul_f32 v[228:229], v[198:199], v[198:199]
	v_pk_mul_f32 v[224:225], v[232:233], v[224:225]
	s_nop 0
	v_pk_mul_f32 v[232:233], v[208:209], v[224:225]
	v_pk_fma_f32 v[224:225], v[208:209], v[224:225], v[208:209] neg_lo:[1,0,0] neg_hi:[1,0,0]
	v_and_b32_e32 v208, 0x7fffffff, v198
	v_cndmask_b32_e32 v232, v224, v232, vcc
	v_cmp_gt_f32_e32 vcc, 0, v209
	v_and_b32_e32 v209, 0x7fffffff, v199
	v_pk_fma_f32 v[208:209], v[208:209], s[86:87], 1.0 op_sel_hi:[1,0,0]
	v_cndmask_b32_e32 v233, v225, v233, vcc
	v_rcp_f32_e32 v208, v208
	v_rcp_f32_e32 v209, v209
	v_cmp_gt_f32_e32 vcc, 0, v198
	v_pk_add_f32 v[206:207], v[232:233], v[206:207]
	v_pk_fma_f32 v[224:225], v[208:209], s[60:61], v[176:177] op_sel_hi:[1,0,0]
	s_nop 0
	v_pk_fma_f32 v[224:225], v[208:209], v[224:225], s[64:65] op_sel_hi:[1,1,0]
	s_nop 0
	v_pk_fma_f32 v[224:225], v[208:209], v[224:225], s[66:67] op_sel_hi:[1,1,0]
	s_nop 0
	v_pk_fma_f32 v[224:225], v[208:209], v[224:225], s[24:25] op_sel_hi:[1,1,0]
	s_nop 0
	v_pk_mul_f32 v[208:209], v[208:209], v[224:225]
	v_pk_mul_f32 v[224:225], v[228:229], s[84:85] op_sel_hi:[1,0]
	s_nop 0
	v_exp_f32_e32 v224, v224
	v_exp_f32_e32 v225, v225
	s_nop 0
	v_pk_mul_f32 v[208:209], v[224:225], v[208:209]
	s_nop 0
	v_pk_mul_f32 v[224:225], v[198:199], v[208:209]
	v_pk_fma_f32 v[208:209], v[198:199], v[208:209], v[198:199] neg_lo:[1,0,0] neg_hi:[1,0,0]
	s_nop 0
	v_cndmask_b32_e32 v198, v208, v224, vcc
	v_cmp_gt_f32_e32 vcc, 0, v199
	s_nop 1
	v_cndmask_b32_e32 v199, v209, v225, vcc
	v_pk_fma_f32 v[208:209], v[226:227], v[226:227], v[200:201]
	v_pk_fma_f32 v[224:225], v[232:233], v[232:233], v[202:203]
	v_cvt_pk_bf16_f32 v200, v226, v227
	v_cvt_pk_bf16_f32 v201, v196, v197
	v_cvt_pk_bf16_f32 v202, v232, v233
	v_cvt_pk_bf16_f32 v203, v198, v199
	global_store_dwordx4 v[180:181], v[200:203], off offset:2304 sc1
	s_nop 1
	v_pk_mul_f32 v[202:203], v[78:79], v[126:127]
	v_pk_mul_f32 v[200:201], v[80:81], v[128:129]
	v_and_b32_e32 v227, 0x7fffffff, v203
	v_and_b32_e32 v226, 0x7fffffff, v202
	v_pk_fma_f32 v[226:227], v[226:227], s[86:87], 1.0 op_sel_hi:[1,0,0]
	v_pk_mul_f32 v[232:233], v[202:203], v[202:203]
	v_rcp_f32_e32 v226, v226
	v_rcp_f32_e32 v227, v227
	v_pk_mul_f32 v[232:233], v[232:233], s[84:85] op_sel_hi:[1,0]
	v_cmp_gt_f32_e32 vcc, 0, v202
	v_exp_f32_e32 v232, v232
	v_pk_fma_f32 v[228:229], v[226:227], s[60:61], v[176:177] op_sel_hi:[1,0,0]
	v_exp_f32_e32 v233, v233
	v_pk_fma_f32 v[228:229], v[226:227], v[228:229], s[64:65] op_sel_hi:[1,1,0]
	s_nop 0
	v_pk_fma_f32 v[228:229], v[226:227], v[228:229], s[66:67] op_sel_hi:[1,1,0]
	s_nop 0
	v_pk_fma_f32 v[228:229], v[226:227], v[228:229], s[24:25] op_sel_hi:[1,1,0]
	s_nop 0
	v_pk_mul_f32 v[226:227], v[226:227], v[228:229]
	v_pk_mul_f32 v[228:229], v[200:201], v[200:201]
	v_pk_mul_f32 v[226:227], v[232:233], v[226:227]
	s_nop 0
	v_pk_mul_f32 v[232:233], v[202:203], v[226:227]
	v_pk_fma_f32 v[226:227], v[202:203], v[226:227], v[202:203] neg_lo:[1,0,0] neg_hi:[1,0,0]
	v_and_b32_e32 v202, 0x7fffffff, v200
	v_cndmask_b32_e32 v232, v226, v232, vcc
	v_cmp_gt_f32_e32 vcc, 0, v203
	v_and_b32_e32 v203, 0x7fffffff, v201
	v_pk_fma_f32 v[202:203], v[202:203], s[86:87], 1.0 op_sel_hi:[1,0,0]
	v_cndmask_b32_e32 v233, v227, v233, vcc
	v_rcp_f32_e32 v202, v202
	v_rcp_f32_e32 v203, v203
	v_cmp_gt_f32_e32 vcc, 0, v200
	v_pk_fma_f32 v[208:209], v[232:233], v[232:233], v[208:209]
	v_pk_fma_f32 v[226:227], v[202:203], s[60:61], v[176:177] op_sel_hi:[1,0,0]
	s_nop 0
	v_pk_fma_f32 v[226:227], v[202:203], v[226:227], s[64:65] op_sel_hi:[1,1,0]
	s_nop 0
	v_pk_fma_f32 v[226:227], v[202:203], v[226:227], s[66:67] op_sel_hi:[1,1,0]
	s_nop 0
	v_pk_fma_f32 v[226:227], v[202:203], v[226:227], s[24:25] op_sel_hi:[1,1,0]
	s_nop 0
	v_pk_mul_f32 v[202:203], v[202:203], v[226:227]
	v_pk_mul_f32 v[226:227], v[228:229], s[84:85] op_sel_hi:[1,0]
	s_nop 0
	v_exp_f32_e32 v226, v226
	v_exp_f32_e32 v227, v227
	s_nop 0
	v_pk_mul_f32 v[202:203], v[226:227], v[202:203]
	s_nop 0
	v_pk_mul_f32 v[226:227], v[200:201], v[202:203]
	v_pk_fma_f32 v[202:203], v[200:201], v[202:203], v[200:201] neg_lo:[1,0,0] neg_hi:[1,0,0]
	s_nop 0
	v_cndmask_b32_e32 v200, v202, v226, vcc
	v_cmp_gt_f32_e32 vcc, 0, v201
	s_nop 1
	v_cndmask_b32_e32 v201, v203, v227, vcc
	v_pk_mul_f32 v[226:227], v[74:75], v[122:123]
	v_pk_mul_f32 v[202:203], v[76:77], v[124:125]
	v_and_b32_e32 v229, 0x7fffffff, v227
	v_and_b32_e32 v228, 0x7fffffff, v226
	v_pk_fma_f32 v[228:229], v[228:229], s[86:87], 1.0 op_sel_hi:[1,0,0]
	v_pk_mul_f32 v[236:237], v[226:227], v[226:227]
	v_rcp_f32_e32 v228, v228
	v_rcp_f32_e32 v229, v229
; __device__ __forceinline__ unsigned cvt_pk_bf16(float lo, float hi) { unsigned r; asm volatile("v_cvt_pk_bf16_f32 %0, %1, %2" : "=v"(r) : "v"(lo), "v"(hi)); return r; }
; __device__ __forceinline__ f32x4 gelu4(f32x4 v) { f32x2 a = gelu_pk((f32x2){v[0], v[1]}), b = gelu_pk((f32x2){v[2], v[3]}); return (f32x4){a.x, a.y, b.x, b.y}; }
; __device__ __forceinline__ f32x2 gelu_pk(f32x2 v) {
;     const f32x2 av = __builtin_elementwise_abs(v), d = av * 0.2316418882f + 1.0f;
;     f32x2 t; t.x = __builtin_amdgcn_rcpf(d.x); t.y = __builtin_amdgcn_rcpf(d.y);
;     f32x2 q = t * 0.5307027145f + (-0.7265760135f); q = q * t + 0.7107068705f; q = q * t + (-0.142248368f); q = q * t + 0.127414796f; q = q * t;
;     const f32x2 s = (v * v) * (-0.72134752044f);
;     f32x2 e; e.x = __builtin_amdgcn_exp2f(s.x); e.y = __builtin_amdgcn_exp2f(s.y);
;     const f32x2 m = v * (q * e), r = v - m;
;     f32x2 o; o.x = v.x < 0.f ? m.x : r.x; o.y = v.y < 0.f ? m.y : r.y; return o;
; }
;     __device__ __forceinline__ void operator()(const f32x4 (&acc)[2][2][4][2], const Unit& u, int wr, int wc, int fr, int fq, int ui) const {
;     ...
;                 for (int ai = 0; ai < 2; ++ai)
; #pragma unroll
;                     for (int m = 0; m < 4; ++m) {
;                         const int ch = ch0 + ai * 128 + m * 16;
;                         const f32x4 v0 = pg8::gelu4(acc[ai][bj][m][0] * rs0), v1 = pg8::gelu4(acc[ai][bj][m][1] * rs1);
;                         sm0 = sm0 + v0; sm1 = sm1 + v1; sq0 = sq0 + v0 * v0; sq1 = sq1 + v1 * v1;
;                         u32x4 w; w.x = cvt_pk_bf16(v0[0], v0[1]); w.y = cvt_pk_bf16(v0[2], v0[3]); w.z = cvt_pk_bf16(v1[0], v1[1]); w.w = cvt_pk_bf16(v1[2], v1[3]);
;                         *(u32x4*)(Gt + ((size_t)(tok >> 3) * 512 + ch) * 8) = w;
;                     }
	v_pk_mul_f32 v[236:237], v[236:237], s[84:85] op_sel_hi:[1,0]
	v_cmp_gt_f32_e32 vcc, 0, v226
	v_exp_f32_e32 v236, v236
	v_pk_fma_f32 v[234:235], v[228:229], s[60:61], v[176:177] op_sel_hi:[1,0,0]
	v_exp_f32_e32 v237, v237
	v_pk_fma_f32 v[234:235], v[228:229], v[234:235], s[64:65] op_sel_hi:[1,1,0]
	s_nop 0
	v_pk_fma_f32 v[234:235], v[228:229], v[234:235], s[66:67] op_sel_hi:[1,1,0]
	s_nop 0
	v_pk_fma_f32 v[234:235], v[228:229], v[234:235], s[24:25] op_sel_hi:[1,1,0]
	s_nop 0
	v_pk_mul_f32 v[228:229], v[228:229], v[234:235]
	v_pk_mul_f32 v[234:235], v[202:203], v[202:203]
	v_pk_mul_f32 v[228:229], v[236:237], v[228:229]
	s_nop 0
	v_pk_mul_f32 v[236:237], v[226:227], v[228:229]
	v_pk_fma_f32 v[228:229], v[226:227], v[228:229], v[226:227] neg_lo:[1,0,0] neg_hi:[1,0,0]
	v_and_b32_e32 v226, 0x7fffffff, v202
	v_cndmask_b32_e32 v236, v228, v236, vcc
	v_cmp_gt_f32_e32 vcc, 0, v227
	v_and_b32_e32 v227, 0x7fffffff, v203
	v_pk_fma_f32 v[226:227], v[226:227], s[86:87], 1.0 op_sel_hi:[1,0,0]
	v_cndmask_b32_e32 v237, v229, v237, vcc
	v_rcp_f32_e32 v226, v226
	v_rcp_f32_e32 v227, v227
	v_cmp_gt_f32_e32 vcc, 0, v202
	v_pk_fma_f32 v[224:225], v[236:237], v[236:237], v[224:225]
	v_pk_fma_f32 v[228:229], v[226:227], s[60:61], v[176:177] op_sel_hi:[1,0,0]
	s_nop 0
	v_pk_fma_f32 v[228:229], v[226:227], v[228:229], s[64:65] op_sel_hi:[1,1,0]
	s_nop 0
	v_pk_fma_f32 v[228:229], v[226:227], v[228:229], s[66:67] op_sel_hi:[1,1,0]
	s_nop 0
	v_pk_fma_f32 v[228:229], v[226:227], v[228:229], s[24:25] op_sel_hi:[1,1,0]
	s_nop 0
	v_pk_mul_f32 v[226:227], v[226:227], v[228:229]
	v_pk_mul_f32 v[228:229], v[234:235], s[84:85] op_sel_hi:[1,0]
	s_nop 0
	v_exp_f32_e32 v228, v228
	v_exp_f32_e32 v229, v229
	s_nop 0
	v_pk_mul_f32 v[226:227], v[228:229], v[226:227]
	s_nop 0
	v_pk_mul_f32 v[228:229], v[202:203], v[226:227]
	v_pk_fma_f32 v[226:227], v[202:203], v[226:227], v[202:203] neg_lo:[1,0,0] neg_hi:[1,0,0]
	s_nop 0
	v_cndmask_b32_e32 v202, v226, v228, vcc
	v_cmp_gt_f32_e32 vcc, 0, v203
	s_nop 1
	v_cndmask_b32_e32 v203, v227, v229, vcc
	v_pk_add_f32 v[226:227], v[232:233], v[204:205]
	v_pk_add_f32 v[228:229], v[236:237], v[206:207]
	v_cvt_pk_bf16_f32 v204, v232, v233
	v_cvt_pk_bf16_f32 v205, v200, v201
	v_cvt_pk_bf16_f32 v206, v236, v237
	v_cvt_pk_bf16_f32 v207, v202, v203
	global_store_dwordx4 v[180:181], v[204:207], off offset:2560 sc1
	s_nop 1
	v_pk_mul_f32 v[206:207], v[70:71], v[126:127]
	v_pk_mul_f32 v[204:205], v[72:73], v[128:129]
	v_and_b32_e32 v233, 0x7fffffff, v207
	v_and_b32_e32 v232, 0x7fffffff, v206
	v_pk_fma_f32 v[232:233], v[232:233], s[86:87], 1.0 op_sel_hi:[1,0,0]
	v_pk_mul_f32 v[236:237], v[206:207], v[206:207]
	v_rcp_f32_e32 v232, v232
	v_rcp_f32_e32 v233, v233
	v_pk_mul_f32 v[236:237], v[236:237], s[84:85] op_sel_hi:[1,0]
	v_cmp_gt_f32_e32 vcc, 0, v206
	v_exp_f32_e32 v236, v236
	v_pk_fma_f32 v[234:235], v[232:233], s[60:61], v[176:177] op_sel_hi:[1,0,0]
	v_exp_f32_e32 v237, v237
	v_pk_fma_f32 v[234:235], v[232:233], v[234:235], s[64:65] op_sel_hi:[1,1,0]
	s_nop 0
	v_pk_fma_f32 v[234:235], v[232:233], v[234:235], s[66:67] op_sel_hi:[1,1,0]
	s_nop 0
	v_pk_fma_f32 v[234:235], v[232:233], v[234:235], s[24:25] op_sel_hi:[1,1,0]
	s_nop 0
	v_pk_mul_f32 v[232:233], v[232:233], v[234:235]
	v_pk_mul_f32 v[234:235], v[204:205], v[204:205]
	v_pk_mul_f32 v[232:233], v[236:237], v[232:233]
	v_pk_mul_f32 v[234:235], v[234:235], s[84:85] op_sel_hi:[1,0]
	v_pk_mul_f32 v[236:237], v[206:207], v[232:233]
	v_pk_fma_f32 v[232:233], v[206:207], v[232:233], v[206:207] neg_lo:[1,0,0] neg_hi:[1,0,0]
	v_and_b32_e32 v206, 0x7fffffff, v204
	v_cndmask_b32_e32 v232, v232, v236, vcc
	v_cmp_gt_f32_e32 vcc, 0, v207
	v_and_b32_e32 v207, 0x7fffffff, v205
	v_pk_fma_f32 v[206:207], v[206:207], s[86:87], 1.0 op_sel_hi:[1,0,0]
	v_cndmask_b32_e32 v233, v233, v237, vcc
	v_rcp_f32_e32 v206, v206
	v_rcp_f32_e32 v207, v207
	v_exp_f32_e32 v234, v234
	v_exp_f32_e32 v235, v235
	v_cmp_gt_f32_e32 vcc, 0, v204
	v_pk_fma_f32 v[236:237], v[206:207], s[60:61], v[176:177] op_sel_hi:[1,0,0]
	v_pk_add_f32 v[226:227], v[232:233], v[226:227]
	v_pk_fma_f32 v[236:237], v[206:207], v[236:237], s[64:65] op_sel_hi:[1,1,0]
	v_pk_fma_f32 v[208:209], v[232:233], v[232:233], v[208:209]
	v_pk_fma_f32 v[236:237], v[206:207], v[236:237], s[66:67] op_sel_hi:[1,1,0]
	v_cvt_pk_bf16_f32 v232, v232, v233
	s_nop 0
	v_pk_fma_f32 v[236:237], v[206:207], v[236:237], s[24:25] op_sel_hi:[1,1,0]
	s_nop 0
	v_pk_mul_f32 v[206:207], v[206:207], v[236:237]
	s_nop 0
	v_pk_mul_f32 v[206:207], v[234:235], v[206:207]
	s_nop 0
	v_pk_mul_f32 v[234:235], v[204:205], v[206:207]
	v_pk_fma_f32 v[206:207], v[204:205], v[206:207], v[204:205] neg_lo:[1,0,0] neg_hi:[1,0,0]
	s_nop 0
	v_cndmask_b32_e32 v204, v206, v234, vcc
	v_cmp_gt_f32_e32 vcc, 0, v205
	s_nop 1
	v_cndmask_b32_e32 v205, v207, v235, vcc
	v_pk_mul_f32 v[234:235], v[66:67], v[122:123]
	v_pk_mul_f32 v[206:207], v[68:69], v[124:125]
	v_and_b32_e32 v237, 0x7fffffff, v235
	v_and_b32_e32 v236, 0x7fffffff, v234
	v_pk_fma_f32 v[236:237], v[236:237], s[86:87], 1.0 op_sel_hi:[1,0,0]
	v_pk_mul_f32 v[244:245], v[234:235], v[234:235]
	v_rcp_f32_e32 v236, v236
	v_rcp_f32_e32 v237, v237
	v_pk_mul_f32 v[244:245], v[244:245], s[84:85] op_sel_hi:[1,0]
	v_cmp_gt_f32_e32 vcc, 0, v234
	v_exp_f32_e32 v244, v244
	v_pk_fma_f32 v[242:243], v[236:237], s[60:61], v[176:177] op_sel_hi:[1,0,0]
	v_exp_f32_e32 v245, v245
	v_pk_fma_f32 v[242:243], v[236:237], v[242:243], s[64:65] op_sel_hi:[1,1,0]
	v_cvt_pk_bf16_f32 v233, v204, v205
	s_nop 0
	v_pk_fma_f32 v[242:243], v[236:237], v[242:243], s[66:67] op_sel_hi:[1,1,0]
	s_nop 0
	v_pk_fma_f32 v[242:243], v[236:237], v[242:243], s[24:25] op_sel_hi:[1,1,0]
	s_nop 0
; __device__ __forceinline__ unsigned cvt_pk_bf16(float lo, float hi) { unsigned r; asm volatile("v_cvt_pk_bf16_f32 %0, %1, %2" : "=v"(r) : "v"(lo), "v"(hi)); return r; }
; __device__ __forceinline__ f32x4 gelu4(f32x4 v) { f32x2 a = gelu_pk((f32x2){v[0], v[1]}), b = gelu_pk((f32x2){v[2], v[3]}); return (f32x4){a.x, a.y, b.x, b.y}; }
; __device__ __forceinline__ void fx_add(i64* p, float v) { atomicAdd((unsigned long long*)p, (unsigned long long)(i64)(v * FX)); }
;     __device__ __forceinline__ void operator()(const f32x4 (&acc)[2][2][4][2], const Unit& u, int wr, int wc, int fr, int fq, int ui) const {
;     ...
;                         const f32x4 v0 = pg8::gelu4(acc[ai][bj][m][0] * rs0), v1 = pg8::gelu4(acc[ai][bj][m][1] * rs1);
;                         sm0 = sm0 + v0; sm1 = sm1 + v1; sq0 = sq0 + v0 * v0; sq1 = sq1 + v1 * v1;
;                         u32x4 w; w.x = cvt_pk_bf16(v0[0], v0[1]); w.y = cvt_pk_bf16(v0[2], v0[3]); w.z = cvt_pk_bf16(v1[0], v1[1]); w.w = cvt_pk_bf16(v1[2], v1[3]);
;                         *(u32x4*)(Gt + ((size_t)(tok >> 3) * 512 + ch) * 8) = w;
;                     }
; #pragma unroll
;                 for (int i = 0; i < 4; ++i) {
;                     float a0 = sm0[i], a1 = sm1[i], b0 = sq0[i], b1 = sq1[i];
; #pragma unroll
;                     for (int o = 1; o < 16; o <<= 1) { a0 += __shfl_xor(a0, o); a1 += __shfl_xor(a1, o); b0 += __shfl_xor(b0, o); b1 += __shfl_xor(b1, o); }
;                     if (fr == 0) { fx_add(lnsum + tok + i, a0); fx_add(lnsum + tok + 4 + i, a1); fx_add(lnsq + tok + i, b0); fx_add(lnsq + tok + 4 + i, b1); }
;                 }
	v_pk_mul_f32 v[236:237], v[236:237], v[242:243]
	v_pk_mul_f32 v[242:243], v[206:207], v[206:207]
	v_pk_mul_f32 v[236:237], v[244:245], v[236:237]
	s_nop 0
	v_pk_mul_f32 v[244:245], v[234:235], v[236:237]
	v_pk_fma_f32 v[236:237], v[234:235], v[236:237], v[234:235] neg_lo:[1,0,0] neg_hi:[1,0,0]
	s_nop 0
	v_cndmask_b32_e32 v234, v236, v244, vcc
	v_cmp_gt_f32_e32 vcc, 0, v235
	v_and_b32_e32 v236, 0x7fffffff, v206
	s_nop 0
	v_cndmask_b32_e32 v235, v237, v245, vcc
	v_and_b32_e32 v237, 0x7fffffff, v207
	v_pk_fma_f32 v[236:237], v[236:237], s[86:87], 1.0 op_sel_hi:[1,0,0]
	v_cmp_gt_f32_e32 vcc, 0, v206
	v_rcp_f32_e32 v236, v236
	v_rcp_f32_e32 v237, v237
	v_pk_add_f32 v[228:229], v[234:235], v[228:229]
	v_pk_fma_f32 v[224:225], v[234:235], v[234:235], v[224:225]
	v_cvt_pk_bf16_f32 v234, v234, v235
	v_pk_fma_f32 v[176:177], v[236:237], s[60:61], v[176:177] op_sel_hi:[1,0,0]
	s_nop 0
	v_pk_fma_f32 v[176:177], v[236:237], v[176:177], s[64:65] op_sel_hi:[1,1,0]
	s_nop 0
	v_pk_fma_f32 v[176:177], v[236:237], v[176:177], s[66:67] op_sel_hi:[1,1,0]
	s_nop 0
	v_pk_fma_f32 v[176:177], v[236:237], v[176:177], s[24:25] op_sel_hi:[1,1,0]
	s_nop 0
	v_pk_mul_f32 v[176:177], v[236:237], v[176:177]
	v_pk_mul_f32 v[236:237], v[242:243], s[84:85] op_sel_hi:[1,0]
	s_nop 0
	v_exp_f32_e32 v236, v236
	v_exp_f32_e32 v237, v237
	s_nop 0
	v_pk_mul_f32 v[176:177], v[236:237], v[176:177]
	s_nop 0
	v_pk_mul_f32 v[236:237], v[206:207], v[176:177]
	v_pk_fma_f32 v[176:177], v[206:207], v[176:177], v[206:207] neg_lo:[1,0,0] neg_hi:[1,0,0]
	s_nop 0
	v_cndmask_b32_e32 v206, v176, v236, vcc
	v_cmp_gt_f32_e32 vcc, 0, v207
	v_add_u32_e32 v176, 64, v0
	v_xor_b32_e32 v0, 1, v238
	v_cndmask_b32_e32 v207, v177, v237, vcc
	v_cmp_lt_i32_e32 vcc, v0, v176
	v_cvt_pk_bf16_f32 v235, v206, v207
	global_store_dwordx4 v[180:181], v[232:235], off offset:2816 sc1
	s_nop 0
	v_cndmask_b32_e32 v0, v238, v0, vcc
	v_lshlrev_b32_e32 v0, 2, v0
	ds_bpermute_b32 v107, v0, v226
	s_waitcnt lgkmcnt(0)
	v_add_f32_e32 v177, v226, v107
	ds_bpermute_b32 v107, v0, v228
	s_waitcnt lgkmcnt(0)
	v_add_f32_e32 v180, v228, v107
	ds_bpermute_b32 v107, v0, v208
	s_waitcnt lgkmcnt(0)
	v_add_f32_e32 v181, v208, v107
	ds_bpermute_b32 v107, v0, v224
	s_waitcnt lgkmcnt(0)
	v_add_f32_e32 v208, v224, v107
	v_xor_b32_e32 v107, 2, v238
	v_cmp_lt_i32_e32 vcc, v107, v176
	s_nop 1
	v_cndmask_b32_e32 v107, v238, v107, vcc
	v_lshlrev_b32_e32 v107, 2, v107
	ds_bpermute_b32 v224, v107, v177
	s_waitcnt lgkmcnt(0)
	v_add_f32_e32 v177, v177, v224
	ds_bpermute_b32 v224, v107, v180
	s_waitcnt lgkmcnt(0)
	v_add_f32_e32 v180, v180, v224
	ds_bpermute_b32 v224, v107, v181
	s_waitcnt lgkmcnt(0)
	v_add_f32_e32 v181, v181, v224
	ds_bpermute_b32 v224, v107, v208
	s_waitcnt lgkmcnt(0)
	v_add_f32_e32 v224, v208, v224
	v_xor_b32_e32 v208, 4, v238
	v_cmp_lt_i32_e32 vcc, v208, v176
	s_nop 1
	v_cndmask_b32_e32 v208, v238, v208, vcc
	v_lshlrev_b32_e32 v208, 2, v208
	ds_bpermute_b32 v226, v208, v177
	s_waitcnt lgkmcnt(0)
	v_add_f32_e32 v228, v177, v226
	ds_bpermute_b32 v177, v208, v180
	s_waitcnt lgkmcnt(0)
	v_add_f32_e32 v226, v180, v177
	ds_bpermute_b32 v177, v208, v181
	s_waitcnt lgkmcnt(0)
	v_add_f32_e32 v232, v181, v177
	ds_bpermute_b32 v177, v208, v224
	s_waitcnt lgkmcnt(0)
	v_add_f32_e32 v242, v224, v177
	v_xor_b32_e32 v177, 8, v238
	v_cmp_lt_i32_e32 vcc, v177, v176
	s_nop 1
	v_cndmask_b32_e32 v176, v238, v177, vcc
	v_lshlrev_b32_e32 v224, 2, v176
	ds_bpermute_b32 v243, v224, v228
	ds_bpermute_b32 v234, v224, v226
	ds_bpermute_b32 v244, v224, v232
	ds_bpermute_b32 v245, v224, v242
	v_lshlrev_b64 v[176:177], 3, v[168:169]
	v_lshl_add_u64 v[180:181], s[88:89], 0, v[176:177]
	v_lshl_add_u64 v[176:177], s[30:31], 0, v[176:177]
	s_and_saveexec_b64 s[54:55], s[44:45]
	s_cbranch_execz .LBB0_849
	s_waitcnt lgkmcnt(0)
	v_add_f32_e32 v228, v228, v243
	v_mul_f32_e32 v228, 0x4b800000, v228
	v_trunc_f32_e32 v228, v228
	v_add_f32_e32 v235, v232, v244
	v_mul_f32_e64 v232, |v228|, s87
	v_floor_f32_e32 v232, v232
	v_fma_f32 v233, v232, s63, |v228|
	v_cvt_u32_f32_e32 v232, v232
	v_cvt_u32_f32_e32 v233, v233
	v_add_f32_e32 v226, v226, v234
	v_ashrrev_i32_e32 v228, 31, v228
	v_xor_b32_e32 v234, v232, v228
	v_xor_b32_e32 v232, v233, v228
	v_mul_f32_e32 v226, 0x4b800000, v226
	v_sub_co_u32_e32 v232, vcc, v232, v228
	v_trunc_f32_e32 v226, v226
	s_nop 0
	v_subb_co_u32_e32 v233, vcc, v234, v228, vcc
	v_mul_f32_e64 v228, |v226|, s87
	v_floor_f32_e32 v228, v228
	v_fma_f32 v234, v228, s63, |v226|
	v_cvt_u32_f32_e32 v234, v234
	v_cvt_u32_f32_e32 v228, v228
	v_ashrrev_i32_e32 v226, 31, v226
	global_atomic_add_x2 v[180:181], v[232:233], off
	v_xor_b32_e32 v232, v234, v226
	v_xor_b32_e32 v228, v228, v226
	v_sub_co_u32_e32 v232, vcc, v232, v226
	v_add_f32_e32 v169, v242, v245
	s_nop 0
	v_subb_co_u32_e32 v233, vcc, v228, v226, vcc
	v_mul_f32_e32 v226, 0x4b800000, v235
	v_trunc_f32_e32 v226, v226
	v_mul_f32_e64 v228, |v226|, s87
	v_floor_f32_e32 v228, v228
	v_fma_f32 v234, v228, s63, |v226|
	v_cvt_u32_f32_e32 v234, v234
	v_cvt_u32_f32_e32 v228, v228
	v_ashrrev_i32_e32 v226, 31, v226
	global_atomic_add_x2 v[180:181], v[232:233], off offset:32
	v_xor_b32_e32 v232, v234, v226
	v_mul_f32_e32 v169, 0x4b800000, v169
	v_xor_b32_e32 v228, v228, v226
	v_sub_co_u32_e32 v232, vcc, v232, v226
	v_trunc_f32_e32 v169, v169
	s_nop 0
	v_subb_co_u32_e32 v233, vcc, v228, v226, vcc
	v_mul_f32_e64 v226, |v169|, s87
	v_floor_f32_e32 v226, v226
	v_fma_f32 v228, v226, s63, |v169|
	v_cvt_u32_f32_e32 v228, v228
	v_cvt_u32_f32_e32 v226, v226
	v_ashrrev_i32_e32 v169, 31, v169
	global_atomic_add_x2 v[176:177], v[232:233], off
	v_xor_b32_e32 v228, v228, v169
	v_xor_b32_e32 v226, v226, v169
	v_sub_co_u32_e32 v232, vcc, v228, v169
	s_nop 1
	v_subb_co_u32_e32 v233, vcc, v226, v169, vcc
	global_atomic_add_x2 v[176:177], v[232:233], off offset:32

;     __device__ __forceinline__ void operator()(const f32x4 (&acc)[2][2][4][2], const Unit& u, int wr, int wc, int fr, int fq, int ui) const {
;     ...
;             if (sect == 0) {
;                 const int b_ = tok >> 13, t0 = tok & (SEQ - 1);
; #pragma unroll
;                 for (int ai = 0; ai < 2; ++ai)
; #pragma unroll
;                     for (int m = 0; m < 4; ++m) {
;                         const int ch = ch0 + ai * 128 + m * 16;
;                         const size_t bhb = (size_t)(b_ * 8 + (ch >> 6)) * (SEQ * 64) + (size_t)(ch & 63) * 8;
;                         const f32x4 v0 = acc[ai][bj][m][0] * rs0, v1 = acc[ai][bj][m][1] * rs1;
;                         u32x4 w; w.x = cvt_pk_bf16(v0[0], v0[1]); w.y = cvt_pk_bf16(v0[2], v0[3]); w.z = cvt_pk_bf16(v1[0], v1[1]); w.w = cvt_pk_bf16(v1[2], v1[3]);
;                         *(u32x4*)(Vt1 + bhb + (size_t)(t0 >> 3) * 512) = w;
;                         { const unsigned a0 = cvt_pk_bf16(v0[0], v1[0]), a1 = cvt_pk_bf16(v0[1], v1[1]), a2 = cvt_pk_bf16(v0[2], v1[2]), a3 = cvt_pk_bf16(v0[3], v1[3]);
;                           const bool odd = fq & 1;
;                           const unsigned s0 = odd ? a0 : a2, s1 = odd ? a1 : a3;
;                           const unsigned r0 = (unsigned)__shfl_xor((int)s0, 16), r1 = (unsigned)__shfl_xor((int)s1, 16);
;                           const int n = (t0 & ~15) >> 2, rb = odd ? 2 : 0;
;                           bf16_t* p4 = Vt4 + bhb + (size_t)(rb * 256 + (n >> 3)) * 512 + (n & 7);
;                           u32x2 q0, q1; q0.x = odd ? r0 : a0; q0.y = odd ? a2 : r0; q1.x = odd ? r1 : a1; q1.y = odd ? a3 : r1;
;                           *(u32x2*)p4 = q0; *(u32x2*)(p4 + (size_t)256 * 512) = q1; }
;                         { const bool hi = fq & 2;
;                           const unsigned s0 = hi ? w.x : w.z, s1 = hi ? w.y : w.w;
;                           const unsigned r0 = (unsigned)__shfl_xor((int)s0, 32), r1 = (unsigned)__shfl_xor((int)s1, 32);
;                           const unsigned lo0 = hi ? r0 : w.x, lo1 = hi ? r1 : w.y, hi0 = hi ? w.z : r0, hi1 = hi ? w.w : r1;
;                           const int n = (t0 & ~31) >> 4, rb = (t0 & 8) + (hi ? 4 : 0);
;                           bf16_t* p16 = Vt16 + bhb + (size_t)(rb * 64 + (n >> 3)) * 512 + (n & 7);
.LBB0_856:
	s_ashr_i32 s4, s20, 2
	s_and_b32 s93, s4, -8
	s_and_b64 vcc, exec, s[54:55]
	v_lshlrev_b32_e32 v94, 1, v148
	s_cbranch_vccz .LBB0_858
	s_lshl_b32 s4, s21, 4
	s_and_b32 s4, s4, 0x1f600
	v_or_b32_e32 v95, s4, v153
	v_lshlrev_b32_e32 v0, 2, v168
	s_movk_i32 s4, 0x7c00
	v_and_or_b32 v182, v0, s4, v155
	s_ashr_i32 s4, s36, 6
	s_add_i32 s4, s4, s93
	s_ashr_i32 s5, s4, 31
	s_lshl_b64 s[54:55], s[4:5], 19
	v_mov_b32_e32 v179, s55
	s_waitcnt lgkmcnt(0)
	v_or_b32_e32 v178, s54, v146
	v_lshlrev_b64 v[178:179], 1, v[178:179]
	v_lshlrev_b32_e32 v0, 7, v168
	v_lshl_add_u64 v[180:181], s[42:43], 0, v[178:179]
	v_and_b32_e32 v0, 0xfbc00, v0
	v_pk_mul_f32 v[136:137], v[136:137], v[128:129]
	v_lshl_add_u64 v[180:181], v[180:181], 0, v[0:1]
	v_pk_mul_f32 v[132:133], v[132:133], v[124:125]
	v_cvt_pk_bf16_f32 v174, v170, v171
	v_cvt_pk_bf16_f32 v175, v136, v137
	v_cvt_pk_bf16_f32 v176, v172, v173
	v_xor_b32_e32 v107, 16, v238
	v_cvt_pk_bf16_f32 v177, v132, v133
	global_store_dwordx4 v[180:181], v[174:177], off sc1
	v_cvt_pk_bf16_f32 v169, v170, v172
	v_cvt_pk_bf16_f32 v172, v171, v173
	v_cvt_pk_bf16_f32 v171, v136, v132
	v_and_b32_e32 v136, 64, v238
	v_add_u32_e32 v180, 64, v136
	v_cmp_lt_i32_e32 vcc, v107, v180
	v_cndmask_b32_e64 v132, v169, v171, s[46:47]
	v_cvt_pk_bf16_f32 v173, v137, v133
	v_lshl_add_u64 v[136:137], s[76:77], 0, v[178:179]
	v_cndmask_b32_e32 v107, v238, v107, vcc
	v_lshlrev_b32_e32 v107, 2, v107
	ds_bpermute_b32 v181, v107, v132
	v_cndmask_b32_e64 v133, v172, v173, s[46:47]
	ds_bpermute_b32 v183, v107, v133
	v_lshlrev_b32_e32 v132, 1, v95
	v_mov_b32_e32 v133, v1
	s_waitcnt lgkmcnt(0)
	v_cndmask_b32_e64 v170, v181, v169, s[46:47]
	v_xor_b32_e32 v169, 32, v238
	v_lshl_add_u64 v[136:137], v[136:137], 0, v[132:133]
	v_mov_b32_e32 v95, v1
	v_cmp_lt_i32_e32 vcc, v169, v180
	v_lshl_add_u64 v[136:137], v[136:137], 0, v[94:95]
	v_cndmask_b32_e64 v171, v171, v181, s[46:47]
	v_cndmask_b32_e32 v169, v238, v169, vcc
	global_store_dwordx2 v[136:137], v[170:171], off
	v_cndmask_b32_e64 v170, v174, v176, s[48:49]
	v_cndmask_b32_e64 v171, v175, v177, s[48:49]
	v_lshlrev_b32_e32 v169, 2, v169
	ds_bpermute_b32 v170, v169, v170
	ds_bpermute_b32 v171, v169, v171
	v_add_co_u32_e32 v136, vcc, s33, v136
	v_cndmask_b32_e64 v172, v183, v172, s[46:47]
	v_cndmask_b32_e64 v173, v173, v183, s[46:47]
	v_addc_co_u32_e32 v137, vcc, 0, v137, vcc
	global_store_dwordx2 v[136:137], v[172:173], off
	s_waitcnt lgkmcnt(0)
	v_cndmask_b32_e64 v174, v170, v174, s[48:49]
	v_cndmask_b32_e64 v180, v171, v175, s[48:49]
	v_cndmask_b32_e64 v175, v176, v170, s[48:49]
	v_cndmask_b32_e64 v176, v177, v171, s[48:49]
	v_lshl_add_u64 v[170:171], s[78:79], 0, v[178:179]
	v_lshlrev_b32_e32 v136, 1, v182
	v_mov_b32_e32 v137, v1
	v_lshl_add_u64 v[172:173], v[170:171], 0, v[136:137]
	v_lshrrev_b32_e32 v170, 3, v168
	v_and_b32_e32 v170, 12, v170
	v_mov_b32_e32 v171, v1
	v_lshlrev_b32_e32 v177, 16, v175
	v_lshl_add_u64 v[172:173], v[172:173], 0, v[170:171]
	v_and_or_b32 v177, v174, s85, v177
	v_lshrrev_b32_e32 v174, 16, v174
	global_store_dword v[172:173], v177, off
	v_and_or_b32 v177, v175, s56, v174
	v_add_co_u32_e32 v174, vcc, s65, v172
	v_pk_mul_f32 v[178:179], v[116:117], v[124:125]
	s_nop 0
	v_addc_co_u32_e32 v175, vcc, 0, v173, vcc
	global_store_dword v[174:175], v177, off
	v_lshlrev_b32_e32 v174, 16, v176
	v_and_or_b32 v177, v180, s85, v174
	v_add_co_u32_e32 v174, vcc, s25, v172
	v_lshl_add_u64 v[116:117], s[42:43], 0, v[0:1]
	s_nop 0
	v_addc_co_u32_e32 v175, vcc, 0, v173, vcc
	global_store_dword v[174:175], v177, off
	v_lshrrev_b32_e32 v174, 16, v180
	v_and_or_b32 v174, v176, s56, v174
	v_mov_b32_e32 v177, s55
	v_or_b32_e32 v176, s54, v150
	v_add_co_u32_e32 v172, vcc, s57, v172
	v_lshlrev_b64 v[176:177], 1, v[176:177]
	s_nop 0
	v_addc_co_u32_e32 v173, vcc, 0, v173, vcc
	v_pk_mul_f32 v[120:121], v[120:121], v[128:129]
	v_lshl_add_u64 v[180:181], v[116:117], 0, v[176:177]
	global_store_dword v[172:173], v174, off
	v_cvt_pk_bf16_f32 v172, v130, v131
	v_cvt_pk_bf16_f32 v173, v120, v121
	v_cvt_pk_bf16_f32 v174, v134, v135
	v_cvt_pk_bf16_f32 v175, v178, v179
	global_store_dwordx4 v[180:181], v[172:175], off sc1
	v_cvt_pk_bf16_f32 v134, v130, v134
	v_cvt_pk_bf16_f32 v180, v131, v135
	v_cvt_pk_bf16_f32 v135, v120, v178
	v_cvt_pk_bf16_f32 v179, v121, v179
	v_pk_mul_f32 v[108:109], v[108:109], v[124:125]
	v_cndmask_b32_e64 v120, v134, v135, s[46:47]
	ds_bpermute_b32 v178, v107, v120
	v_cndmask_b32_e64 v120, v180, v179, s[46:47]
	ds_bpermute_b32 v181, v107, v120
	v_lshl_add_u64 v[120:121], v[156:157], 0, v[132:133]
	v_lshl_add_u64 v[130:131], v[120:121], 0, v[176:177]
	s_waitcnt lgkmcnt(0)
	v_cndmask_b32_e64 v134, v178, v134, s[46:47]
	v_cndmask_b32_e64 v135, v135, v178, s[46:47]
	global_store_dwordx2 v[130:131], v[134:135], off
	v_cndmask_b32_e64 v134, v172, v174, s[48:49]
	v_cndmask_b32_e64 v135, v173, v175, s[48:49]
	ds_bpermute_b32 v134, v169, v134
	ds_bpermute_b32 v135, v169, v135
	v_add_co_u32_e32 v130, vcc, s33, v130
	v_cndmask_b32_e64 v178, v181, v180, s[46:47]
	v_cndmask_b32_e64 v179, v179, v181, s[46:47]
	v_addc_co_u32_e32 v131, vcc, 0, v131, vcc
	global_store_dwordx2 v[130:131], v[178:179], off
	s_waitcnt lgkmcnt(0)
;     __device__ __forceinline__ void operator()(const f32x4 (&acc)[2][2][4][2], const Unit& u, int wr, int wc, int fr, int fq, int ui) const {
;     ...
;             if (sect == 0) {
;                 const int b_ = tok >> 13, t0 = tok & (SEQ - 1);
; #pragma unroll
;                 for (int ai = 0; ai < 2; ++ai)
; #pragma unroll
;                     for (int m = 0; m < 4; ++m) {
;                         const int ch = ch0 + ai * 128 + m * 16;
;                         const size_t bhb = (size_t)(b_ * 8 + (ch >> 6)) * (SEQ * 64) + (size_t)(ch & 63) * 8;
;                         const f32x4 v0 = acc[ai][bj][m][0] * rs0, v1 = acc[ai][bj][m][1] * rs1;
;                         u32x4 w; w.x = cvt_pk_bf16(v0[0], v0[1]); w.y = cvt_pk_bf16(v0[2], v0[3]); w.z = cvt_pk_bf16(v1[0], v1[1]); w.w = cvt_pk_bf16(v1[2], v1[3]);
;                         *(u32x4*)(Vt1 + bhb + (size_t)(t0 >> 3) * 512) = w;
;                         { const unsigned a0 = cvt_pk_bf16(v0[0], v1[0]), a1 = cvt_pk_bf16(v0[1], v1[1]), a2 = cvt_pk_bf16(v0[2], v1[2]), a3 = cvt_pk_bf16(v0[3], v1[3]);
;                           const bool odd = fq & 1;
;                           const unsigned s0 = odd ? a0 : a2, s1 = odd ? a1 : a3;
;                           const unsigned r0 = (unsigned)__shfl_xor((int)s0, 16), r1 = (unsigned)__shfl_xor((int)s1, 16);
;                           const int n = (t0 & ~15) >> 2, rb = odd ? 2 : 0;
;                           bf16_t* p4 = Vt4 + bhb + (size_t)(rb * 256 + (n >> 3)) * 512 + (n & 7);
;                           u32x2 q0, q1; q0.x = odd ? r0 : a0; q0.y = odd ? a2 : r0; q1.x = odd ? r1 : a1; q1.y = odd ? a3 : r1;
;                           *(u32x2*)p4 = q0; *(u32x2*)(p4 + (size_t)256 * 512) = q1; }
;                         { const bool hi = fq & 2;
;                           const unsigned s0 = hi ? w.x : w.z, s1 = hi ? w.y : w.w;
;                           const unsigned r0 = (unsigned)__shfl_xor((int)s0, 32), r1 = (unsigned)__shfl_xor((int)s1, 32);
;                           const unsigned lo0 = hi ? r0 : w.x, lo1 = hi ? r1 : w.y, hi0 = hi ? w.z : r0, hi1 = hi ? w.w : r1;
;                           const int n = (t0 & ~31) >> 4, rb = (t0 & 8) + (hi ? 4 : 0);
;                           bf16_t* p16 = Vt16 + bhb + (size_t)(rb * 64 + (n >> 3)) * 512 + (n & 7);
	v_cndmask_b32_e64 v178, v135, v173, s[48:49]
	v_cndmask_b32_e64 v173, v174, v134, s[48:49]
	v_lshl_add_u64 v[130:131], s[78:79], 0, v[136:137]
	v_cndmask_b32_e64 v172, v134, v172, s[48:49]
	v_cndmask_b32_e64 v174, v175, v135, s[48:49]
	v_lshl_add_u64 v[130:131], v[130:131], 0, v[170:171]
	v_lshlrev_b32_e32 v175, 16, v173
	v_lshl_add_u64 v[134:135], v[130:131], 0, v[176:177]
	v_and_or_b32 v175, v172, s85, v175
	v_lshrrev_b32_e32 v172, 16, v172
	global_store_dword v[134:135], v175, off
	v_and_or_b32 v175, v173, s56, v172
	v_add_co_u32_e32 v172, vcc, s65, v134
	v_pk_mul_f32 v[112:113], v[112:113], v[128:129]
	s_nop 0
	v_addc_co_u32_e32 v173, vcc, 0, v135, vcc
	global_store_dword v[172:173], v175, off
	v_lshlrev_b32_e32 v172, 16, v174
	v_and_or_b32 v175, v178, s85, v172
	v_add_co_u32_e32 v172, vcc, s25, v134
	v_pk_mul_f32 v[100:101], v[100:101], v[124:125]
	s_nop 0
	v_addc_co_u32_e32 v173, vcc, 0, v135, vcc
	global_store_dword v[172:173], v175, off
	v_lshrrev_b32_e32 v172, 16, v178
	v_add_co_u32_e32 v134, vcc, s57, v134
	v_and_or_b32 v172, v174, s56, v172
	s_nop 0
	v_addc_co_u32_e32 v135, vcc, 0, v135, vcc
	global_store_dword v[134:135], v172, off
	v_mov_b32_e32 v135, s55
	v_or_b32_e32 v134, s54, v152
	v_lshlrev_b64 v[134:135], 1, v[134:135]
	v_lshl_add_u64 v[176:177], v[116:117], 0, v[134:135]
	v_cvt_pk_bf16_f32 v172, v114, v115
	v_cvt_pk_bf16_f32 v173, v112, v113
	v_cvt_pk_bf16_f32 v174, v118, v119
	v_cvt_pk_bf16_f32 v175, v108, v109
	global_store_dwordx4 v[176:177], v[172:175], off sc1
	v_cvt_pk_bf16_f32 v114, v114, v118
	v_cvt_pk_bf16_f32 v115, v115, v119
	v_cvt_pk_bf16_f32 v118, v112, v108
	v_cvt_pk_bf16_f32 v119, v113, v109
	v_pk_mul_f32 v[104:105], v[104:105], v[128:129]
	v_cndmask_b32_e64 v108, v114, v118, s[46:47]
	ds_bpermute_b32 v113, v107, v108
	v_cndmask_b32_e64 v108, v115, v119, s[46:47]
	ds_bpermute_b32 v176, v107, v108
	v_lshl_add_u64 v[108:109], v[120:121], 0, v[134:135]
	s_add_i32 s4, s36, 0x80
	s_waitcnt lgkmcnt(0)
	v_cndmask_b32_e64 v112, v113, v114, s[46:47]
	v_cndmask_b32_e64 v113, v118, v113, s[46:47]
	global_store_dwordx2 v[108:109], v[112:113], off
	v_cndmask_b32_e64 v112, v172, v174, s[48:49]
	v_cndmask_b32_e64 v113, v173, v175, s[48:49]
	ds_bpermute_b32 v112, v169, v112
	ds_bpermute_b32 v113, v169, v113
	v_add_co_u32_e32 v108, vcc, s33, v108
	v_cndmask_b32_e64 v114, v176, v115, s[46:47]
	v_cndmask_b32_e64 v115, v119, v176, s[46:47]
	v_addc_co_u32_e32 v109, vcc, 0, v109, vcc
	global_store_dwordx2 v[108:109], v[114:115], off
	s_waitcnt lgkmcnt(0)
	v_cndmask_b32_e64 v114, v112, v172, s[48:49]
	v_cndmask_b32_e64 v112, v174, v112, s[48:49]
	v_cndmask_b32_e64 v115, v113, v173, s[48:49]
	v_cndmask_b32_e64 v118, v175, v113, s[48:49]
	v_lshlrev_b32_e32 v113, 16, v112
	v_lshl_add_u64 v[108:109], v[130:131], 0, v[134:135]
	v_and_or_b32 v113, v114, s85, v113
	global_store_dword v[108:109], v113, off
	v_lshrrev_b32_e32 v113, 16, v114
	v_and_or_b32 v114, v112, s56, v113
	v_add_co_u32_e32 v112, vcc, s65, v108
	s_ashr_i32 s4, s4, 6
	s_nop 0
	v_addc_co_u32_e32 v113, vcc, 0, v109, vcc
	global_store_dword v[112:113], v114, off
	v_lshlrev_b32_e32 v112, 16, v118
	v_and_or_b32 v114, v115, s85, v112
	v_add_co_u32_e32 v112, vcc, s25, v108
	s_add_i32 s4, s4, s93
	s_nop 0
	v_addc_co_u32_e32 v113, vcc, 0, v109, vcc
	global_store_dword v[112:113], v114, off
	v_lshrrev_b32_e32 v112, 16, v115
	v_add_co_u32_e32 v108, vcc, s57, v108
	v_and_or_b32 v112, v118, s56, v112
	s_nop 0
	v_addc_co_u32_e32 v109, vcc, 0, v109, vcc
	global_store_dword v[108:109], v112, off
	v_mov_b32_e32 v109, s55
	v_or_b32_e32 v108, s54, v154
	v_lshlrev_b64 v[108:109], 1, v[108:109]
	v_lshl_add_u64 v[118:119], v[116:117], 0, v[108:109]
	v_cvt_pk_bf16_f32 v112, v102, v103
	v_cvt_pk_bf16_f32 v113, v104, v105
	v_cvt_pk_bf16_f32 v114, v110, v111
	v_cvt_pk_bf16_f32 v115, v100, v101
	global_store_dwordx4 v[118:119], v[112:115], off sc1
	v_cvt_pk_bf16_f32 v102, v102, v110
	v_cvt_pk_bf16_f32 v110, v103, v111
	v_cvt_pk_bf16_f32 v103, v104, v100
	v_cvt_pk_bf16_f32 v105, v105, v101
	s_ashr_i32 s5, s4, 31
	v_cndmask_b32_e64 v100, v102, v103, s[46:47]
	ds_bpermute_b32 v104, v107, v100
	v_cndmask_b32_e64 v100, v110, v105, s[46:47]
	ds_bpermute_b32 v111, v107, v100
	v_lshl_add_u64 v[100:101], v[120:121], 0, v[108:109]
	s_lshl_b64 s[54:55], s[4:5], 19
	s_waitcnt lgkmcnt(0)
	v_cndmask_b32_e64 v102, v104, v102, s[46:47]
	v_cndmask_b32_e64 v103, v103, v104, s[46:47]
	global_store_dwordx2 v[100:101], v[102:103], off
	v_cndmask_b32_e64 v102, v112, v114, s[48:49]
	v_cndmask_b32_e64 v103, v113, v115, s[48:49]
	ds_bpermute_b32 v102, v169, v102
	ds_bpermute_b32 v103, v169, v103
	v_add_co_u32_e32 v100, vcc, s33, v100
	v_cndmask_b32_e64 v104, v111, v110, s[46:47]
	v_cndmask_b32_e64 v105, v105, v111, s[46:47]
	v_addc_co_u32_e32 v101, vcc, 0, v101, vcc
	global_store_dwordx2 v[100:101], v[104:105], off
	s_waitcnt lgkmcnt(0)
;     __device__ __forceinline__ void operator()(const f32x4 (&acc)[2][2][4][2], const Unit& u, int wr, int wc, int fr, int fq, int ui) const {
;     ...
;             if (sect == 0) {
;                 const int b_ = tok >> 13, t0 = tok & (SEQ - 1);
; #pragma unroll
;                 for (int ai = 0; ai < 2; ++ai)
; #pragma unroll
;                     for (int m = 0; m < 4; ++m) {
;                         const int ch = ch0 + ai * 128 + m * 16;
;                         const size_t bhb = (size_t)(b_ * 8 + (ch >> 6)) * (SEQ * 64) + (size_t)(ch & 63) * 8;
;                         const f32x4 v0 = acc[ai][bj][m][0] * rs0, v1 = acc[ai][bj][m][1] * rs1;
;                         u32x4 w; w.x = cvt_pk_bf16(v0[0], v0[1]); w.y = cvt_pk_bf16(v0[2], v0[3]); w.z = cvt_pk_bf16(v1[0], v1[1]); w.w = cvt_pk_bf16(v1[2], v1[3]);
;                         *(u32x4*)(Vt1 + bhb + (size_t)(t0 >> 3) * 512) = w;
;                         { const unsigned a0 = cvt_pk_bf16(v0[0], v1[0]), a1 = cvt_pk_bf16(v0[1], v1[1]), a2 = cvt_pk_bf16(v0[2], v1[2]), a3 = cvt_pk_bf16(v0[3], v1[3]);
;                           const bool odd = fq & 1;
;                           const unsigned s0 = odd ? a0 : a2, s1 = odd ? a1 : a3;
;                           const unsigned r0 = (unsigned)__shfl_xor((int)s0, 16), r1 = (unsigned)__shfl_xor((int)s1, 16);
;                           const int n = (t0 & ~15) >> 2, rb = odd ? 2 : 0;
;                           bf16_t* p4 = Vt4 + bhb + (size_t)(rb * 256 + (n >> 3)) * 512 + (n & 7);
;                           u32x2 q0, q1; q0.x = odd ? r0 : a0; q0.y = odd ? a2 : r0; q1.x = odd ? r1 : a1; q1.y = odd ? a3 : r1;
;                           *(u32x2*)p4 = q0; *(u32x2*)(p4 + (size_t)256 * 512) = q1; }
;                         { const bool hi = fq & 2;
;                           const unsigned s0 = hi ? w.x : w.z, s1 = hi ? w.y : w.w;
;                           const unsigned r0 = (unsigned)__shfl_xor((int)s0, 32), r1 = (unsigned)__shfl_xor((int)s1, 32);
;                           const unsigned lo0 = hi ? r0 : w.x, lo1 = hi ? r1 : w.y, hi0 = hi ? w.z : r0, hi1 = hi ? w.w : r1;
;                           const int n = (t0 & ~31) >> 4, rb = (t0 & 8) + (hi ? 4 : 0);
;                           bf16_t* p16 = Vt16 + bhb + (size_t)(rb * 64 + (n >> 3)) * 512 + (n & 7);
	v_cndmask_b32_e64 v104, v102, v112, s[48:49]
	v_cndmask_b32_e64 v102, v114, v102, s[48:49]
	v_cndmask_b32_e64 v105, v103, v113, s[48:49]
	v_cndmask_b32_e64 v110, v115, v103, s[48:49]
	v_lshlrev_b32_e32 v103, 16, v102
	v_lshl_add_u64 v[100:101], v[130:131], 0, v[108:109]
	v_and_or_b32 v103, v104, s85, v103
	global_store_dword v[100:101], v103, off
	v_lshrrev_b32_e32 v103, 16, v104
	v_and_or_b32 v104, v102, s56, v103
	v_add_co_u32_e32 v102, vcc, s65, v100
	v_pk_mul_f32 v[96:97], v[96:97], v[128:129]
	s_nop 0
	v_addc_co_u32_e32 v103, vcc, 0, v101, vcc
	global_store_dword v[102:103], v104, off
	v_lshlrev_b32_e32 v102, 16, v110
	v_and_or_b32 v104, v105, s85, v102
	v_add_co_u32_e32 v102, vcc, s25, v100
	v_pk_mul_f32 v[86:87], v[86:87], v[126:127]
	s_nop 0
	v_addc_co_u32_e32 v103, vcc, 0, v101, vcc
	global_store_dword v[102:103], v104, off
	v_lshrrev_b32_e32 v102, 16, v105
	v_add_co_u32_e32 v100, vcc, s57, v100
	v_and_or_b32 v102, v110, s56, v102
	s_nop 0
	v_addc_co_u32_e32 v101, vcc, 0, v101, vcc
	global_store_dword v[100:101], v102, off
	v_mov_b32_e32 v101, s55
	v_or_b32_e32 v100, s54, v146
	v_lshlrev_b64 v[100:101], 1, v[100:101]
	v_lshl_add_u64 v[108:109], s[42:43], 0, v[100:101]
	v_pk_mul_f32 v[104:105], v[90:91], v[122:123]
	v_lshl_add_u64 v[108:109], v[108:109], 0, v[0:1]
	v_pk_mul_f32 v[102:103], v[92:93], v[124:125]
	v_cvt_pk_bf16_f32 v90, v98, v99
	v_cvt_pk_bf16_f32 v91, v96, v97
	v_cvt_pk_bf16_f32 v92, v104, v105
	v_pk_mul_f32 v[88:89], v[88:89], v[128:129]
	v_cvt_pk_bf16_f32 v93, v102, v103
	global_store_dwordx4 v[108:109], v[90:93], off sc1
	v_cvt_pk_bf16_f32 v0, v98, v104
	v_cvt_pk_bf16_f32 v104, v99, v105
	v_cvt_pk_bf16_f32 v99, v96, v102
	v_cvt_pk_bf16_f32 v103, v97, v103
	v_pk_mul_f32 v[78:79], v[78:79], v[126:127]
	v_cndmask_b32_e64 v96, v0, v99, s[46:47]
	ds_bpermute_b32 v102, v107, v96
	v_cndmask_b32_e64 v97, v104, v103, s[46:47]
	ds_bpermute_b32 v105, v107, v97
	v_lshl_add_u64 v[96:97], s[76:77], 0, v[100:101]
	v_lshl_add_u64 v[96:97], v[96:97], 0, v[132:133]
	v_lshl_add_u64 v[96:97], v[96:97], 0, v[94:95]
	s_waitcnt lgkmcnt(0)
	v_cndmask_b32_e64 v98, v102, v0, s[46:47]
	v_cndmask_b32_e64 v0, v90, v92, s[48:49]
	v_cndmask_b32_e64 v95, v91, v93, s[48:49]
	ds_bpermute_b32 v0, v169, v0
	ds_bpermute_b32 v95, v169, v95
	v_cndmask_b32_e64 v99, v99, v102, s[46:47]
	global_store_dwordx2 v[96:97], v[98:99], off
	v_add_co_u32_e32 v96, vcc, s33, v96
	v_cndmask_b32_e64 v102, v105, v104, s[46:47]
	v_cndmask_b32_e64 v103, v103, v105, s[46:47]
	v_addc_co_u32_e32 v97, vcc, 0, v97, vcc
	global_store_dwordx2 v[96:97], v[102:103], off
	s_waitcnt lgkmcnt(0)
	v_cndmask_b32_e64 v96, v0, v90, s[48:49]
	v_cndmask_b32_e64 v97, v95, v91, s[48:49]
	v_cndmask_b32_e64 v0, v92, v0, s[48:49]
	v_lshl_add_u64 v[90:91], s[78:79], 0, v[100:101]
	v_lshl_add_u64 v[90:91], v[90:91], 0, v[136:137]
	v_lshlrev_b32_e32 v92, 16, v0
	v_lshl_add_u64 v[90:91], v[90:91], 0, v[170:171]
	v_and_or_b32 v92, v96, s85, v92
	global_store_dword v[90:91], v92, off
	v_lshrrev_b32_e32 v92, 16, v96
	v_and_or_b32 v0, v0, s56, v92
	v_add_co_u32_e32 v92, vcc, s65, v90
	v_cndmask_b32_e64 v95, v93, v95, s[48:49]
	s_nop 0
	v_addc_co_u32_e32 v93, vcc, 0, v91, vcc
	global_store_dword v[92:93], v0, off
	v_lshlrev_b32_e32 v0, 16, v95
	v_add_co_u32_e32 v92, vcc, s25, v90
	v_and_or_b32 v0, v97, s85, v0
	s_nop 0
	v_addc_co_u32_e32 v93, vcc, 0, v91, vcc
	global_store_dword v[92:93], v0, off
	v_lshrrev_b32_e32 v0, 16, v97
	v_add_co_u32_e32 v90, vcc, s57, v90
	v_and_or_b32 v0, v95, s56, v0
	s_nop 0
	v_addc_co_u32_e32 v91, vcc, 0, v91, vcc
	global_store_dword v[90:91], v0, off
	v_mov_b32_e32 v91, s55
	v_or_b32_e32 v90, s54, v150
	v_lshlrev_b64 v[90:91], 1, v[90:91]
	v_pk_mul_f32 v[92:93], v[84:85], v[124:125]
	v_lshl_add_u64 v[98:99], v[116:117], 0, v[90:91]
	v_pk_mul_f32 v[96:97], v[82:83], v[122:123]
	v_cvt_pk_bf16_f32 v82, v86, v87
	v_cvt_pk_bf16_f32 v83, v88, v89
	v_pk_mul_f32 v[80:81], v[80:81], v[128:129]
	v_cvt_pk_bf16_f32 v84, v96, v97
	v_cvt_pk_bf16_f32 v85, v92, v93
	global_store_dwordx4 v[98:99], v[82:85], off sc1
	v_cvt_pk_bf16_f32 v0, v86, v96
	v_cvt_pk_bf16_f32 v95, v87, v97
	v_cvt_pk_bf16_f32 v92, v88, v92
	v_cvt_pk_bf16_f32 v93, v89, v93
	v_pk_mul_f32 v[70:71], v[70:71], v[126:127]
	v_cndmask_b32_e64 v86, v0, v92, s[46:47]
	ds_bpermute_b32 v89, v107, v86
	v_cndmask_b32_e64 v86, v95, v93, s[46:47]
	ds_bpermute_b32 v96, v107, v86
	v_lshl_add_u64 v[86:87], v[120:121], 0, v[90:91]
	v_pk_mul_f32 v[72:73], v[72:73], v[128:129]
	s_waitcnt lgkmcnt(0)
	v_cndmask_b32_e64 v88, v89, v0, s[46:47]
	v_cndmask_b32_e64 v0, v82, v84, s[48:49]
	v_cndmask_b32_e64 v89, v92, v89, s[46:47]
	ds_bpermute_b32 v0, v169, v0
	global_store_dwordx2 v[86:87], v[88:89], off
	v_cndmask_b32_e64 v88, v83, v85, s[48:49]
	ds_bpermute_b32 v88, v169, v88
	v_add_co_u32_e32 v86, vcc, s33, v86
	v_cndmask_b32_e64 v92, v96, v95, s[46:47]
	v_cndmask_b32_e64 v93, v93, v96, s[46:47]
	v_addc_co_u32_e32 v87, vcc, 0, v87, vcc
	global_store_dwordx2 v[86:87], v[92:93], off
	s_waitcnt lgkmcnt(0)
;     __device__ __forceinline__ void operator()(const f32x4 (&acc)[2][2][4][2], const Unit& u, int wr, int wc, int fr, int fq, int ui) const {
;     ...
;             if (sect == 0) {
;                 const int b_ = tok >> 13, t0 = tok & (SEQ - 1);
; #pragma unroll
;                 for (int ai = 0; ai < 2; ++ai)
; #pragma unroll
;                     for (int m = 0; m < 4; ++m) {
;                         const int ch = ch0 + ai * 128 + m * 16;
;                         const size_t bhb = (size_t)(b_ * 8 + (ch >> 6)) * (SEQ * 64) + (size_t)(ch & 63) * 8;
;                         const f32x4 v0 = acc[ai][bj][m][0] * rs0, v1 = acc[ai][bj][m][1] * rs1;
;                         u32x4 w; w.x = cvt_pk_bf16(v0[0], v0[1]); w.y = cvt_pk_bf16(v0[2], v0[3]); w.z = cvt_pk_bf16(v1[0], v1[1]); w.w = cvt_pk_bf16(v1[2], v1[3]);
;                         *(u32x4*)(Vt1 + bhb + (size_t)(t0 >> 3) * 512) = w;
;                         { const unsigned a0 = cvt_pk_bf16(v0[0], v1[0]), a1 = cvt_pk_bf16(v0[1], v1[1]), a2 = cvt_pk_bf16(v0[2], v1[2]), a3 = cvt_pk_bf16(v0[3], v1[3]);
;                           const bool odd = fq & 1;
;                           const unsigned s0 = odd ? a0 : a2, s1 = odd ? a1 : a3;
;                           const unsigned r0 = (unsigned)__shfl_xor((int)s0, 16), r1 = (unsigned)__shfl_xor((int)s1, 16);
;                           const int n = (t0 & ~15) >> 2, rb = odd ? 2 : 0;
;                           bf16_t* p4 = Vt4 + bhb + (size_t)(rb * 256 + (n >> 3)) * 512 + (n & 7);
;                           u32x2 q0, q1; q0.x = odd ? r0 : a0; q0.y = odd ? a2 : r0; q1.x = odd ? r1 : a1; q1.y = odd ? a3 : r1;
;                           *(u32x2*)p4 = q0; *(u32x2*)(p4 + (size_t)256 * 512) = q1; }
;                         { const bool hi = fq & 2;
;                           const unsigned s0 = hi ? w.x : w.z, s1 = hi ? w.y : w.w;
;                           const unsigned r0 = (unsigned)__shfl_xor((int)s0, 32), r1 = (unsigned)__shfl_xor((int)s1, 32);
;                           const unsigned lo0 = hi ? r0 : w.x, lo1 = hi ? r1 : w.y, hi0 = hi ? w.z : r0, hi1 = hi ? w.w : r1;
;                           const int n = (t0 & ~31) >> 4, rb = (t0 & 8) + (hi ? 4 : 0);
;                           bf16_t* p16 = Vt16 + bhb + (size_t)(rb * 64 + (n >> 3)) * 512 + (n & 7);
	v_cndmask_b32_e64 v86, v0, v82, s[48:49]
	v_cndmask_b32_e64 v0, v84, v0, s[48:49]
	v_lshlrev_b32_e32 v84, 16, v0
	v_cndmask_b32_e64 v87, v88, v83, s[48:49]
	v_lshl_add_u64 v[82:83], v[130:131], 0, v[90:91]
	v_and_or_b32 v84, v86, s85, v84
	global_store_dword v[82:83], v84, off
	v_lshrrev_b32_e32 v84, 16, v86
	v_and_or_b32 v0, v0, s56, v84
	v_add_co_u32_e32 v84, vcc, s65, v82
	v_cndmask_b32_e64 v88, v85, v88, s[48:49]
	s_nop 0
	v_addc_co_u32_e32 v85, vcc, 0, v83, vcc
	global_store_dword v[84:85], v0, off
	v_lshlrev_b32_e32 v0, 16, v88
	v_add_co_u32_e32 v84, vcc, s25, v82
	v_and_or_b32 v0, v87, s85, v0
	s_nop 0
	v_addc_co_u32_e32 v85, vcc, 0, v83, vcc
	global_store_dword v[84:85], v0, off
	v_lshrrev_b32_e32 v0, 16, v87
	v_add_co_u32_e32 v82, vcc, s57, v82
	v_and_or_b32 v0, v88, s56, v0
	s_nop 0
	v_addc_co_u32_e32 v83, vcc, 0, v83, vcc
	global_store_dword v[82:83], v0, off
	v_mov_b32_e32 v83, s55
	v_or_b32_e32 v82, s54, v152
	v_lshlrev_b64 v[82:83], 1, v[82:83]
	v_pk_mul_f32 v[84:85], v[76:77], v[124:125]
	v_pk_mul_f32 v[86:87], v[74:75], v[122:123]
	v_lshl_add_u64 v[88:89], v[116:117], 0, v[82:83]
	v_cvt_pk_bf16_f32 v74, v78, v79
	v_cvt_pk_bf16_f32 v75, v80, v81
	v_cvt_pk_bf16_f32 v76, v86, v87
	v_cvt_pk_bf16_f32 v77, v84, v85
	global_store_dwordx4 v[88:89], v[74:77], off sc1
	v_cvt_pk_bf16_f32 v0, v78, v86
	v_cvt_pk_bf16_f32 v86, v79, v87
	v_cvt_pk_bf16_f32 v84, v80, v84
	v_cvt_pk_bf16_f32 v85, v81, v85
	s_nop 0
	v_cndmask_b32_e64 v78, v0, v84, s[46:47]
	ds_bpermute_b32 v81, v107, v78
	v_cndmask_b32_e64 v78, v86, v85, s[46:47]
	ds_bpermute_b32 v87, v107, v78
	v_lshl_add_u64 v[78:79], v[120:121], 0, v[82:83]
	s_waitcnt lgkmcnt(0)
	v_cndmask_b32_e64 v80, v81, v0, s[46:47]
	v_cndmask_b32_e64 v0, v74, v76, s[48:49]
	v_cndmask_b32_e64 v81, v84, v81, s[46:47]
	ds_bpermute_b32 v0, v169, v0
	global_store_dwordx2 v[78:79], v[80:81], off
	v_cndmask_b32_e64 v80, v75, v77, s[48:49]
	ds_bpermute_b32 v80, v169, v80
	v_add_co_u32_e32 v78, vcc, s33, v78
	v_cndmask_b32_e64 v84, v87, v86, s[46:47]
	v_cndmask_b32_e64 v85, v85, v87, s[46:47]
	v_addc_co_u32_e32 v79, vcc, 0, v79, vcc
	global_store_dwordx2 v[78:79], v[84:85], off
	s_waitcnt lgkmcnt(0)
	v_cndmask_b32_e64 v78, v0, v74, s[48:49]
	v_cndmask_b32_e64 v0, v76, v0, s[48:49]
	v_lshlrev_b32_e32 v76, 16, v0
	v_cndmask_b32_e64 v79, v80, v75, s[48:49]
	v_lshl_add_u64 v[74:75], v[130:131], 0, v[82:83]
	v_and_or_b32 v76, v78, s85, v76
	global_store_dword v[74:75], v76, off
	v_lshrrev_b32_e32 v76, 16, v78
	v_and_or_b32 v0, v0, s56, v76
	v_add_co_u32_e32 v76, vcc, s65, v74
	v_cndmask_b32_e64 v80, v77, v80, s[48:49]
	s_nop 0
	v_addc_co_u32_e32 v77, vcc, 0, v75, vcc
	global_store_dword v[76:77], v0, off
	v_lshlrev_b32_e32 v0, 16, v80
	v_add_co_u32_e32 v76, vcc, s25, v74
	v_and_or_b32 v0, v79, s85, v0
	s_nop 0
	v_addc_co_u32_e32 v77, vcc, 0, v75, vcc
	global_store_dword v[76:77], v0, off
	v_lshrrev_b32_e32 v0, 16, v79
	v_add_co_u32_e32 v74, vcc, s57, v74
	v_and_or_b32 v0, v80, s56, v0
	s_nop 0
	v_addc_co_u32_e32 v75, vcc, 0, v75, vcc
	global_store_dword v[74:75], v0, off
	v_mov_b32_e32 v75, s55
	v_or_b32_e32 v74, s54, v154
	v_lshlrev_b64 v[74:75], 1, v[74:75]
	v_pk_mul_f32 v[76:77], v[68:69], v[124:125]
	v_pk_mul_f32 v[78:79], v[66:67], v[122:123]
	v_lshl_add_u64 v[80:81], v[116:117], 0, v[74:75]
	v_cvt_pk_bf16_f32 v66, v70, v71
	v_cvt_pk_bf16_f32 v67, v72, v73
	v_cvt_pk_bf16_f32 v68, v78, v79
	v_cvt_pk_bf16_f32 v69, v76, v77
	global_store_dwordx4 v[80:81], v[66:69], off sc1
	v_cvt_pk_bf16_f32 v0, v70, v78
	v_cvt_pk_bf16_f32 v78, v71, v79
	v_cvt_pk_bf16_f32 v76, v72, v76
	v_cvt_pk_bf16_f32 v77, v73, v77
	s_nop 0
	v_cndmask_b32_e64 v70, v0, v76, s[46:47]
	ds_bpermute_b32 v73, v107, v70
	v_cndmask_b32_e64 v70, v78, v77, s[46:47]
	ds_bpermute_b32 v79, v107, v70
	v_lshl_add_u64 v[70:71], v[120:121], 0, v[74:75]
	s_waitcnt lgkmcnt(0)
	v_cndmask_b32_e64 v72, v73, v0, s[46:47]
	v_cndmask_b32_e64 v0, v66, v68, s[48:49]
	v_cndmask_b32_e64 v73, v76, v73, s[46:47]
	ds_bpermute_b32 v0, v169, v0
	global_store_dwordx2 v[70:71], v[72:73], off
	v_cndmask_b32_e64 v72, v67, v69, s[48:49]
	ds_bpermute_b32 v72, v169, v72
	v_add_co_u32_e32 v70, vcc, s33, v70
	v_cndmask_b32_e64 v76, v79, v78, s[46:47]
	v_cndmask_b32_e64 v77, v77, v79, s[46:47]
	v_addc_co_u32_e32 v71, vcc, 0, v71, vcc
	global_store_dwordx2 v[70:71], v[76:77], off
	s_waitcnt lgkmcnt(0)
	v_cndmask_b32_e64 v70, v0, v66, s[48:49]
	v_cndmask_b32_e64 v0, v68, v0, s[48:49]
	v_lshlrev_b32_e32 v68, 16, v0
	v_cndmask_b32_e64 v71, v72, v67, s[48:49]
	v_lshl_add_u64 v[66:67], v[130:131], 0, v[74:75]
	v_and_or_b32 v68, v70, s85, v68
	global_store_dword v[66:67], v68, off
	v_lshrrev_b32_e32 v68, 16, v70
	v_and_or_b32 v0, v0, s56, v68
	v_add_co_u32_e32 v68, vcc, 0x10000, v66
	v_cndmask_b32_e64 v72, v69, v72, s[48:49]
	s_nop 0
	v_addc_co_u32_e32 v69, vcc, 0, v67, vcc
	global_store_dword v[68:69], v0, off
	v_lshlrev_b32_e32 v0, 16, v72
	v_add_co_u32_e32 v68, vcc, 0x20000, v66
	v_and_or_b32 v0, v71, s85, v0
	s_nop 0
	v_addc_co_u32_e32 v69, vcc, 0, v67, vcc
	global_store_dword v[68:69], v0, off
	v_lshrrev_b32_e32 v0, 16, v71
	v_add_co_u32_e32 v66, vcc, 0x30000, v66
	v_and_or_b32 v0, v72, s56, v0
	s_nop 0
	v_addc_co_u32_e32 v67, vcc, 0, v67, vcc
	global_store_dword v[66:67], v0, off

; __device__ __forceinline__ unsigned cvt_pk_bf16(float lo, float hi) { unsigned r; asm volatile("v_cvt_pk_bf16_f32 %0, %1, %2" : "=v"(r) : "v"(lo), "v"(hi)); return r; }
; __device__ __forceinline__ f32x4 gelu4(f32x4 v) { f32x2 a = gelu_pk((f32x2){v[0], v[1]}), b = gelu_pk((f32x2){v[2], v[3]}); return (f32x4){a.x, a.y, b.x, b.y}; }
; __device__ __forceinline__ f32x2 gelu_pk(f32x2 v) {
;     const f32x2 av = __builtin_elementwise_abs(v), d = av * 0.2316418882f + 1.0f;
;     f32x2 t; t.x = __builtin_amdgcn_rcpf(d.x); t.y = __builtin_amdgcn_rcpf(d.y);
;     f32x2 q = t * 0.5307027145f + (-0.7265760135f); q = q * t + 0.7107068705f; q = q * t + (-0.142248368f); q = q * t + 0.127414796f; q = q * t;
;     const f32x2 s = (v * v) * (-0.72134752044f);
;     f32x2 e; e.x = __builtin_amdgcn_exp2f(s.x); e.y = __builtin_amdgcn_exp2f(s.y);
;     const f32x2 m = v * (q * e), r = v - m;
;     f32x2 o; o.x = v.x < 0.f ? m.x : r.x; o.y = v.y < 0.f ? m.y : r.y; return o;
; }
;     __device__ __forceinline__ void operator()(const f32x4 (&acc)[2][2][4][2], const Unit& u, int wr, int wc, int fr, int fq, int ui) const {
;     ...
;                 f32x4 sm0 = (f32x4){0.f, 0.f, 0.f, 0.f}, sm1 = sm0, sq0 = sm0, sq1 = sm0;
; #pragma unroll
;                 for (int ai = 0; ai < 2; ++ai)
; #pragma unroll
;                     for (int m = 0; m < 4; ++m) {
;                         const int ch = ch0 + ai * 128 + m * 16;
;                         const f32x4 v0 = pg8::gelu4(acc[ai][bj][m][0] * rs0), v1 = pg8::gelu4(acc[ai][bj][m][1] * rs1);
;                         sm0 = sm0 + v0; sm1 = sm1 + v1; sq0 = sq0 + v0 * v0; sq1 = sq1 + v1 * v1;
;                         u32x4 w; w.x = cvt_pk_bf16(v0[0], v0[1]); w.y = cvt_pk_bf16(v0[2], v0[3]); w.z = cvt_pk_bf16(v1[0], v1[1]); w.w = cvt_pk_bf16(v1[2], v1[3]);
;                         *(u32x4*)(Gt + ((size_t)(tok >> 3) * 512 + ch) * 8) = w;
;                     }
.LBB0_861:
	v_and_b32_e32 v79, 0x7fffffff, v63
	v_and_b32_e32 v78, 0x7fffffff, v62
	v_pk_fma_f32 v[78:79], v[78:79], s[86:87], 1.0 op_sel_hi:[1,0,0]
	v_mov_b64_e32 v[80:81], s[62:63]
	v_rcp_f32_e32 v78, v78
	v_rcp_f32_e32 v79, v79
	v_pk_mul_f32 v[86:87], v[62:63], v[62:63]
	v_ashrrev_i32_e32 v76, 3, v74
	v_pk_mul_f32 v[86:87], v[86:87], s[84:85] op_sel_hi:[1,0]
	v_pk_fma_f32 v[84:85], v[78:79], s[60:61], v[80:81] op_sel_hi:[1,0,0]
	v_exp_f32_e32 v86, v86
	v_pk_fma_f32 v[84:85], v[78:79], v[84:85], s[64:65] op_sel_hi:[1,1,0]
	v_exp_f32_e32 v87, v87
	v_pk_fma_f32 v[84:85], v[78:79], v[84:85], s[66:67] op_sel_hi:[1,1,0]
	v_ashrrev_i32_e32 v77, 31, v76
	v_pk_fma_f32 v[84:85], v[78:79], v[84:85], s[24:25] op_sel_hi:[1,1,0]
	v_cmp_gt_f32_e32 vcc, 0, v62
	v_pk_mul_f32 v[78:79], v[78:79], v[84:85]
	v_lshlrev_b64 v[82:83], 13, v[76:77]
	v_pk_mul_f32 v[78:79], v[86:87], v[78:79]
	v_pk_mul_f32 v[76:77], v[64:65], v[72:73]
	v_pk_mul_f32 v[86:87], v[62:63], v[78:79]
	v_pk_fma_f32 v[78:79], v[62:63], v[78:79], v[62:63] neg_lo:[1,0,0] neg_hi:[1,0,0]
	v_pk_mul_f32 v[84:85], v[76:77], v[76:77]
	v_cndmask_b32_e32 v88, v78, v86, vcc
	v_cmp_gt_f32_e32 vcc, 0, v63
	v_and_b32_e32 v78, 0x7fffffff, v76
	v_pk_mul_f32 v[84:85], v[84:85], s[84:85] op_sel_hi:[1,0]
	v_cndmask_b32_e32 v89, v79, v87, vcc
	v_and_b32_e32 v79, 0x7fffffff, v77
	v_pk_fma_f32 v[78:79], v[78:79], s[86:87], 1.0 op_sel_hi:[1,0,0]
	v_exp_f32_e32 v84, v84
	v_rcp_f32_e32 v78, v78
	v_rcp_f32_e32 v79, v79
	v_exp_f32_e32 v85, v85
	v_cmp_gt_f32_e32 vcc, 0, v76
	v_pk_mul_f32 v[90:91], v[58:59], v[58:59]
	v_pk_fma_f32 v[86:87], v[78:79], s[60:61], v[80:81] op_sel_hi:[1,0,0]
	v_pk_mul_f32 v[90:91], v[90:91], s[84:85] op_sel_hi:[1,0]
	v_pk_fma_f32 v[86:87], v[78:79], v[86:87], s[64:65] op_sel_hi:[1,1,0]
	v_exp_f32_e32 v90, v90
	v_pk_fma_f32 v[86:87], v[78:79], v[86:87], s[66:67] op_sel_hi:[1,1,0]
	v_exp_f32_e32 v91, v91
	v_pk_fma_f32 v[86:87], v[78:79], v[86:87], s[24:25] op_sel_hi:[1,1,0]
	v_lshl_add_u64 v[98:99], s[80:81], 0, v[82:83]
	v_pk_mul_f32 v[78:79], v[78:79], v[86:87]
	v_cvt_pk_bf16_f32 v100, v88, v89
	v_pk_mul_f32 v[82:83], v[56:57], v[72:73]
	v_pk_mul_f32 v[78:79], v[84:85], v[78:79]
	v_pk_mul_f32 v[108:109], v[50:51], v[50:51]
	v_pk_mul_f32 v[84:85], v[76:77], v[78:79]
	v_pk_fma_f32 v[78:79], v[76:77], v[78:79], v[76:77] neg_lo:[1,0,0] neg_hi:[1,0,0]
	v_pk_mul_f32 v[108:109], v[108:109], s[84:85] op_sel_hi:[1,0]
	v_cndmask_b32_e32 v76, v78, v84, vcc
	v_cmp_gt_f32_e32 vcc, 0, v77
	v_and_b32_e32 v84, 0x7fffffff, v58
	v_exp_f32_e32 v108, v108
	v_cndmask_b32_e32 v77, v79, v85, vcc
	v_and_b32_e32 v85, 0x7fffffff, v59
	v_pk_fma_f32 v[84:85], v[84:85], s[86:87], 1.0 op_sel_hi:[1,0,0]
	v_cmp_gt_f32_e32 vcc, 0, v58
	v_rcp_f32_e32 v84, v84
	v_rcp_f32_e32 v85, v85
	v_pk_mul_f32 v[78:79], v[60:61], v[68:69]
	v_cvt_pk_bf16_f32 v101, v76, v77
	v_exp_f32_e32 v109, v109
	v_pk_fma_f32 v[86:87], v[84:85], s[60:61], v[80:81] op_sel_hi:[1,0,0]
	v_pk_mul_f32 v[116:117], v[34:35], v[34:35]
	v_pk_fma_f32 v[86:87], v[84:85], v[86:87], s[64:65] op_sel_hi:[1,1,0]
	v_pk_mul_f32 v[116:117], v[116:117], s[84:85] op_sel_hi:[1,0]
	v_pk_fma_f32 v[86:87], v[84:85], v[86:87], s[66:67] op_sel_hi:[1,1,0]
	v_exp_f32_e32 v116, v116
	v_pk_fma_f32 v[86:87], v[84:85], v[86:87], s[24:25] op_sel_hi:[1,1,0]
	v_exp_f32_e32 v117, v117
	v_pk_mul_f32 v[84:85], v[84:85], v[86:87]
	v_pk_mul_f32 v[86:87], v[78:79], v[78:79]
	v_pk_mul_f32 v[84:85], v[90:91], v[84:85]
	v_pk_mul_f32 v[86:87], v[86:87], s[84:85] op_sel_hi:[1,0]
	v_pk_mul_f32 v[90:91], v[58:59], v[84:85]
	v_pk_fma_f32 v[84:85], v[58:59], v[84:85], v[58:59] neg_lo:[1,0,0] neg_hi:[1,0,0]
	v_exp_f32_e32 v86, v86
	v_cndmask_b32_e32 v90, v84, v90, vcc
	v_cmp_gt_f32_e32 vcc, 0, v59
	v_and_b32_e32 v84, 0x7fffffff, v78
	v_exp_f32_e32 v87, v87
	v_cndmask_b32_e32 v91, v85, v91, vcc
	v_and_b32_e32 v85, 0x7fffffff, v79
	v_pk_fma_f32 v[84:85], v[84:85], s[86:87], 1.0 op_sel_hi:[1,0,0]
	v_cmp_gt_f32_e32 vcc, 0, v78
	v_rcp_f32_e32 v84, v84
	v_rcp_f32_e32 v85, v85
	v_cvt_pk_bf16_f32 v102, v90, v91
	v_pk_add_f32 v[96:97], v[90:91], 0 op_sel_hi:[1,0]
	v_ashrrev_i32_e32 v107, 31, v106
	v_pk_fma_f32 v[92:93], v[84:85], s[60:61], v[80:81] op_sel_hi:[1,0,0]
	v_and_b32_e32 v0, 64, v238
	v_pk_fma_f32 v[92:93], v[84:85], v[92:93], s[64:65] op_sel_hi:[1,1,0]
	v_ashrrev_i32_e32 v75, 31, v74
	v_pk_fma_f32 v[92:93], v[84:85], v[92:93], s[66:67] op_sel_hi:[1,1,0]
	s_nop 0
	v_pk_fma_f32 v[92:93], v[84:85], v[92:93], s[24:25] op_sel_hi:[1,1,0]
	s_nop 0
	v_pk_mul_f32 v[84:85], v[84:85], v[92:93]
	v_pk_add_f32 v[92:93], v[88:89], 0 op_sel_hi:[1,0]
	v_pk_mul_f32 v[84:85], v[86:87], v[84:85]
	s_nop 0
	v_pk_mul_f32 v[86:87], v[78:79], v[84:85]
	v_pk_fma_f32 v[84:85], v[78:79], v[84:85], v[78:79] neg_lo:[1,0,0] neg_hi:[1,0,0]
	s_nop 0
	v_cndmask_b32_e32 v78, v84, v86, vcc
	v_cmp_gt_f32_e32 vcc, 0, v79
	v_and_b32_e32 v86, 0x7fffffff, v54
	s_nop 0
	v_cndmask_b32_e32 v79, v85, v87, vcc
	v_and_b32_e32 v87, 0x7fffffff, v55
	v_pk_fma_f32 v[86:87], v[86:87], s[86:87], 1.0 op_sel_hi:[1,0,0]
	v_cvt_pk_bf16_f32 v103, v78, v79
	v_lshl_add_u64 v[84:85], v[166:167], 4, v[98:99]
	v_rcp_f32_e32 v86, v86
	v_rcp_f32_e32 v87, v87
	global_store_dwordx4 v[84:85], v[100:103], off sc1
	v_cmp_gt_f32_e32 vcc, 0, v54
	s_nop 0
	v_pk_mul_f32 v[102:103], v[54:55], v[54:55]
	v_pk_fma_f32 v[100:101], v[86:87], s[60:61], v[80:81] op_sel_hi:[1,0,0]
	v_pk_mul_f32 v[102:103], v[102:103], s[84:85] op_sel_hi:[1,0]
	v_pk_fma_f32 v[100:101], v[86:87], v[100:101], s[64:65] op_sel_hi:[1,1,0]
	v_exp_f32_e32 v102, v102
	v_exp_f32_e32 v103, v103
	v_pk_fma_f32 v[100:101], v[86:87], v[100:101], s[66:67] op_sel_hi:[1,1,0]
	s_nop 0
; __device__ __forceinline__ unsigned cvt_pk_bf16(float lo, float hi) { unsigned r; asm volatile("v_cvt_pk_bf16_f32 %0, %1, %2" : "=v"(r) : "v"(lo), "v"(hi)); return r; }
; __device__ __forceinline__ f32x4 gelu4(f32x4 v) { f32x2 a = gelu_pk((f32x2){v[0], v[1]}), b = gelu_pk((f32x2){v[2], v[3]}); return (f32x4){a.x, a.y, b.x, b.y}; }
; __device__ __forceinline__ f32x2 gelu_pk(f32x2 v) {
;     const f32x2 av = __builtin_elementwise_abs(v), d = av * 0.2316418882f + 1.0f;
;     f32x2 t; t.x = __builtin_amdgcn_rcpf(d.x); t.y = __builtin_amdgcn_rcpf(d.y);
;     f32x2 q = t * 0.5307027145f + (-0.7265760135f); q = q * t + 0.7107068705f; q = q * t + (-0.142248368f); q = q * t + 0.127414796f; q = q * t;
;     const f32x2 s = (v * v) * (-0.72134752044f);
;     f32x2 e; e.x = __builtin_amdgcn_exp2f(s.x); e.y = __builtin_amdgcn_exp2f(s.y);
;     const f32x2 m = v * (q * e), r = v - m;
;     f32x2 o; o.x = v.x < 0.f ? m.x : r.x; o.y = v.y < 0.f ? m.y : r.y; return o;
; }
;     __device__ __forceinline__ void operator()(const f32x4 (&acc)[2][2][4][2], const Unit& u, int wr, int wc, int fr, int fq, int ui) const {
;     ...
;                 f32x4 sm0 = (f32x4){0.f, 0.f, 0.f, 0.f}, sm1 = sm0, sq0 = sm0, sq1 = sm0;
; #pragma unroll
;                 for (int ai = 0; ai < 2; ++ai)
; #pragma unroll
;                     for (int m = 0; m < 4; ++m) {
;                         const int ch = ch0 + ai * 128 + m * 16;
;                         const f32x4 v0 = pg8::gelu4(acc[ai][bj][m][0] * rs0), v1 = pg8::gelu4(acc[ai][bj][m][1] * rs1);
;                         sm0 = sm0 + v0; sm1 = sm1 + v1; sq0 = sq0 + v0 * v0; sq1 = sq1 + v1 * v1;
;                         u32x4 w; w.x = cvt_pk_bf16(v0[0], v0[1]); w.y = cvt_pk_bf16(v0[2], v0[3]); w.z = cvt_pk_bf16(v1[0], v1[1]); w.w = cvt_pk_bf16(v1[2], v1[3]);
;                         *(u32x4*)(Gt + ((size_t)(tok >> 3) * 512 + ch) * 8) = w;
;                     }
	v_pk_fma_f32 v[100:101], v[86:87], v[100:101], s[24:25] op_sel_hi:[1,1,0]
	s_nop 0
	v_pk_mul_f32 v[86:87], v[86:87], v[100:101]
	v_pk_mul_f32 v[100:101], v[82:83], v[82:83]
	v_pk_mul_f32 v[86:87], v[102:103], v[86:87]
	v_pk_mul_f32 v[100:101], v[100:101], s[84:85] op_sel_hi:[1,0]
	v_pk_mul_f32 v[102:103], v[54:55], v[86:87]
	v_pk_fma_f32 v[86:87], v[54:55], v[86:87], v[54:55] neg_lo:[1,0,0] neg_hi:[1,0,0]
	v_exp_f32_e32 v100, v100
	v_cndmask_b32_e32 v104, v86, v102, vcc
	v_cmp_gt_f32_e32 vcc, 0, v55
	v_and_b32_e32 v86, 0x7fffffff, v82
	v_exp_f32_e32 v101, v101
	v_cndmask_b32_e32 v105, v87, v103, vcc
	v_and_b32_e32 v87, 0x7fffffff, v83
	v_pk_fma_f32 v[86:87], v[86:87], s[86:87], 1.0 op_sel_hi:[1,0,0]
	v_cmp_gt_f32_e32 vcc, 0, v82
	v_rcp_f32_e32 v86, v86
	v_rcp_f32_e32 v87, v87
	v_pk_add_f32 v[92:93], v[104:105], v[92:93]
	v_pk_fma_f32 v[102:103], v[86:87], s[60:61], v[80:81] op_sel_hi:[1,0,0]
	s_nop 0
	v_pk_fma_f32 v[102:103], v[86:87], v[102:103], s[64:65] op_sel_hi:[1,1,0]
	s_nop 0
	v_pk_fma_f32 v[102:103], v[86:87], v[102:103], s[66:67] op_sel_hi:[1,1,0]
	s_nop 0
	v_pk_fma_f32 v[102:103], v[86:87], v[102:103], s[24:25] op_sel_hi:[1,1,0]
	s_nop 0
	v_pk_mul_f32 v[86:87], v[86:87], v[102:103]
	s_nop 0
	v_pk_mul_f32 v[86:87], v[100:101], v[86:87]
	s_nop 0
	v_pk_mul_f32 v[100:101], v[82:83], v[86:87]
	v_pk_fma_f32 v[86:87], v[82:83], v[86:87], v[82:83] neg_lo:[1,0,0] neg_hi:[1,0,0]
	s_nop 0
	v_cndmask_b32_e32 v82, v86, v100, vcc
	v_cmp_gt_f32_e32 vcc, 0, v83
	v_and_b32_e32 v100, 0x7fffffff, v50
	s_nop 0
	v_cndmask_b32_e32 v83, v87, v101, vcc
	v_and_b32_e32 v101, 0x7fffffff, v51
	v_pk_fma_f32 v[100:101], v[100:101], s[86:87], 1.0 op_sel_hi:[1,0,0]
	v_cmp_gt_f32_e32 vcc, 0, v50
	v_rcp_f32_e32 v100, v100
	v_rcp_f32_e32 v101, v101
	v_pk_mul_f32 v[86:87], v[52:53], v[68:69]
	v_pk_fma_f32 v[102:103], v[100:101], s[60:61], v[80:81] op_sel_hi:[1,0,0]
	s_nop 0
	v_pk_fma_f32 v[102:103], v[100:101], v[102:103], s[64:65] op_sel_hi:[1,1,0]
	s_nop 0
	v_pk_fma_f32 v[102:103], v[100:101], v[102:103], s[66:67] op_sel_hi:[1,1,0]
	s_nop 0
	v_pk_fma_f32 v[102:103], v[100:101], v[102:103], s[24:25] op_sel_hi:[1,1,0]
	s_nop 0
	v_pk_mul_f32 v[100:101], v[100:101], v[102:103]
	v_pk_mul_f32 v[102:103], v[86:87], v[86:87]
	v_pk_mul_f32 v[100:101], v[108:109], v[100:101]
	v_pk_mul_f32 v[102:103], v[102:103], s[84:85] op_sel_hi:[1,0]
	v_pk_mul_f32 v[108:109], v[50:51], v[100:101]
	v_pk_fma_f32 v[100:101], v[50:51], v[100:101], v[50:51] neg_lo:[1,0,0] neg_hi:[1,0,0]
	v_exp_f32_e32 v102, v102
	v_cndmask_b32_e32 v108, v100, v108, vcc
	v_cmp_gt_f32_e32 vcc, 0, v51
	v_and_b32_e32 v100, 0x7fffffff, v86
	v_exp_f32_e32 v103, v103
	v_cndmask_b32_e32 v109, v101, v109, vcc
	v_and_b32_e32 v101, 0x7fffffff, v87
	v_pk_fma_f32 v[100:101], v[100:101], s[86:87], 1.0 op_sel_hi:[1,0,0]
	v_cmp_gt_f32_e32 vcc, 0, v86
	v_rcp_f32_e32 v100, v100
	v_rcp_f32_e32 v101, v101
	v_pk_add_f32 v[96:97], v[108:109], v[96:97]
	v_pk_fma_f32 v[110:111], v[100:101], s[60:61], v[80:81] op_sel_hi:[1,0,0]
	s_nop 0
	v_pk_fma_f32 v[110:111], v[100:101], v[110:111], s[64:65] op_sel_hi:[1,1,0]
	s_nop 0
	v_pk_fma_f32 v[110:111], v[100:101], v[110:111], s[66:67] op_sel_hi:[1,1,0]
	s_nop 0
	v_pk_fma_f32 v[110:111], v[100:101], v[110:111], s[24:25] op_sel_hi:[1,1,0]
	s_nop 0
	v_pk_mul_f32 v[100:101], v[100:101], v[110:111]
	v_pk_mul_f32 v[110:111], v[42:43], v[42:43]
	v_pk_mul_f32 v[100:101], v[102:103], v[100:101]
	v_pk_mul_f32 v[110:111], v[110:111], s[84:85] op_sel_hi:[1,0]
	v_pk_mul_f32 v[102:103], v[86:87], v[100:101]
	v_pk_fma_f32 v[100:101], v[86:87], v[100:101], v[86:87] neg_lo:[1,0,0] neg_hi:[1,0,0]
	v_exp_f32_e32 v110, v110
	v_cndmask_b32_e32 v86, v100, v102, vcc
	v_cmp_gt_f32_e32 vcc, 0, v87
	v_exp_f32_e32 v111, v111
	s_nop 0
	v_cndmask_b32_e32 v87, v101, v103, vcc
	v_pk_mul_f32 v[100:101], v[104:105], v[104:105]
	v_cmp_gt_f32_e32 vcc, 0, v46
	v_pk_fma_f32 v[100:101], v[88:89], v[88:89], v[100:101]
	v_pk_mul_f32 v[88:89], v[108:109], v[108:109]
	s_nop 0
	v_pk_fma_f32 v[102:103], v[90:91], v[90:91], v[88:89]
	v_cvt_pk_bf16_f32 v88, v104, v105
	v_cvt_pk_bf16_f32 v89, v82, v83
	v_cvt_pk_bf16_f32 v90, v108, v109
	v_cvt_pk_bf16_f32 v91, v86, v87
	v_lshl_add_u64 v[104:105], v[164:165], 4, v[98:99]
	global_store_dwordx4 v[104:105], v[88:91], off sc1
	v_pk_mul_f32 v[108:109], v[46:47], v[46:47]
	s_nop 0
	v_and_b32_e32 v91, 0x7fffffff, v47
	v_and_b32_e32 v90, 0x7fffffff, v46
	v_pk_fma_f32 v[90:91], v[90:91], s[86:87], 1.0 op_sel_hi:[1,0,0]
	v_pk_mul_f32 v[108:109], v[108:109], s[84:85] op_sel_hi:[1,0]
	v_rcp_f32_e32 v90, v90
	v_rcp_f32_e32 v91, v91
	v_exp_f32_e32 v108, v108
	v_exp_f32_e32 v109, v109
	v_pk_mul_f32 v[88:89], v[48:49], v[72:73]
	v_pk_fma_f32 v[104:105], v[90:91], s[60:61], v[80:81] op_sel_hi:[1,0,0]
	s_nop 0
	v_pk_fma_f32 v[104:105], v[90:91], v[104:105], s[64:65] op_sel_hi:[1,1,0]
	s_nop 0
	v_pk_fma_f32 v[104:105], v[90:91], v[104:105], s[66:67] op_sel_hi:[1,1,0]
	s_nop 0
	v_pk_fma_f32 v[104:105], v[90:91], v[104:105], s[24:25] op_sel_hi:[1,1,0]
	s_nop 0
	v_pk_mul_f32 v[90:91], v[90:91], v[104:105]
	v_pk_mul_f32 v[104:105], v[88:89], v[88:89]
	v_pk_mul_f32 v[90:91], v[108:109], v[90:91]
	v_pk_mul_f32 v[104:105], v[104:105], s[84:85] op_sel_hi:[1,0]
	v_pk_mul_f32 v[108:109], v[46:47], v[90:91]
	v_pk_fma_f32 v[90:91], v[46:47], v[90:91], v[46:47] neg_lo:[1,0,0] neg_hi:[1,0,0]
	v_exp_f32_e32 v104, v104
	v_cndmask_b32_e32 v112, v90, v108, vcc
	v_cmp_gt_f32_e32 vcc, 0, v47
	v_and_b32_e32 v90, 0x7fffffff, v88
	v_exp_f32_e32 v105, v105
	v_cndmask_b32_e32 v113, v91, v109, vcc
	v_and_b32_e32 v91, 0x7fffffff, v89
	v_pk_fma_f32 v[90:91], v[90:91], s[86:87], 1.0 op_sel_hi:[1,0,0]
	v_cmp_gt_f32_e32 vcc, 0, v88
; __device__ __forceinline__ unsigned cvt_pk_bf16(float lo, float hi) { unsigned r; asm volatile("v_cvt_pk_bf16_f32 %0, %1, %2" : "=v"(r) : "v"(lo), "v"(hi)); return r; }
; __device__ __forceinline__ f32x4 gelu4(f32x4 v) { f32x2 a = gelu_pk((f32x2){v[0], v[1]}), b = gelu_pk((f32x2){v[2], v[3]}); return (f32x4){a.x, a.y, b.x, b.y}; }
; __device__ __forceinline__ f32x2 gelu_pk(f32x2 v) {
;     const f32x2 av = __builtin_elementwise_abs(v), d = av * 0.2316418882f + 1.0f;
;     f32x2 t; t.x = __builtin_amdgcn_rcpf(d.x); t.y = __builtin_amdgcn_rcpf(d.y);
;     f32x2 q = t * 0.5307027145f + (-0.7265760135f); q = q * t + 0.7107068705f; q = q * t + (-0.142248368f); q = q * t + 0.127414796f; q = q * t;
;     const f32x2 s = (v * v) * (-0.72134752044f);
;     f32x2 e; e.x = __builtin_amdgcn_exp2f(s.x); e.y = __builtin_amdgcn_exp2f(s.y);
;     const f32x2 m = v * (q * e), r = v - m;
;     f32x2 o; o.x = v.x < 0.f ? m.x : r.x; o.y = v.y < 0.f ? m.y : r.y; return o;
; }
;     __device__ __forceinline__ void operator()(const f32x4 (&acc)[2][2][4][2], const Unit& u, int wr, int wc, int fr, int fq, int ui) const {
;     ...
;                 f32x4 sm0 = (f32x4){0.f, 0.f, 0.f, 0.f}, sm1 = sm0, sq0 = sm0, sq1 = sm0;
; #pragma unroll
;                 for (int ai = 0; ai < 2; ++ai)
; #pragma unroll
;                     for (int m = 0; m < 4; ++m) {
;                         const int ch = ch0 + ai * 128 + m * 16;
;                         const f32x4 v0 = pg8::gelu4(acc[ai][bj][m][0] * rs0), v1 = pg8::gelu4(acc[ai][bj][m][1] * rs1);
;                         sm0 = sm0 + v0; sm1 = sm1 + v1; sq0 = sq0 + v0 * v0; sq1 = sq1 + v1 * v1;
;                         u32x4 w; w.x = cvt_pk_bf16(v0[0], v0[1]); w.y = cvt_pk_bf16(v0[2], v0[3]); w.z = cvt_pk_bf16(v1[0], v1[1]); w.w = cvt_pk_bf16(v1[2], v1[3]);
;                         *(u32x4*)(Gt + ((size_t)(tok >> 3) * 512 + ch) * 8) = w;
;                     }
	v_rcp_f32_e32 v90, v90
	v_rcp_f32_e32 v91, v91
	v_pk_fma_f32 v[100:101], v[112:113], v[112:113], v[100:101]
	v_pk_fma_f32 v[108:109], v[90:91], s[60:61], v[80:81] op_sel_hi:[1,0,0]
	s_nop 0
	v_pk_fma_f32 v[108:109], v[90:91], v[108:109], s[64:65] op_sel_hi:[1,1,0]
	s_nop 0
	v_pk_fma_f32 v[108:109], v[90:91], v[108:109], s[66:67] op_sel_hi:[1,1,0]
	s_nop 0
	v_pk_fma_f32 v[108:109], v[90:91], v[108:109], s[24:25] op_sel_hi:[1,1,0]
	s_nop 0
	v_pk_mul_f32 v[90:91], v[90:91], v[108:109]
	s_nop 0
	v_pk_mul_f32 v[90:91], v[104:105], v[90:91]
	s_nop 0
	v_pk_mul_f32 v[104:105], v[88:89], v[90:91]
	v_pk_fma_f32 v[90:91], v[88:89], v[90:91], v[88:89] neg_lo:[1,0,0] neg_hi:[1,0,0]
	s_nop 0
	v_cndmask_b32_e32 v88, v90, v104, vcc
	v_cmp_gt_f32_e32 vcc, 0, v89
	v_and_b32_e32 v104, 0x7fffffff, v42
	s_nop 0
	v_cndmask_b32_e32 v89, v91, v105, vcc
	v_and_b32_e32 v105, 0x7fffffff, v43
	v_pk_fma_f32 v[104:105], v[104:105], s[86:87], 1.0 op_sel_hi:[1,0,0]
	v_cmp_gt_f32_e32 vcc, 0, v42
	v_rcp_f32_e32 v104, v104
	v_rcp_f32_e32 v105, v105
	v_pk_mul_f32 v[90:91], v[44:45], v[68:69]
	v_pk_fma_f32 v[108:109], v[104:105], s[60:61], v[80:81] op_sel_hi:[1,0,0]
	s_nop 0
	v_pk_fma_f32 v[108:109], v[104:105], v[108:109], s[64:65] op_sel_hi:[1,1,0]
	s_nop 0
	v_pk_fma_f32 v[108:109], v[104:105], v[108:109], s[66:67] op_sel_hi:[1,1,0]
	s_nop 0
	v_pk_fma_f32 v[108:109], v[104:105], v[108:109], s[24:25] op_sel_hi:[1,1,0]
	s_nop 0
	v_pk_mul_f32 v[104:105], v[104:105], v[108:109]
	v_pk_mul_f32 v[108:109], v[90:91], v[90:91]
	v_pk_mul_f32 v[104:105], v[110:111], v[104:105]
	v_pk_mul_f32 v[108:109], v[108:109], s[84:85] op_sel_hi:[1,0]
	v_pk_mul_f32 v[110:111], v[42:43], v[104:105]
	v_pk_fma_f32 v[104:105], v[42:43], v[104:105], v[42:43] neg_lo:[1,0,0] neg_hi:[1,0,0]
	v_exp_f32_e32 v108, v108
	v_cndmask_b32_e32 v114, v104, v110, vcc
	v_cmp_gt_f32_e32 vcc, 0, v43
	v_and_b32_e32 v104, 0x7fffffff, v90
	v_exp_f32_e32 v109, v109
	v_cndmask_b32_e32 v115, v105, v111, vcc
	v_and_b32_e32 v105, 0x7fffffff, v91
	v_pk_fma_f32 v[104:105], v[104:105], s[86:87], 1.0 op_sel_hi:[1,0,0]
	v_cmp_gt_f32_e32 vcc, 0, v90
	v_rcp_f32_e32 v104, v104
	v_rcp_f32_e32 v105, v105
	s_nop 0
	v_pk_fma_f32 v[110:111], v[104:105], s[60:61], v[80:81] op_sel_hi:[1,0,0]
	s_nop 0
	v_pk_fma_f32 v[110:111], v[104:105], v[110:111], s[64:65] op_sel_hi:[1,1,0]
	s_nop 0
	v_pk_fma_f32 v[110:111], v[104:105], v[110:111], s[66:67] op_sel_hi:[1,1,0]
	s_nop 0
	v_pk_fma_f32 v[110:111], v[104:105], v[110:111], s[24:25] op_sel_hi:[1,1,0]
	s_nop 0
	v_pk_mul_f32 v[104:105], v[104:105], v[110:111]
	v_pk_fma_f32 v[110:111], v[114:115], v[114:115], v[102:103]
	v_pk_mul_f32 v[104:105], v[108:109], v[104:105]
	s_nop 0
	v_pk_mul_f32 v[108:109], v[90:91], v[104:105]
	v_pk_fma_f32 v[104:105], v[90:91], v[104:105], v[90:91] neg_lo:[1,0,0] neg_hi:[1,0,0]
	s_nop 0
	v_cndmask_b32_e32 v90, v104, v108, vcc
	v_cmp_gt_f32_e32 vcc, 0, v91
	s_nop 1
	v_cndmask_b32_e32 v91, v105, v109, vcc
	v_pk_add_f32 v[108:109], v[114:115], v[96:97]
	v_and_b32_e32 v97, 0x7fffffff, v39
	v_and_b32_e32 v96, 0x7fffffff, v38
	v_pk_fma_f32 v[96:97], v[96:97], s[86:87], 1.0 op_sel_hi:[1,0,0]
	v_pk_add_f32 v[104:105], v[112:113], v[92:93]
	v_rcp_f32_e32 v96, v96
	v_rcp_f32_e32 v97, v97
	v_cvt_pk_bf16_f32 v112, v112, v113
	v_cvt_pk_bf16_f32 v113, v88, v89
	v_lshl_add_u64 v[92:93], v[162:163], 4, v[98:99]
	v_cvt_pk_bf16_f32 v114, v114, v115
	v_cvt_pk_bf16_f32 v115, v90, v91
	global_store_dwordx4 v[92:93], v[112:115], off sc1
	v_pk_fma_f32 v[102:103], v[96:97], s[60:61], v[80:81] op_sel_hi:[1,0,0]
	v_cmp_gt_f32_e32 vcc, 0, v38
	v_pk_mul_f32 v[112:113], v[38:39], v[38:39]
	v_pk_fma_f32 v[102:103], v[96:97], v[102:103], s[64:65] op_sel_hi:[1,1,0]
	v_pk_mul_f32 v[112:113], v[112:113], s[84:85] op_sel_hi:[1,0]
	v_pk_fma_f32 v[102:103], v[96:97], v[102:103], s[66:67] op_sel_hi:[1,1,0]
	v_exp_f32_e32 v112, v112
	v_exp_f32_e32 v113, v113
	v_pk_fma_f32 v[102:103], v[96:97], v[102:103], s[24:25] op_sel_hi:[1,1,0]
	v_pk_mul_f32 v[92:93], v[40:41], v[72:73]
	v_pk_mul_f32 v[96:97], v[96:97], v[102:103]
	v_pk_mul_f32 v[102:103], v[92:93], v[92:93]
	v_pk_mul_f32 v[96:97], v[112:113], v[96:97]
	v_pk_mul_f32 v[102:103], v[102:103], s[84:85] op_sel_hi:[1,0]
	v_pk_mul_f32 v[112:113], v[38:39], v[96:97]
	v_pk_fma_f32 v[96:97], v[38:39], v[96:97], v[38:39] neg_lo:[1,0,0] neg_hi:[1,0,0]
	v_exp_f32_e32 v102, v102
	v_cndmask_b32_e32 v112, v96, v112, vcc
	v_cmp_gt_f32_e32 vcc, 0, v39
	v_and_b32_e32 v96, 0x7fffffff, v92
	v_exp_f32_e32 v103, v103
	v_cndmask_b32_e32 v113, v97, v113, vcc
	v_and_b32_e32 v97, 0x7fffffff, v93
	v_pk_fma_f32 v[96:97], v[96:97], s[86:87], 1.0 op_sel_hi:[1,0,0]
	v_cmp_gt_f32_e32 vcc, 0, v92
	v_rcp_f32_e32 v96, v96
	v_rcp_f32_e32 v97, v97
	v_lshl_add_u64 v[98:99], v[106:107], 4, v[98:99]
	v_pk_fma_f32 v[114:115], v[96:97], s[60:61], v[80:81] op_sel_hi:[1,0,0]
	s_nop 0
	v_pk_fma_f32 v[114:115], v[96:97], v[114:115], s[64:65] op_sel_hi:[1,1,0]
	s_nop 0
	v_pk_fma_f32 v[114:115], v[96:97], v[114:115], s[66:67] op_sel_hi:[1,1,0]
	s_nop 0
	v_pk_fma_f32 v[114:115], v[96:97], v[114:115], s[24:25] op_sel_hi:[1,1,0]
	s_nop 0
	v_pk_mul_f32 v[96:97], v[96:97], v[114:115]
	s_nop 0
	v_pk_mul_f32 v[96:97], v[102:103], v[96:97]
	s_nop 0
	v_pk_mul_f32 v[102:103], v[92:93], v[96:97]
	v_pk_fma_f32 v[96:97], v[92:93], v[96:97], v[92:93] neg_lo:[1,0,0] neg_hi:[1,0,0]
	s_nop 0
	v_cndmask_b32_e32 v92, v96, v102, vcc
	v_cmp_gt_f32_e32 vcc, 0, v93
	v_and_b32_e32 v102, 0x7fffffff, v34
	s_nop 0
	v_cndmask_b32_e32 v93, v97, v103, vcc
	v_and_b32_e32 v103, 0x7fffffff, v35
	v_pk_fma_f32 v[102:103], v[102:103], s[86:87], 1.0 op_sel_hi:[1,0,0]
	v_cmp_gt_f32_e32 vcc, 0, v34
	v_rcp_f32_e32 v102, v102
; __device__ __forceinline__ unsigned cvt_pk_bf16(float lo, float hi) { unsigned r; asm volatile("v_cvt_pk_bf16_f32 %0, %1, %2" : "=v"(r) : "v"(lo), "v"(hi)); return r; }
; __device__ __forceinline__ f32x4 gelu4(f32x4 v) { f32x2 a = gelu_pk((f32x2){v[0], v[1]}), b = gelu_pk((f32x2){v[2], v[3]}); return (f32x4){a.x, a.y, b.x, b.y}; }
; __device__ __forceinline__ f32x2 gelu_pk(f32x2 v) {
;     const f32x2 av = __builtin_elementwise_abs(v), d = av * 0.2316418882f + 1.0f;
;     f32x2 t; t.x = __builtin_amdgcn_rcpf(d.x); t.y = __builtin_amdgcn_rcpf(d.y);
;     f32x2 q = t * 0.5307027145f + (-0.7265760135f); q = q * t + 0.7107068705f; q = q * t + (-0.142248368f); q = q * t + 0.127414796f; q = q * t;
;     const f32x2 s = (v * v) * (-0.72134752044f);
;     f32x2 e; e.x = __builtin_amdgcn_exp2f(s.x); e.y = __builtin_amdgcn_exp2f(s.y);
;     const f32x2 m = v * (q * e), r = v - m;
;     f32x2 o; o.x = v.x < 0.f ? m.x : r.x; o.y = v.y < 0.f ? m.y : r.y; return o;
; }
;     __device__ __forceinline__ void operator()(const f32x4 (&acc)[2][2][4][2], const Unit& u, int wr, int wc, int fr, int fq, int ui) const {
;     ...
;                 f32x4 sm0 = (f32x4){0.f, 0.f, 0.f, 0.f}, sm1 = sm0, sq0 = sm0, sq1 = sm0;
; #pragma unroll
;                 for (int ai = 0; ai < 2; ++ai)
; #pragma unroll
;                     for (int m = 0; m < 4; ++m) {
;                         const int ch = ch0 + ai * 128 + m * 16;
;                         const f32x4 v0 = pg8::gelu4(acc[ai][bj][m][0] * rs0), v1 = pg8::gelu4(acc[ai][bj][m][1] * rs1);
;                         sm0 = sm0 + v0; sm1 = sm1 + v1; sq0 = sq0 + v0 * v0; sq1 = sq1 + v1 * v1;
;                         u32x4 w; w.x = cvt_pk_bf16(v0[0], v0[1]); w.y = cvt_pk_bf16(v0[2], v0[3]); w.z = cvt_pk_bf16(v1[0], v1[1]); w.w = cvt_pk_bf16(v1[2], v1[3]);
;                         *(u32x4*)(Gt + ((size_t)(tok >> 3) * 512 + ch) * 8) = w;
;                     }
	v_rcp_f32_e32 v103, v103
	v_pk_mul_f32 v[96:97], v[36:37], v[68:69]
	v_pk_fma_f32 v[114:115], v[102:103], s[60:61], v[80:81] op_sel_hi:[1,0,0]
	s_nop 0
	v_pk_fma_f32 v[114:115], v[102:103], v[114:115], s[64:65] op_sel_hi:[1,1,0]
	s_nop 0
	v_pk_fma_f32 v[114:115], v[102:103], v[114:115], s[66:67] op_sel_hi:[1,1,0]
	s_nop 0
	v_pk_fma_f32 v[114:115], v[102:103], v[114:115], s[24:25] op_sel_hi:[1,1,0]
	s_nop 0
	v_pk_mul_f32 v[102:103], v[102:103], v[114:115]
	v_pk_mul_f32 v[114:115], v[96:97], v[96:97]
	v_pk_mul_f32 v[102:103], v[116:117], v[102:103]
	v_pk_mul_f32 v[114:115], v[114:115], s[84:85] op_sel_hi:[1,0]
	v_pk_mul_f32 v[116:117], v[34:35], v[102:103]
	v_pk_fma_f32 v[102:103], v[34:35], v[102:103], v[34:35] neg_lo:[1,0,0] neg_hi:[1,0,0]
	v_exp_f32_e32 v114, v114
	v_cndmask_b32_e32 v116, v102, v116, vcc
	v_cmp_gt_f32_e32 vcc, 0, v35
	v_and_b32_e32 v102, 0x7fffffff, v96
	v_exp_f32_e32 v115, v115
	v_cndmask_b32_e32 v117, v103, v117, vcc
	v_and_b32_e32 v103, 0x7fffffff, v97
	v_pk_fma_f32 v[102:103], v[102:103], s[86:87], 1.0 op_sel_hi:[1,0,0]
	v_cmp_gt_f32_e32 vcc, 0, v96
	v_rcp_f32_e32 v102, v102
	v_rcp_f32_e32 v103, v103
	v_pk_fma_f32 v[110:111], v[116:117], v[116:117], v[110:111]
	v_pk_fma_f32 v[118:119], v[102:103], s[60:61], v[80:81] op_sel_hi:[1,0,0]
	s_nop 0
	v_pk_fma_f32 v[118:119], v[102:103], v[118:119], s[64:65] op_sel_hi:[1,1,0]
	s_nop 0
	v_pk_fma_f32 v[118:119], v[102:103], v[118:119], s[66:67] op_sel_hi:[1,1,0]
	s_nop 0
	v_pk_fma_f32 v[118:119], v[102:103], v[118:119], s[24:25] op_sel_hi:[1,1,0]
	s_nop 0
	v_pk_mul_f32 v[102:103], v[102:103], v[118:119]
	s_nop 0
	v_pk_mul_f32 v[102:103], v[114:115], v[102:103]
	s_nop 0
	v_pk_mul_f32 v[114:115], v[96:97], v[102:103]
	v_pk_fma_f32 v[102:103], v[96:97], v[102:103], v[96:97] neg_lo:[1,0,0] neg_hi:[1,0,0]
	s_nop 0
	v_cndmask_b32_e32 v96, v102, v114, vcc
	v_cmp_gt_f32_e32 vcc, 0, v97
	s_nop 1
	v_cndmask_b32_e32 v97, v103, v115, vcc
	v_pk_add_f32 v[102:103], v[112:113], v[104:105]
	v_pk_add_f32 v[104:105], v[116:117], v[108:109]
	v_pk_fma_f32 v[108:109], v[112:113], v[112:113], v[100:101]
	v_and_b32_e32 v101, 0x7fffffff, v31
	v_and_b32_e32 v100, 0x7fffffff, v30
	v_pk_fma_f32 v[100:101], v[100:101], s[86:87], 1.0 op_sel_hi:[1,0,0]
	v_cvt_pk_bf16_f32 v112, v112, v113
	v_cvt_pk_bf16_f32 v113, v92, v93
	v_cvt_pk_bf16_f32 v114, v116, v117
	v_cvt_pk_bf16_f32 v115, v96, v97
	global_store_dwordx4 v[98:99], v[112:115], off sc1
	v_rcp_f32_e32 v100, v100
	v_rcp_f32_e32 v101, v101
	v_pk_mul_f32 v[112:113], v[30:31], v[30:31]
	v_cmp_gt_f32_e32 vcc, 0, v30
	v_pk_mul_f32 v[112:113], v[112:113], s[84:85] op_sel_hi:[1,0]
	v_pk_fma_f32 v[106:107], v[100:101], s[60:61], v[80:81] op_sel_hi:[1,0,0]
	v_exp_f32_e32 v112, v112
	v_pk_fma_f32 v[106:107], v[100:101], v[106:107], s[64:65] op_sel_hi:[1,1,0]
	v_exp_f32_e32 v113, v113
	v_pk_fma_f32 v[106:107], v[100:101], v[106:107], s[66:67] op_sel_hi:[1,1,0]
	v_pk_mul_f32 v[98:99], v[32:33], v[72:73]
	v_pk_fma_f32 v[106:107], v[100:101], v[106:107], s[24:25] op_sel_hi:[1,1,0]
	s_nop 0
	v_pk_mul_f32 v[100:101], v[100:101], v[106:107]
	v_pk_mul_f32 v[106:107], v[98:99], v[98:99]
	v_pk_mul_f32 v[100:101], v[112:113], v[100:101]
	v_pk_mul_f32 v[106:107], v[106:107], s[84:85] op_sel_hi:[1,0]
	v_pk_mul_f32 v[112:113], v[30:31], v[100:101]
	v_pk_fma_f32 v[100:101], v[30:31], v[100:101], v[30:31] neg_lo:[1,0,0] neg_hi:[1,0,0]
	v_exp_f32_e32 v106, v106
	v_cndmask_b32_e32 v114, v100, v112, vcc
	v_cmp_gt_f32_e32 vcc, 0, v31
	v_and_b32_e32 v100, 0x7fffffff, v98
	v_exp_f32_e32 v107, v107
	v_cndmask_b32_e32 v115, v101, v113, vcc
	v_and_b32_e32 v101, 0x7fffffff, v99
	v_pk_fma_f32 v[100:101], v[100:101], s[86:87], 1.0 op_sel_hi:[1,0,0]
	v_cmp_gt_f32_e32 vcc, 0, v98
	v_rcp_f32_e32 v100, v100
	v_rcp_f32_e32 v101, v101
	v_pk_fma_f32 v[108:109], v[114:115], v[114:115], v[108:109]
	v_pk_fma_f32 v[112:113], v[100:101], s[60:61], v[80:81] op_sel_hi:[1,0,0]
	s_nop 0
	v_pk_fma_f32 v[112:113], v[100:101], v[112:113], s[64:65] op_sel_hi:[1,1,0]
	s_nop 0
	v_pk_fma_f32 v[112:113], v[100:101], v[112:113], s[66:67] op_sel_hi:[1,1,0]
	s_nop 0
	v_pk_fma_f32 v[112:113], v[100:101], v[112:113], s[24:25] op_sel_hi:[1,1,0]
	s_nop 0
	v_pk_mul_f32 v[100:101], v[100:101], v[112:113]
	s_nop 0
	v_pk_mul_f32 v[100:101], v[106:107], v[100:101]
	s_nop 0
	v_pk_mul_f32 v[106:107], v[98:99], v[100:101]
	v_pk_fma_f32 v[100:101], v[98:99], v[100:101], v[98:99] neg_lo:[1,0,0] neg_hi:[1,0,0]
	s_nop 0
	v_cndmask_b32_e32 v98, v100, v106, vcc
	v_cmp_gt_f32_e32 vcc, 0, v99
	s_nop 1
	v_cndmask_b32_e32 v99, v101, v107, vcc
	v_pk_mul_f32 v[106:107], v[26:27], v[66:67]
	v_pk_mul_f32 v[100:101], v[28:29], v[68:69]
	v_and_b32_e32 v113, 0x7fffffff, v107
	v_and_b32_e32 v112, 0x7fffffff, v106
	v_pk_fma_f32 v[112:113], v[112:113], s[86:87], 1.0 op_sel_hi:[1,0,0]
	v_pk_mul_f32 v[118:119], v[106:107], v[106:107]
	v_rcp_f32_e32 v112, v112
	v_rcp_f32_e32 v113, v113
	v_pk_mul_f32 v[118:119], v[118:119], s[84:85] op_sel_hi:[1,0]
	v_cmp_gt_f32_e32 vcc, 0, v106
	v_exp_f32_e32 v118, v118
	v_pk_fma_f32 v[116:117], v[112:113], s[60:61], v[80:81] op_sel_hi:[1,0,0]
	v_exp_f32_e32 v119, v119
	v_pk_fma_f32 v[116:117], v[112:113], v[116:117], s[64:65] op_sel_hi:[1,1,0]
	s_nop 0
	v_pk_fma_f32 v[116:117], v[112:113], v[116:117], s[66:67] op_sel_hi:[1,1,0]
	s_nop 0
	v_pk_fma_f32 v[116:117], v[112:113], v[116:117], s[24:25] op_sel_hi:[1,1,0]
	s_nop 0
	v_pk_mul_f32 v[112:113], v[112:113], v[116:117]
	v_pk_mul_f32 v[116:117], v[100:101], v[100:101]
	v_pk_mul_f32 v[112:113], v[118:119], v[112:113]
	s_nop 0
	v_pk_mul_f32 v[118:119], v[106:107], v[112:113]
	v_pk_fma_f32 v[112:113], v[106:107], v[112:113], v[106:107] neg_lo:[1,0,0] neg_hi:[1,0,0]
; __device__ __forceinline__ unsigned cvt_pk_bf16(float lo, float hi) { unsigned r; asm volatile("v_cvt_pk_bf16_f32 %0, %1, %2" : "=v"(r) : "v"(lo), "v"(hi)); return r; }
; __device__ __forceinline__ f32x4 gelu4(f32x4 v) { f32x2 a = gelu_pk((f32x2){v[0], v[1]}), b = gelu_pk((f32x2){v[2], v[3]}); return (f32x4){a.x, a.y, b.x, b.y}; }
; __device__ __forceinline__ f32x2 gelu_pk(f32x2 v) {
;     const f32x2 av = __builtin_elementwise_abs(v), d = av * 0.2316418882f + 1.0f;
;     f32x2 t; t.x = __builtin_amdgcn_rcpf(d.x); t.y = __builtin_amdgcn_rcpf(d.y);
;     f32x2 q = t * 0.5307027145f + (-0.7265760135f); q = q * t + 0.7107068705f; q = q * t + (-0.142248368f); q = q * t + 0.127414796f; q = q * t;
;     const f32x2 s = (v * v) * (-0.72134752044f);
;     f32x2 e; e.x = __builtin_amdgcn_exp2f(s.x); e.y = __builtin_amdgcn_exp2f(s.y);
;     const f32x2 m = v * (q * e), r = v - m;
;     f32x2 o; o.x = v.x < 0.f ? m.x : r.x; o.y = v.y < 0.f ? m.y : r.y; return o;
; }
;     __device__ __forceinline__ void operator()(const f32x4 (&acc)[2][2][4][2], const Unit& u, int wr, int wc, int fr, int fq, int ui) const {
;     ...
;                 f32x4 sm0 = (f32x4){0.f, 0.f, 0.f, 0.f}, sm1 = sm0, sq0 = sm0, sq1 = sm0;
; #pragma unroll
;                 for (int ai = 0; ai < 2; ++ai)
; #pragma unroll
;                     for (int m = 0; m < 4; ++m) {
;                         const int ch = ch0 + ai * 128 + m * 16;
;                         const f32x4 v0 = pg8::gelu4(acc[ai][bj][m][0] * rs0), v1 = pg8::gelu4(acc[ai][bj][m][1] * rs1);
;                         sm0 = sm0 + v0; sm1 = sm1 + v1; sq0 = sq0 + v0 * v0; sq1 = sq1 + v1 * v1;
;                         u32x4 w; w.x = cvt_pk_bf16(v0[0], v0[1]); w.y = cvt_pk_bf16(v0[2], v0[3]); w.z = cvt_pk_bf16(v1[0], v1[1]); w.w = cvt_pk_bf16(v1[2], v1[3]);
;                         *(u32x4*)(Gt + ((size_t)(tok >> 3) * 512 + ch) * 8) = w;
;                     }
	v_and_b32_e32 v106, 0x7fffffff, v100
	v_cndmask_b32_e32 v118, v112, v118, vcc
	v_cmp_gt_f32_e32 vcc, 0, v107
	v_and_b32_e32 v107, 0x7fffffff, v101
	v_pk_fma_f32 v[106:107], v[106:107], s[86:87], 1.0 op_sel_hi:[1,0,0]
	v_cndmask_b32_e32 v119, v113, v119, vcc
	v_rcp_f32_e32 v106, v106
	v_rcp_f32_e32 v107, v107
	v_cmp_gt_f32_e32 vcc, 0, v100
	v_pk_fma_f32 v[110:111], v[118:119], v[118:119], v[110:111]
	v_pk_fma_f32 v[112:113], v[106:107], s[60:61], v[80:81] op_sel_hi:[1,0,0]
	s_nop 0
	v_pk_fma_f32 v[112:113], v[106:107], v[112:113], s[64:65] op_sel_hi:[1,1,0]
	s_nop 0
	v_pk_fma_f32 v[112:113], v[106:107], v[112:113], s[66:67] op_sel_hi:[1,1,0]
	s_nop 0
	v_pk_fma_f32 v[112:113], v[106:107], v[112:113], s[24:25] op_sel_hi:[1,1,0]
	s_nop 0
	v_pk_mul_f32 v[106:107], v[106:107], v[112:113]
	v_pk_mul_f32 v[112:113], v[116:117], s[84:85] op_sel_hi:[1,0]
	s_nop 0
	v_exp_f32_e32 v112, v112
	v_exp_f32_e32 v113, v113
	s_nop 0
	v_pk_mul_f32 v[106:107], v[112:113], v[106:107]
	s_nop 0
	v_pk_mul_f32 v[112:113], v[100:101], v[106:107]
	v_pk_fma_f32 v[106:107], v[100:101], v[106:107], v[100:101] neg_lo:[1,0,0] neg_hi:[1,0,0]
	s_nop 0
	v_cndmask_b32_e32 v100, v106, v112, vcc
	v_cmp_gt_f32_e32 vcc, 0, v101
	s_nop 1
	v_cndmask_b32_e32 v101, v107, v113, vcc
	v_pk_add_f32 v[106:107], v[114:115], v[102:103]
	v_pk_add_f32 v[112:113], v[118:119], v[104:105]
	v_cvt_pk_bf16_f32 v102, v114, v115
	v_cvt_pk_bf16_f32 v103, v98, v99
	v_cvt_pk_bf16_f32 v104, v118, v119
	v_cvt_pk_bf16_f32 v105, v100, v101
	global_store_dwordx4 v[84:85], v[102:105], off offset:2048 sc1
	s_nop 1
	v_pk_mul_f32 v[104:105], v[22:23], v[70:71]
	v_pk_mul_f32 v[102:103], v[24:25], v[72:73]
	v_and_b32_e32 v115, 0x7fffffff, v105
	v_and_b32_e32 v114, 0x7fffffff, v104
	v_pk_fma_f32 v[114:115], v[114:115], s[86:87], 1.0 op_sel_hi:[1,0,0]
	v_pk_mul_f32 v[118:119], v[104:105], v[104:105]
	v_rcp_f32_e32 v114, v114
	v_rcp_f32_e32 v115, v115
	v_pk_mul_f32 v[118:119], v[118:119], s[84:85] op_sel_hi:[1,0]
	v_cmp_gt_f32_e32 vcc, 0, v104
	v_exp_f32_e32 v118, v118
	v_pk_fma_f32 v[116:117], v[114:115], s[60:61], v[80:81] op_sel_hi:[1,0,0]
	v_exp_f32_e32 v119, v119
	v_pk_fma_f32 v[116:117], v[114:115], v[116:117], s[64:65] op_sel_hi:[1,1,0]
	s_nop 0
	v_pk_fma_f32 v[116:117], v[114:115], v[116:117], s[66:67] op_sel_hi:[1,1,0]
	s_nop 0
	v_pk_fma_f32 v[116:117], v[114:115], v[116:117], s[24:25] op_sel_hi:[1,1,0]
	s_nop 0
	v_pk_mul_f32 v[114:115], v[114:115], v[116:117]
	v_pk_mul_f32 v[116:117], v[102:103], v[102:103]
	v_pk_mul_f32 v[114:115], v[118:119], v[114:115]
	s_nop 0
	v_pk_mul_f32 v[118:119], v[104:105], v[114:115]
	v_pk_fma_f32 v[114:115], v[104:105], v[114:115], v[104:105] neg_lo:[1,0,0] neg_hi:[1,0,0]
	v_and_b32_e32 v104, 0x7fffffff, v102
	v_cndmask_b32_e32 v118, v114, v118, vcc
	v_cmp_gt_f32_e32 vcc, 0, v105
	v_and_b32_e32 v105, 0x7fffffff, v103
	v_pk_fma_f32 v[104:105], v[104:105], s[86:87], 1.0 op_sel_hi:[1,0,0]
	v_cndmask_b32_e32 v119, v115, v119, vcc
	v_rcp_f32_e32 v104, v104
	v_rcp_f32_e32 v105, v105
	v_cmp_gt_f32_e32 vcc, 0, v102
	v_pk_fma_f32 v[114:115], v[104:105], s[60:61], v[80:81] op_sel_hi:[1,0,0]
	s_nop 0
	v_pk_fma_f32 v[114:115], v[104:105], v[114:115], s[64:65] op_sel_hi:[1,1,0]
	s_nop 0
	v_pk_fma_f32 v[114:115], v[104:105], v[114:115], s[66:67] op_sel_hi:[1,1,0]
	s_nop 0
	v_pk_fma_f32 v[114:115], v[104:105], v[114:115], s[24:25] op_sel_hi:[1,1,0]
	s_nop 0
	v_pk_mul_f32 v[104:105], v[104:105], v[114:115]
	v_pk_mul_f32 v[114:115], v[116:117], s[84:85] op_sel_hi:[1,0]
	s_nop 0
	v_exp_f32_e32 v114, v114
	v_exp_f32_e32 v115, v115
	s_nop 0
	v_pk_mul_f32 v[104:105], v[114:115], v[104:105]
	s_nop 0
	v_pk_mul_f32 v[114:115], v[102:103], v[104:105]
	v_pk_fma_f32 v[104:105], v[102:103], v[104:105], v[102:103] neg_lo:[1,0,0] neg_hi:[1,0,0]
	s_nop 0
	v_cndmask_b32_e32 v102, v104, v114, vcc
	v_cmp_gt_f32_e32 vcc, 0, v103
	s_nop 1
	v_cndmask_b32_e32 v103, v105, v115, vcc
	v_pk_mul_f32 v[114:115], v[18:19], v[66:67]
	v_pk_mul_f32 v[104:105], v[20:21], v[68:69]
	v_and_b32_e32 v117, 0x7fffffff, v115
	v_and_b32_e32 v116, 0x7fffffff, v114
	v_pk_fma_f32 v[116:117], v[116:117], s[86:87], 1.0 op_sel_hi:[1,0,0]
	v_pk_mul_f32 v[122:123], v[114:115], v[114:115]
	v_rcp_f32_e32 v116, v116
	v_rcp_f32_e32 v117, v117
	v_pk_mul_f32 v[122:123], v[122:123], s[84:85] op_sel_hi:[1,0]
	v_cmp_gt_f32_e32 vcc, 0, v114
	v_exp_f32_e32 v122, v122
	v_pk_fma_f32 v[120:121], v[116:117], s[60:61], v[80:81] op_sel_hi:[1,0,0]
	v_exp_f32_e32 v123, v123
	v_pk_fma_f32 v[120:121], v[116:117], v[120:121], s[64:65] op_sel_hi:[1,1,0]
	s_nop 0
	v_pk_fma_f32 v[120:121], v[116:117], v[120:121], s[66:67] op_sel_hi:[1,1,0]
	s_nop 0
	v_pk_fma_f32 v[120:121], v[116:117], v[120:121], s[24:25] op_sel_hi:[1,1,0]
	s_nop 0
	v_pk_mul_f32 v[116:117], v[116:117], v[120:121]
	v_pk_mul_f32 v[120:121], v[104:105], v[104:105]
	v_pk_mul_f32 v[116:117], v[122:123], v[116:117]
	s_nop 0
	v_pk_mul_f32 v[122:123], v[114:115], v[116:117]
	v_pk_fma_f32 v[116:117], v[114:115], v[116:117], v[114:115] neg_lo:[1,0,0] neg_hi:[1,0,0]
	v_and_b32_e32 v114, 0x7fffffff, v104
	v_cndmask_b32_e32 v122, v116, v122, vcc
	v_cmp_gt_f32_e32 vcc, 0, v115
	v_and_b32_e32 v115, 0x7fffffff, v105
	v_pk_fma_f32 v[114:115], v[114:115], s[86:87], 1.0 op_sel_hi:[1,0,0]
	v_cndmask_b32_e32 v123, v117, v123, vcc
	v_rcp_f32_e32 v114, v114
	v_rcp_f32_e32 v115, v115
	v_cmp_gt_f32_e32 vcc, 0, v104
	v_pk_add_f32 v[112:113], v[122:123], v[112:113]
	v_pk_fma_f32 v[110:111], v[122:123], v[122:123], v[110:111]
	v_pk_fma_f32 v[116:117], v[114:115], s[60:61], v[80:81] op_sel_hi:[1,0,0]
	s_nop 0
	v_pk_fma_f32 v[116:117], v[114:115], v[116:117], s[64:65] op_sel_hi:[1,1,0]
	s_nop 0
; __device__ __forceinline__ unsigned cvt_pk_bf16(float lo, float hi) { unsigned r; asm volatile("v_cvt_pk_bf16_f32 %0, %1, %2" : "=v"(r) : "v"(lo), "v"(hi)); return r; }
; __device__ __forceinline__ f32x4 gelu4(f32x4 v) { f32x2 a = gelu_pk((f32x2){v[0], v[1]}), b = gelu_pk((f32x2){v[2], v[3]}); return (f32x4){a.x, a.y, b.x, b.y}; }
; __device__ __forceinline__ f32x2 gelu_pk(f32x2 v) {
;     const f32x2 av = __builtin_elementwise_abs(v), d = av * 0.2316418882f + 1.0f;
;     f32x2 t; t.x = __builtin_amdgcn_rcpf(d.x); t.y = __builtin_amdgcn_rcpf(d.y);
;     f32x2 q = t * 0.5307027145f + (-0.7265760135f); q = q * t + 0.7107068705f; q = q * t + (-0.142248368f); q = q * t + 0.127414796f; q = q * t;
;     const f32x2 s = (v * v) * (-0.72134752044f);
;     f32x2 e; e.x = __builtin_amdgcn_exp2f(s.x); e.y = __builtin_amdgcn_exp2f(s.y);
;     const f32x2 m = v * (q * e), r = v - m;
;     f32x2 o; o.x = v.x < 0.f ? m.x : r.x; o.y = v.y < 0.f ? m.y : r.y; return o;
; }
;     __device__ __forceinline__ void operator()(const f32x4 (&acc)[2][2][4][2], const Unit& u, int wr, int wc, int fr, int fq, int ui) const {
;     ...
;                 f32x4 sm0 = (f32x4){0.f, 0.f, 0.f, 0.f}, sm1 = sm0, sq0 = sm0, sq1 = sm0;
; #pragma unroll
;                 for (int ai = 0; ai < 2; ++ai)
; #pragma unroll
;                     for (int m = 0; m < 4; ++m) {
;                         const int ch = ch0 + ai * 128 + m * 16;
;                         const f32x4 v0 = pg8::gelu4(acc[ai][bj][m][0] * rs0), v1 = pg8::gelu4(acc[ai][bj][m][1] * rs1);
;                         sm0 = sm0 + v0; sm1 = sm1 + v1; sq0 = sq0 + v0 * v0; sq1 = sq1 + v1 * v1;
;                         u32x4 w; w.x = cvt_pk_bf16(v0[0], v0[1]); w.y = cvt_pk_bf16(v0[2], v0[3]); w.z = cvt_pk_bf16(v1[0], v1[1]); w.w = cvt_pk_bf16(v1[2], v1[3]);
;                         *(u32x4*)(Gt + ((size_t)(tok >> 3) * 512 + ch) * 8) = w;
;                     }
	v_pk_fma_f32 v[116:117], v[114:115], v[116:117], s[66:67] op_sel_hi:[1,1,0]
	s_nop 0
	v_pk_fma_f32 v[116:117], v[114:115], v[116:117], s[24:25] op_sel_hi:[1,1,0]
	s_nop 0
	v_pk_mul_f32 v[114:115], v[114:115], v[116:117]
	v_pk_mul_f32 v[116:117], v[120:121], s[84:85] op_sel_hi:[1,0]
	s_nop 0
	v_exp_f32_e32 v116, v116
	v_exp_f32_e32 v117, v117
	s_nop 0
	v_pk_mul_f32 v[114:115], v[116:117], v[114:115]
	s_nop 0
	v_pk_mul_f32 v[116:117], v[104:105], v[114:115]
	v_pk_fma_f32 v[114:115], v[104:105], v[114:115], v[104:105] neg_lo:[1,0,0] neg_hi:[1,0,0]
	s_nop 0
	v_cndmask_b32_e32 v104, v114, v116, vcc
	v_cmp_gt_f32_e32 vcc, 0, v105
	s_nop 1
	v_cndmask_b32_e32 v105, v115, v117, vcc
	v_pk_add_f32 v[114:115], v[118:119], v[106:107]
	v_pk_fma_f32 v[116:117], v[118:119], v[118:119], v[108:109]
	v_cvt_pk_bf16_f32 v106, v118, v119
	v_cvt_pk_bf16_f32 v107, v102, v103
	v_cvt_pk_bf16_f32 v108, v122, v123
	v_cvt_pk_bf16_f32 v109, v104, v105
	global_store_dwordx4 v[84:85], v[106:109], off offset:2304 sc1
	s_nop 1
	v_pk_mul_f32 v[108:109], v[14:15], v[70:71]
	v_pk_mul_f32 v[106:107], v[16:17], v[72:73]
	v_and_b32_e32 v119, 0x7fffffff, v109
	v_and_b32_e32 v118, 0x7fffffff, v108
	v_pk_fma_f32 v[118:119], v[118:119], s[86:87], 1.0 op_sel_hi:[1,0,0]
	v_pk_mul_f32 v[122:123], v[108:109], v[108:109]
	v_rcp_f32_e32 v118, v118
	v_rcp_f32_e32 v119, v119
	v_pk_mul_f32 v[122:123], v[122:123], s[84:85] op_sel_hi:[1,0]
	v_cmp_gt_f32_e32 vcc, 0, v108
	v_exp_f32_e32 v122, v122
	v_pk_fma_f32 v[120:121], v[118:119], s[60:61], v[80:81] op_sel_hi:[1,0,0]
	v_exp_f32_e32 v123, v123
	v_pk_fma_f32 v[120:121], v[118:119], v[120:121], s[64:65] op_sel_hi:[1,1,0]
	s_nop 0
	v_pk_fma_f32 v[120:121], v[118:119], v[120:121], s[66:67] op_sel_hi:[1,1,0]
	s_nop 0
	v_pk_fma_f32 v[120:121], v[118:119], v[120:121], s[24:25] op_sel_hi:[1,1,0]
	s_nop 0
	v_pk_mul_f32 v[118:119], v[118:119], v[120:121]
	v_pk_mul_f32 v[120:121], v[106:107], v[106:107]
	v_pk_mul_f32 v[118:119], v[122:123], v[118:119]
	s_nop 0
	v_pk_mul_f32 v[122:123], v[108:109], v[118:119]
	v_pk_fma_f32 v[118:119], v[108:109], v[118:119], v[108:109] neg_lo:[1,0,0] neg_hi:[1,0,0]
	v_and_b32_e32 v108, 0x7fffffff, v106
	v_cndmask_b32_e32 v122, v118, v122, vcc
	v_cmp_gt_f32_e32 vcc, 0, v109
	v_and_b32_e32 v109, 0x7fffffff, v107
	v_pk_fma_f32 v[108:109], v[108:109], s[86:87], 1.0 op_sel_hi:[1,0,0]
	v_cndmask_b32_e32 v123, v119, v123, vcc
	v_rcp_f32_e32 v108, v108
	v_rcp_f32_e32 v109, v109
	v_cmp_gt_f32_e32 vcc, 0, v106
	v_pk_add_f32 v[114:115], v[122:123], v[114:115]
	v_pk_fma_f32 v[116:117], v[122:123], v[122:123], v[116:117]
	v_pk_fma_f32 v[118:119], v[108:109], s[60:61], v[80:81] op_sel_hi:[1,0,0]
	s_nop 0
	v_pk_fma_f32 v[118:119], v[108:109], v[118:119], s[64:65] op_sel_hi:[1,1,0]
	s_nop 0
	v_pk_fma_f32 v[118:119], v[108:109], v[118:119], s[66:67] op_sel_hi:[1,1,0]
	s_nop 0
	v_pk_fma_f32 v[118:119], v[108:109], v[118:119], s[24:25] op_sel_hi:[1,1,0]
	s_nop 0
	v_pk_mul_f32 v[108:109], v[108:109], v[118:119]
	v_pk_mul_f32 v[118:119], v[120:121], s[84:85] op_sel_hi:[1,0]
	s_nop 0
	v_exp_f32_e32 v118, v118
	v_exp_f32_e32 v119, v119
	s_nop 0
	v_pk_mul_f32 v[108:109], v[118:119], v[108:109]
	s_nop 0
	v_pk_mul_f32 v[118:119], v[106:107], v[108:109]
	v_pk_fma_f32 v[108:109], v[106:107], v[108:109], v[106:107] neg_lo:[1,0,0] neg_hi:[1,0,0]
	s_nop 0
	v_cndmask_b32_e32 v106, v108, v118, vcc
	v_cmp_gt_f32_e32 vcc, 0, v107
	s_nop 1
	v_cndmask_b32_e32 v107, v109, v119, vcc
	v_pk_mul_f32 v[118:119], v[10:11], v[66:67]
	v_pk_mul_f32 v[108:109], v[12:13], v[68:69]
	v_and_b32_e32 v121, 0x7fffffff, v119
	v_and_b32_e32 v120, 0x7fffffff, v118
	v_pk_fma_f32 v[120:121], v[120:121], s[86:87], 1.0 op_sel_hi:[1,0,0]
	v_pk_mul_f32 v[126:127], v[118:119], v[118:119]
	v_rcp_f32_e32 v120, v120
	v_rcp_f32_e32 v121, v121
	v_pk_mul_f32 v[126:127], v[126:127], s[84:85] op_sel_hi:[1,0]
	v_cmp_gt_f32_e32 vcc, 0, v118
	v_exp_f32_e32 v126, v126
	v_pk_fma_f32 v[124:125], v[120:121], s[60:61], v[80:81] op_sel_hi:[1,0,0]
	v_exp_f32_e32 v127, v127
	v_pk_fma_f32 v[124:125], v[120:121], v[124:125], s[64:65] op_sel_hi:[1,1,0]
	s_nop 0
	v_pk_fma_f32 v[124:125], v[120:121], v[124:125], s[66:67] op_sel_hi:[1,1,0]
	s_nop 0
	v_pk_fma_f32 v[124:125], v[120:121], v[124:125], s[24:25] op_sel_hi:[1,1,0]
	s_nop 0
	v_pk_mul_f32 v[120:121], v[120:121], v[124:125]
	v_pk_mul_f32 v[124:125], v[108:109], v[108:109]
	v_pk_mul_f32 v[120:121], v[126:127], v[120:121]
	s_nop 0
	v_pk_mul_f32 v[126:127], v[118:119], v[120:121]
	v_pk_fma_f32 v[120:121], v[118:119], v[120:121], v[118:119] neg_lo:[1,0,0] neg_hi:[1,0,0]
	v_and_b32_e32 v118, 0x7fffffff, v108
	v_cndmask_b32_e32 v126, v120, v126, vcc
	v_cmp_gt_f32_e32 vcc, 0, v119
	v_and_b32_e32 v119, 0x7fffffff, v109
	v_pk_fma_f32 v[118:119], v[118:119], s[86:87], 1.0 op_sel_hi:[1,0,0]
	v_cndmask_b32_e32 v127, v121, v127, vcc
	v_rcp_f32_e32 v118, v118
	v_rcp_f32_e32 v119, v119
	v_cmp_gt_f32_e32 vcc, 0, v108
	v_pk_fma_f32 v[120:121], v[118:119], s[60:61], v[80:81] op_sel_hi:[1,0,0]
	s_nop 0
	v_pk_fma_f32 v[120:121], v[118:119], v[120:121], s[64:65] op_sel_hi:[1,1,0]
	s_nop 0
	v_pk_fma_f32 v[120:121], v[118:119], v[120:121], s[66:67] op_sel_hi:[1,1,0]
	s_nop 0
	v_pk_fma_f32 v[120:121], v[118:119], v[120:121], s[24:25] op_sel_hi:[1,1,0]
	s_nop 0
	v_pk_mul_f32 v[118:119], v[118:119], v[120:121]
	v_pk_mul_f32 v[120:121], v[124:125], s[84:85] op_sel_hi:[1,0]
	s_nop 0
	v_exp_f32_e32 v120, v120
	v_exp_f32_e32 v121, v121
	s_nop 0
	v_pk_mul_f32 v[118:119], v[120:121], v[118:119]
	s_nop 0
	v_pk_mul_f32 v[120:121], v[108:109], v[118:119]
	v_pk_fma_f32 v[118:119], v[108:109], v[118:119], v[108:109] neg_lo:[1,0,0] neg_hi:[1,0,0]
	s_nop 0
	v_cndmask_b32_e32 v108, v118, v120, vcc
; __device__ __forceinline__ unsigned cvt_pk_bf16(float lo, float hi) { unsigned r; asm volatile("v_cvt_pk_bf16_f32 %0, %1, %2" : "=v"(r) : "v"(lo), "v"(hi)); return r; }
; __device__ __forceinline__ f32x4 gelu4(f32x4 v) { f32x2 a = gelu_pk((f32x2){v[0], v[1]}), b = gelu_pk((f32x2){v[2], v[3]}); return (f32x4){a.x, a.y, b.x, b.y}; }
; __device__ __forceinline__ f32x2 gelu_pk(f32x2 v) {
;     const f32x2 av = __builtin_elementwise_abs(v), d = av * 0.2316418882f + 1.0f;
;     f32x2 t; t.x = __builtin_amdgcn_rcpf(d.x); t.y = __builtin_amdgcn_rcpf(d.y);
;     f32x2 q = t * 0.5307027145f + (-0.7265760135f); q = q * t + 0.7107068705f; q = q * t + (-0.142248368f); q = q * t + 0.127414796f; q = q * t;
;     const f32x2 s = (v * v) * (-0.72134752044f);
;     f32x2 e; e.x = __builtin_amdgcn_exp2f(s.x); e.y = __builtin_amdgcn_exp2f(s.y);
;     const f32x2 m = v * (q * e), r = v - m;
;     f32x2 o; o.x = v.x < 0.f ? m.x : r.x; o.y = v.y < 0.f ? m.y : r.y; return o;
; }
;     __device__ __forceinline__ void operator()(const f32x4 (&acc)[2][2][4][2], const Unit& u, int wr, int wc, int fr, int fq, int ui) const {
;     ...
;                         const f32x4 v0 = pg8::gelu4(acc[ai][bj][m][0] * rs0), v1 = pg8::gelu4(acc[ai][bj][m][1] * rs1);
;                         sm0 = sm0 + v0; sm1 = sm1 + v1; sq0 = sq0 + v0 * v0; sq1 = sq1 + v1 * v1;
;                         u32x4 w; w.x = cvt_pk_bf16(v0[0], v0[1]); w.y = cvt_pk_bf16(v0[2], v0[3]); w.z = cvt_pk_bf16(v1[0], v1[1]); w.w = cvt_pk_bf16(v1[2], v1[3]);
;                         *(u32x4*)(Gt + ((size_t)(tok >> 3) * 512 + ch) * 8) = w;
;                     }
	v_cmp_gt_f32_e32 vcc, 0, v109
	s_nop 1
	v_cndmask_b32_e32 v109, v119, v121, vcc
	v_pk_add_f32 v[118:119], v[126:127], v[112:113]
	v_pk_fma_f32 v[120:121], v[126:127], v[126:127], v[110:111]
	v_cvt_pk_bf16_f32 v110, v122, v123
	v_cvt_pk_bf16_f32 v111, v106, v107
	v_cvt_pk_bf16_f32 v112, v126, v127
	v_cvt_pk_bf16_f32 v113, v108, v109
	global_store_dwordx4 v[84:85], v[110:113], off offset:2560 sc1
	s_nop 1
	v_pk_mul_f32 v[112:113], v[6:7], v[70:71]
	v_pk_mul_f32 v[110:111], v[8:9], v[72:73]
	v_and_b32_e32 v123, 0x7fffffff, v113
	v_and_b32_e32 v122, 0x7fffffff, v112
	v_pk_fma_f32 v[122:123], v[122:123], s[86:87], 1.0 op_sel_hi:[1,0,0]
	v_pk_mul_f32 v[126:127], v[112:113], v[112:113]
	v_rcp_f32_e32 v122, v122
	v_rcp_f32_e32 v123, v123
	v_pk_mul_f32 v[126:127], v[126:127], s[84:85] op_sel_hi:[1,0]
	v_cmp_gt_f32_e32 vcc, 0, v112
	v_exp_f32_e32 v126, v126
	v_pk_fma_f32 v[124:125], v[122:123], s[60:61], v[80:81] op_sel_hi:[1,0,0]
	v_exp_f32_e32 v127, v127
	v_pk_fma_f32 v[124:125], v[122:123], v[124:125], s[64:65] op_sel_hi:[1,1,0]
	s_nop 0
	v_pk_fma_f32 v[124:125], v[122:123], v[124:125], s[66:67] op_sel_hi:[1,1,0]
	s_nop 0
	v_pk_fma_f32 v[124:125], v[122:123], v[124:125], s[24:25] op_sel_hi:[1,1,0]
	s_nop 0
	v_pk_mul_f32 v[122:123], v[122:123], v[124:125]
	v_pk_mul_f32 v[124:125], v[110:111], v[110:111]
	v_pk_mul_f32 v[122:123], v[126:127], v[122:123]
	v_pk_mul_f32 v[124:125], v[124:125], s[84:85] op_sel_hi:[1,0]
	v_pk_mul_f32 v[126:127], v[112:113], v[122:123]
	v_pk_fma_f32 v[122:123], v[112:113], v[122:123], v[112:113] neg_lo:[1,0,0] neg_hi:[1,0,0]
	v_and_b32_e32 v112, 0x7fffffff, v110
	v_cndmask_b32_e32 v122, v122, v126, vcc
	v_cmp_gt_f32_e32 vcc, 0, v113
	v_and_b32_e32 v113, 0x7fffffff, v111
	v_pk_fma_f32 v[112:113], v[112:113], s[86:87], 1.0 op_sel_hi:[1,0,0]
	v_cndmask_b32_e32 v123, v123, v127, vcc
	v_rcp_f32_e32 v112, v112
	v_rcp_f32_e32 v113, v113
	v_exp_f32_e32 v124, v124
	v_exp_f32_e32 v125, v125
	v_cmp_gt_f32_e32 vcc, 0, v110
	v_pk_fma_f32 v[126:127], v[112:113], s[60:61], v[80:81] op_sel_hi:[1,0,0]
	v_pk_add_f32 v[114:115], v[122:123], v[114:115]
	v_pk_fma_f32 v[126:127], v[112:113], v[126:127], s[64:65] op_sel_hi:[1,1,0]
	v_pk_fma_f32 v[116:117], v[122:123], v[122:123], v[116:117]
	v_pk_fma_f32 v[126:127], v[112:113], v[126:127], s[66:67] op_sel_hi:[1,1,0]
	v_cvt_pk_bf16_f32 v122, v122, v123
	s_nop 0
	v_pk_fma_f32 v[126:127], v[112:113], v[126:127], s[24:25] op_sel_hi:[1,1,0]
	s_nop 0
	v_pk_mul_f32 v[112:113], v[112:113], v[126:127]
	s_nop 0
	v_pk_mul_f32 v[112:113], v[124:125], v[112:113]
	s_nop 0
	v_pk_mul_f32 v[124:125], v[110:111], v[112:113]
	v_pk_fma_f32 v[112:113], v[110:111], v[112:113], v[110:111] neg_lo:[1,0,0] neg_hi:[1,0,0]
	s_nop 0
	v_cndmask_b32_e32 v110, v112, v124, vcc
	v_cmp_gt_f32_e32 vcc, 0, v111
	s_nop 1
	v_cndmask_b32_e32 v111, v113, v125, vcc
	v_pk_mul_f32 v[124:125], v[2:3], v[66:67]
	v_pk_mul_f32 v[112:113], v[4:5], v[68:69]
	v_and_b32_e32 v127, 0x7fffffff, v125
	v_and_b32_e32 v126, 0x7fffffff, v124
	v_pk_fma_f32 v[126:127], v[126:127], s[86:87], 1.0 op_sel_hi:[1,0,0]
	v_pk_mul_f32 v[130:131], v[124:125], v[124:125]
	v_rcp_f32_e32 v126, v126
	v_rcp_f32_e32 v127, v127
	v_pk_mul_f32 v[130:131], v[130:131], s[84:85] op_sel_hi:[1,0]
	v_cmp_gt_f32_e32 vcc, 0, v124
	v_exp_f32_e32 v130, v130
	v_pk_fma_f32 v[128:129], v[126:127], s[60:61], v[80:81] op_sel_hi:[1,0,0]
	v_exp_f32_e32 v131, v131
	v_pk_fma_f32 v[128:129], v[126:127], v[128:129], s[64:65] op_sel_hi:[1,1,0]
	v_cvt_pk_bf16_f32 v123, v110, v111
	s_nop 0
	v_pk_fma_f32 v[128:129], v[126:127], v[128:129], s[66:67] op_sel_hi:[1,1,0]
	s_nop 0
	v_pk_fma_f32 v[128:129], v[126:127], v[128:129], s[24:25] op_sel_hi:[1,1,0]
	s_nop 0
	v_pk_mul_f32 v[126:127], v[126:127], v[128:129]
	v_pk_mul_f32 v[128:129], v[112:113], v[112:113]
	v_pk_mul_f32 v[126:127], v[130:131], v[126:127]
	s_nop 0
	v_pk_mul_f32 v[130:131], v[124:125], v[126:127]
	v_pk_fma_f32 v[126:127], v[124:125], v[126:127], v[124:125] neg_lo:[1,0,0] neg_hi:[1,0,0]
	s_nop 0
	v_cndmask_b32_e32 v124, v126, v130, vcc
	v_cmp_gt_f32_e32 vcc, 0, v125
	v_and_b32_e32 v126, 0x7fffffff, v112
	s_nop 0
	v_cndmask_b32_e32 v125, v127, v131, vcc
	v_and_b32_e32 v127, 0x7fffffff, v113
	v_pk_fma_f32 v[126:127], v[126:127], s[86:87], 1.0 op_sel_hi:[1,0,0]
	v_cmp_gt_f32_e32 vcc, 0, v112
	v_rcp_f32_e32 v126, v126
	v_rcp_f32_e32 v127, v127
	v_pk_fma_f32 v[120:121], v[124:125], v[124:125], v[120:121]
	v_pk_add_f32 v[118:119], v[124:125], v[118:119]
	v_cvt_pk_bf16_f32 v124, v124, v125
	v_pk_fma_f32 v[80:81], v[126:127], s[60:61], v[80:81] op_sel_hi:[1,0,0]
	s_nop 0
	v_pk_fma_f32 v[80:81], v[126:127], v[80:81], s[64:65] op_sel_hi:[1,1,0]
	s_nop 0
	v_pk_fma_f32 v[80:81], v[126:127], v[80:81], s[66:67] op_sel_hi:[1,1,0]
	s_nop 0
	v_pk_fma_f32 v[80:81], v[126:127], v[80:81], s[24:25] op_sel_hi:[1,1,0]
	s_nop 0
	v_pk_mul_f32 v[80:81], v[126:127], v[80:81]
	v_pk_mul_f32 v[126:127], v[128:129], s[84:85] op_sel_hi:[1,0]
	s_nop 0
	v_exp_f32_e32 v126, v126
	v_exp_f32_e32 v127, v127
	s_nop 0
	v_pk_mul_f32 v[80:81], v[126:127], v[80:81]
	s_nop 0
	v_pk_mul_f32 v[126:127], v[112:113], v[80:81]
	v_pk_fma_f32 v[80:81], v[112:113], v[80:81], v[112:113] neg_lo:[1,0,0] neg_hi:[1,0,0]
	s_nop 0
	v_cndmask_b32_e32 v112, v80, v126, vcc
	v_cmp_gt_f32_e32 vcc, 0, v113
	v_add_u32_e32 v80, 64, v0
	v_xor_b32_e32 v0, 1, v238
	v_cndmask_b32_e32 v113, v81, v127, vcc
	v_cmp_lt_i32_e32 vcc, v0, v80
	v_cvt_pk_bf16_f32 v125, v112, v113
	global_store_dwordx4 v[84:85], v[122:125], off offset:2816 sc1
	s_nop 0
	v_cndmask_b32_e32 v0, v238, v0, vcc
	v_lshlrev_b32_e32 v0, 2, v0
	ds_bpermute_b32 v81, v0, v114
	ds_bpermute_b32 v95, v0, v120
	ds_bpermute_b32 v85, v0, v116
	ds_bpermute_b32 v84, v0, v118
	s_waitcnt lgkmcnt(0)
; __device__ __forceinline__ void fx_add(i64* p, float v) { atomicAdd((unsigned long long*)p, (unsigned long long)(i64)(v * FX)); }
;     __device__ __forceinline__ void operator()(const f32x4 (&acc)[2][2][4][2], const Unit& u, int wr, int wc, int fr, int fq, int ui) const {
;     ...
; #pragma unroll
;                 for (int i = 0; i < 4; ++i) {
;                     float a0 = sm0[i], a1 = sm1[i], b0 = sq0[i], b1 = sq1[i];
; #pragma unroll
;                     for (int o = 1; o < 16; o <<= 1) { a0 += __shfl_xor(a0, o); a1 += __shfl_xor(a1, o); b0 += __shfl_xor(b0, o); b1 += __shfl_xor(b1, o); }
;                     if (fr == 0) { fx_add(lnsum + tok + i, a0); fx_add(lnsum + tok + 4 + i, a1); fx_add(lnsq + tok + i, b0); fx_add(lnsq + tok + 4 + i, b1); }
;                 }
	v_add_f32_e32 v81, v114, v81
	v_add_f32_e32 v114, v120, v95
	v_xor_b32_e32 v95, 2, v238
	v_cmp_lt_i32_e32 vcc, v95, v80
	v_add_f32_e32 v85, v116, v85
	v_add_f32_e32 v84, v118, v84
	v_cndmask_b32_e32 v95, v238, v95, vcc
	v_lshlrev_b32_e32 v95, 2, v95
	ds_bpermute_b32 v116, v95, v81
	s_waitcnt lgkmcnt(0)
	v_add_f32_e32 v81, v81, v116
	ds_bpermute_b32 v116, v95, v84
	s_waitcnt lgkmcnt(0)
	v_add_f32_e32 v84, v84, v116
	ds_bpermute_b32 v116, v95, v85
	s_waitcnt lgkmcnt(0)
	v_add_f32_e32 v85, v85, v116
	ds_bpermute_b32 v116, v95, v114
	s_waitcnt lgkmcnt(0)
	v_add_f32_e32 v116, v114, v116
	v_xor_b32_e32 v114, 4, v238
	v_cmp_lt_i32_e32 vcc, v114, v80
	s_nop 1
	v_cndmask_b32_e32 v114, v238, v114, vcc
	v_lshlrev_b32_e32 v114, 2, v114
	ds_bpermute_b32 v118, v114, v81
	s_waitcnt lgkmcnt(0)
	v_add_f32_e32 v120, v81, v118
	ds_bpermute_b32 v81, v114, v84
	s_waitcnt lgkmcnt(0)
	v_add_f32_e32 v118, v84, v81
	ds_bpermute_b32 v81, v114, v85
	s_waitcnt lgkmcnt(0)
	v_add_f32_e32 v122, v85, v81
	ds_bpermute_b32 v81, v114, v116
	s_waitcnt lgkmcnt(0)
	v_add_f32_e32 v124, v116, v81
	v_xor_b32_e32 v81, 8, v238
	v_cmp_lt_i32_e32 vcc, v81, v80
	s_nop 1
	v_cndmask_b32_e32 v80, v238, v81, vcc
	v_lshlrev_b32_e32 v116, 2, v80
	ds_bpermute_b32 v125, v116, v120
	ds_bpermute_b32 v123, v116, v118
	ds_bpermute_b32 v126, v116, v122
	ds_bpermute_b32 v127, v116, v124
	v_lshlrev_b64 v[80:81], 3, v[74:75]
	v_lshl_add_u64 v[84:85], s[88:89], 0, v[80:81]
	v_lshl_add_u64 v[80:81], s[30:31], 0, v[80:81]
	s_and_saveexec_b64 s[52:53], s[44:45]
	s_cbranch_execz .LBB0_863
	s_waitcnt lgkmcnt(0)
	v_add_f32_e32 v120, v120, v125
	v_mul_f32_e32 v120, 0x4b800000, v120
	v_trunc_f32_e32 v120, v120
	v_add_f32_e32 v75, v124, v127
	v_add_f32_e32 v124, v122, v126
	v_mul_f32_e64 v122, |v120|, s87
	v_floor_f32_e32 v122, v122
	v_fma_f32 v125, v122, s63, |v120|
	v_cvt_u32_f32_e32 v122, v122
	v_cvt_u32_f32_e32 v125, v125
	v_add_f32_e32 v118, v118, v123
	v_ashrrev_i32_e32 v120, 31, v120
	v_xor_b32_e32 v123, v122, v120
	v_xor_b32_e32 v122, v125, v120
	v_mul_f32_e32 v118, 0x4b800000, v118
	v_sub_co_u32_e32 v122, vcc, v122, v120
	v_trunc_f32_e32 v118, v118
	s_nop 0
	v_subb_co_u32_e32 v123, vcc, v123, v120, vcc
	v_mul_f32_e64 v120, |v118|, s87
	v_floor_f32_e32 v120, v120
	v_fma_f32 v125, v120, s63, |v118|
	v_cvt_u32_f32_e32 v125, v125
	v_cvt_u32_f32_e32 v120, v120
	v_ashrrev_i32_e32 v118, 31, v118
	global_atomic_add_x2 v[84:85], v[122:123], off
	v_xor_b32_e32 v122, v125, v118
	v_xor_b32_e32 v120, v120, v118
	v_sub_co_u32_e32 v122, vcc, v122, v118
	v_mul_f32_e32 v75, 0x4b800000, v75
	s_nop 0
	v_subb_co_u32_e32 v123, vcc, v120, v118, vcc
	v_mul_f32_e32 v118, 0x4b800000, v124
	v_trunc_f32_e32 v118, v118
	v_mul_f32_e64 v120, |v118|, s87
	v_floor_f32_e32 v120, v120
	v_fma_f32 v124, v120, s63, |v118|
	v_cvt_u32_f32_e32 v124, v124
	v_cvt_u32_f32_e32 v120, v120
	v_ashrrev_i32_e32 v118, 31, v118
	global_atomic_add_x2 v[84:85], v[122:123], off offset:32
	v_xor_b32_e32 v122, v124, v118
	v_xor_b32_e32 v120, v120, v118
	v_sub_co_u32_e32 v122, vcc, v122, v118
	v_trunc_f32_e32 v75, v75
	s_nop 0
	v_subb_co_u32_e32 v123, vcc, v120, v118, vcc
	v_mul_f32_e64 v118, |v75|, s87
	v_floor_f32_e32 v118, v118
	v_fma_f32 v120, v118, s63, |v75|
	v_cvt_u32_f32_e32 v120, v120
	v_cvt_u32_f32_e32 v118, v118
	v_ashrrev_i32_e32 v75, 31, v75
	global_atomic_add_x2 v[80:81], v[122:123], off
	v_xor_b32_e32 v120, v120, v75
	v_xor_b32_e32 v118, v118, v75
	v_sub_co_u32_e32 v122, vcc, v120, v75
	s_nop 1
	v_subb_co_u32_e32 v123, vcc, v118, v75, vcc
	global_atomic_add_x2 v[80:81], v[122:123], off offset:32

;     __device__ __forceinline__ void operator()(const f32x4 (&acc)[2][2][4][2], const Unit& u, int wr, int wc, int fr, int fq, int ui) const {
;     ...
;                         const size_t bhb = (size_t)(b_ * 8 + (ch >> 6)) * (SEQ * 64) + (size_t)(ch & 63) * 8;
;                         const f32x4 v0 = acc[ai][bj][m][0] * rs0, v1 = acc[ai][bj][m][1] * rs1;
;                         u32x4 w; w.x = cvt_pk_bf16(v0[0], v0[1]); w.y = cvt_pk_bf16(v0[2], v0[3]); w.z = cvt_pk_bf16(v1[0], v1[1]); w.w = cvt_pk_bf16(v1[2], v1[3]);
;                         *(u32x4*)(Vt1 + bhb + (size_t)(t0 >> 3) * 512) = w;
;                         { const unsigned a0 = cvt_pk_bf16(v0[0], v1[0]), a1 = cvt_pk_bf16(v0[1], v1[1]), a2 = cvt_pk_bf16(v0[2], v1[2]), a3 = cvt_pk_bf16(v0[3], v1[3]);
;                           const bool odd = fq & 1;
;                           const unsigned s0 = odd ? a0 : a2, s1 = odd ? a1 : a3;
;                           const unsigned r0 = (unsigned)__shfl_xor((int)s0, 16), r1 = (unsigned)__shfl_xor((int)s1, 16);
;                           const int n = (t0 & ~15) >> 2, rb = odd ? 2 : 0;
;                           bf16_t* p4 = Vt4 + bhb + (size_t)(rb * 256 + (n >> 3)) * 512 + (n & 7);
;                           u32x2 q0, q1; q0.x = odd ? r0 : a0; q0.y = odd ? a2 : r0; q1.x = odd ? r1 : a1; q1.y = odd ? a3 : r1;
;                           *(u32x2*)p4 = q0; *(u32x2*)(p4 + (size_t)256 * 512) = q1; }
;                         { const bool hi = fq & 2;
;                           const unsigned s0 = hi ? w.x : w.z, s1 = hi ? w.y : w.w;
;                           const unsigned r0 = (unsigned)__shfl_xor((int)s0, 32), r1 = (unsigned)__shfl_xor((int)s1, 32);
;                           const unsigned lo0 = hi ? r0 : w.x, lo1 = hi ? r1 : w.y, hi0 = hi ? w.z : r0, hi1 = hi ? w.w : r1;
;                           const int n = (t0 & ~31) >> 4, rb = (t0 & 8) + (hi ? 4 : 0);
;                           bf16_t* p16 = Vt16 + bhb + (size_t)(rb * 64 + (n >> 3)) * 512 + (n & 7);
;                           *(unsigned*)(p16 + (size_t)0 * 64 * 512) = (lo0 & 0xffffu) | (hi0 << 16);
;                           *(unsigned*)(p16 + (size_t)1 * 64 * 512) = (lo0 >> 16) | (hi0 & 0xffff0000u);
;                           *(unsigned*)(p16 + (size_t)2 * 64 * 512) = (lo1 & 0xffffu) | (hi1 << 16);
.LBB0_870:
	v_lshlrev_b32_e32 v0, 4, v74
	s_mov_b32 s4, 0x1fe00
	v_and_or_b32 v75, v0, s4, v153
	v_lshlrev_b32_e32 v0, 2, v74
	s_movk_i32 s4, 0x7e00
	v_and_or_b32 v84, v0, s4, v155
	s_ashr_i32 s4, s36, 6
	s_add_i32 s4, s4, s93
	s_ashr_i32 s5, s4, 31
	s_lshl_b64 s[52:53], s[4:5], 19
	v_mov_b32_e32 v81, s53
	v_or_b32_e32 v80, s52, v146
	v_lshlrev_b64 v[80:81], 1, v[80:81]
	v_lshlrev_b32_e32 v0, 7, v74
	s_waitcnt lgkmcnt(0)
	v_lshl_add_u64 v[82:83], s[42:43], 0, v[80:81]
	v_and_b32_e32 v0, 0xffc00, v0
	v_pk_mul_f32 v[64:65], v[64:65], v[72:73]
	v_pk_mul_f32 v[60:61], v[60:61], v[68:69]
	v_lshl_add_u64 v[82:83], v[82:83], 0, v[0:1]
	v_cvt_pk_bf16_f32 v76, v62, v63
	v_cvt_pk_bf16_f32 v77, v64, v65
	v_cvt_pk_bf16_f32 v78, v58, v59
	v_cvt_pk_bf16_f32 v79, v60, v61
	global_store_dwordx4 v[82:83], v[76:79], off sc1
	v_cvt_pk_bf16_f32 v62, v62, v58
	v_cvt_pk_bf16_f32 v82, v63, v59
	v_cvt_pk_bf16_f32 v63, v64, v60
	v_cvt_pk_bf16_f32 v65, v65, v61
	v_and_b32_e32 v61, 64, v238
	v_xor_b32_e32 v60, 16, v238
	v_add_u32_e32 v85, 64, v61
	v_cmp_lt_i32_e32 vcc, v60, v85
	v_cndmask_b32_e64 v58, v62, v63, s[46:47]
	v_cndmask_b32_e64 v59, v82, v65, s[46:47]
	v_cndmask_b32_e32 v60, v238, v60, vcc
	v_lshlrev_b32_e32 v64, 2, v60
	ds_bpermute_b32 v83, v64, v58
	ds_bpermute_b32 v86, v64, v59
	v_lshl_add_u64 v[60:61], s[76:77], 0, v[80:81]
	v_lshlrev_b32_e32 v58, 1, v75
	v_mov_b32_e32 v59, v1
	s_waitcnt lgkmcnt(0)
	v_cndmask_b32_e64 v62, v83, v62, s[46:47]
	v_cndmask_b32_e64 v63, v63, v83, s[46:47]
	v_cndmask_b32_e64 v83, v65, v86, s[46:47]
	v_xor_b32_e32 v65, 32, v238
	v_lshl_add_u64 v[60:61], v[60:61], 0, v[58:59]
	v_mov_b32_e32 v95, v1
	v_cmp_lt_i32_e32 vcc, v65, v85
	v_lshl_add_u64 v[60:61], v[60:61], 0, v[94:95]
	global_store_dwordx2 v[60:61], v[62:63], off
	v_cndmask_b32_e32 v65, v238, v65, vcc
	v_cndmask_b32_e64 v62, v76, v78, s[48:49]
	v_cndmask_b32_e64 v63, v77, v79, s[48:49]
	v_lshlrev_b32_e32 v65, 2, v65
	ds_bpermute_b32 v62, v65, v62
	ds_bpermute_b32 v63, v65, v63
	v_add_co_u32_e32 v60, vcc, s33, v60
	v_cndmask_b32_e64 v82, v86, v82, s[46:47]
	s_nop 0
	v_addc_co_u32_e32 v61, vcc, 0, v61, vcc
	global_store_dwordx2 v[60:61], v[82:83], off
	s_waitcnt lgkmcnt(0)
	v_cndmask_b32_e64 v82, v62, v76, s[48:49]
	v_cndmask_b32_e64 v83, v63, v77, s[48:49]
	v_cndmask_b32_e64 v78, v78, v62, s[48:49]
	v_cndmask_b32_e64 v79, v79, v63, s[48:49]
	v_lshl_add_u64 v[62:63], s[78:79], 0, v[80:81]
	v_lshlrev_b32_e32 v60, 1, v84
	v_mov_b32_e32 v61, v1
	v_lshl_add_u64 v[76:77], v[62:63], 0, v[60:61]
	v_lshrrev_b32_e32 v62, 3, v74
	v_and_b32_e32 v62, 12, v62
	v_mov_b32_e32 v63, v1
	v_lshl_add_u64 v[74:75], v[76:77], 0, v[62:63]
	v_lshlrev_b32_e32 v76, 16, v78
	v_and_or_b32 v76, v82, s85, v76
	global_store_dword v[74:75], v76, off
	v_lshrrev_b32_e32 v76, 16, v82
	v_and_or_b32 v78, v78, s56, v76
	v_add_co_u32_e32 v76, vcc, s65, v74
	v_pk_mul_f32 v[80:81], v[52:53], v[68:69]
	s_nop 0
	v_addc_co_u32_e32 v77, vcc, 0, v75, vcc
	global_store_dword v[76:77], v78, off
	v_lshlrev_b32_e32 v76, 16, v79
	v_and_or_b32 v78, v83, s85, v76
	v_add_co_u32_e32 v76, vcc, s25, v74
	v_lshl_add_u64 v[52:53], s[42:43], 0, v[0:1]
	s_nop 0
	v_addc_co_u32_e32 v77, vcc, 0, v75, vcc
	global_store_dword v[76:77], v78, off
	v_lshrrev_b32_e32 v76, 16, v83
	v_and_or_b32 v76, v79, s56, v76
	v_mov_b32_e32 v79, s53
	v_or_b32_e32 v78, s52, v150
	v_add_co_u32_e32 v74, vcc, s57, v74
	v_lshlrev_b64 v[78:79], 1, v[78:79]
	s_nop 0
	v_addc_co_u32_e32 v75, vcc, 0, v75, vcc
	v_lshl_add_u64 v[82:83], v[52:53], 0, v[78:79]
	global_store_dword v[74:75], v76, off
	v_pk_mul_f32 v[56:57], v[56:57], v[72:73]
	v_cvt_pk_bf16_f32 v74, v54, v55
	v_pk_mul_f32 v[48:49], v[48:49], v[72:73]
	v_cvt_pk_bf16_f32 v75, v56, v57
	v_cvt_pk_bf16_f32 v76, v50, v51
	v_cvt_pk_bf16_f32 v77, v80, v81
	global_store_dwordx4 v[82:83], v[74:77], off sc1
	v_cvt_pk_bf16_f32 v82, v54, v50
	v_cvt_pk_bf16_f32 v83, v55, v51
	v_cvt_pk_bf16_f32 v80, v56, v80
	v_cvt_pk_bf16_f32 v81, v57, v81
	v_pk_mul_f32 v[44:45], v[44:45], v[68:69]
	v_cndmask_b32_e64 v50, v82, v80, s[46:47]
	ds_bpermute_b32 v57, v64, v50
	v_cndmask_b32_e64 v50, v83, v81, s[46:47]
	ds_bpermute_b32 v84, v64, v50
	v_lshl_add_u64 v[50:51], v[156:157], 0, v[58:59]
	v_lshl_add_u64 v[54:55], v[50:51], 0, v[78:79]
	s_waitcnt lgkmcnt(0)
	v_cndmask_b32_e64 v56, v57, v82, s[46:47]
	v_cndmask_b32_e64 v57, v80, v57, s[46:47]
	global_store_dwordx2 v[54:55], v[56:57], off
	v_cndmask_b32_e64 v56, v74, v76, s[48:49]
	v_cndmask_b32_e64 v57, v75, v77, s[48:49]
	ds_bpermute_b32 v56, v65, v56
	ds_bpermute_b32 v57, v65, v57
	v_add_co_u32_e32 v54, vcc, s33, v54
	v_cndmask_b32_e64 v80, v84, v83, s[46:47]
	v_cndmask_b32_e64 v81, v81, v84, s[46:47]
	v_addc_co_u32_e32 v55, vcc, 0, v55, vcc
	global_store_dwordx2 v[54:55], v[80:81], off
	s_waitcnt lgkmcnt(0)
;     __device__ __forceinline__ void operator()(const f32x4 (&acc)[2][2][4][2], const Unit& u, int wr, int wc, int fr, int fq, int ui) const {
;     ...
;             if (sect == 0) {
;                 const int b_ = tok >> 13, t0 = tok & (SEQ - 1);
; #pragma unroll
;                 for (int ai = 0; ai < 2; ++ai)
; #pragma unroll
;                     for (int m = 0; m < 4; ++m) {
;                         const int ch = ch0 + ai * 128 + m * 16;
;                         const size_t bhb = (size_t)(b_ * 8 + (ch >> 6)) * (SEQ * 64) + (size_t)(ch & 63) * 8;
;                         const f32x4 v0 = acc[ai][bj][m][0] * rs0, v1 = acc[ai][bj][m][1] * rs1;
;                         u32x4 w; w.x = cvt_pk_bf16(v0[0], v0[1]); w.y = cvt_pk_bf16(v0[2], v0[3]); w.z = cvt_pk_bf16(v1[0], v1[1]); w.w = cvt_pk_bf16(v1[2], v1[3]);
;                         *(u32x4*)(Vt1 + bhb + (size_t)(t0 >> 3) * 512) = w;
;                         { const unsigned a0 = cvt_pk_bf16(v0[0], v1[0]), a1 = cvt_pk_bf16(v0[1], v1[1]), a2 = cvt_pk_bf16(v0[2], v1[2]), a3 = cvt_pk_bf16(v0[3], v1[3]);
;                           const bool odd = fq & 1;
;                           const unsigned s0 = odd ? a0 : a2, s1 = odd ? a1 : a3;
;                           const unsigned r0 = (unsigned)__shfl_xor((int)s0, 16), r1 = (unsigned)__shfl_xor((int)s1, 16);
;                           const int n = (t0 & ~15) >> 2, rb = odd ? 2 : 0;
;                           bf16_t* p4 = Vt4 + bhb + (size_t)(rb * 256 + (n >> 3)) * 512 + (n & 7);
;                           u32x2 q0, q1; q0.x = odd ? r0 : a0; q0.y = odd ? a2 : r0; q1.x = odd ? r1 : a1; q1.y = odd ? a3 : r1;
;                           *(u32x2*)p4 = q0; *(u32x2*)(p4 + (size_t)256 * 512) = q1; }
;                         { const bool hi = fq & 2;
;                           const unsigned s0 = hi ? w.x : w.z, s1 = hi ? w.y : w.w;
;                           const unsigned r0 = (unsigned)__shfl_xor((int)s0, 32), r1 = (unsigned)__shfl_xor((int)s1, 32);
;                           const unsigned lo0 = hi ? r0 : w.x, lo1 = hi ? r1 : w.y, hi0 = hi ? w.z : r0, hi1 = hi ? w.w : r1;
;                           const int n = (t0 & ~31) >> 4, rb = (t0 & 8) + (hi ? 4 : 0);
;                           bf16_t* p16 = Vt16 + bhb + (size_t)(rb * 64 + (n >> 3)) * 512 + (n & 7);
	v_cndmask_b32_e64 v80, v57, v75, s[48:49]
	v_cndmask_b32_e64 v75, v76, v56, s[48:49]
	v_lshl_add_u64 v[54:55], s[78:79], 0, v[60:61]
	v_cndmask_b32_e64 v74, v56, v74, s[48:49]
	v_cndmask_b32_e64 v76, v77, v57, s[48:49]
	v_lshl_add_u64 v[54:55], v[54:55], 0, v[62:63]
	v_lshlrev_b32_e32 v77, 16, v75
	v_lshl_add_u64 v[56:57], v[54:55], 0, v[78:79]
	v_and_or_b32 v77, v74, s85, v77
	v_lshrrev_b32_e32 v74, 16, v74
	global_store_dword v[56:57], v77, off
	v_and_or_b32 v77, v75, s56, v74
	v_add_co_u32_e32 v74, vcc, s65, v56
	v_pk_mul_f32 v[36:37], v[36:37], v[68:69]
	s_nop 0
	v_addc_co_u32_e32 v75, vcc, 0, v57, vcc
	global_store_dword v[74:75], v77, off
	v_lshlrev_b32_e32 v74, 16, v76
	v_and_or_b32 v77, v80, s85, v74
	v_add_co_u32_e32 v74, vcc, s25, v56
	s_addk_i32 s36, 0x80
	s_nop 0
	v_addc_co_u32_e32 v75, vcc, 0, v57, vcc
	global_store_dword v[74:75], v77, off
	v_lshrrev_b32_e32 v74, 16, v80
	v_add_co_u32_e32 v56, vcc, s57, v56
	v_and_or_b32 v74, v76, s56, v74
	s_nop 0
	v_addc_co_u32_e32 v57, vcc, 0, v57, vcc
	global_store_dword v[56:57], v74, off
	v_mov_b32_e32 v57, s53
	v_or_b32_e32 v56, s52, v152
	v_lshlrev_b64 v[56:57], 1, v[56:57]
	v_lshl_add_u64 v[78:79], v[52:53], 0, v[56:57]
	v_cvt_pk_bf16_f32 v74, v46, v47
	v_cvt_pk_bf16_f32 v75, v48, v49
	v_cvt_pk_bf16_f32 v76, v42, v43
	v_cvt_pk_bf16_f32 v77, v44, v45
	global_store_dwordx4 v[78:79], v[74:77], off sc1
	v_cvt_pk_bf16_f32 v46, v46, v42
	v_cvt_pk_bf16_f32 v47, v47, v43
	v_cvt_pk_bf16_f32 v48, v48, v44
	v_cvt_pk_bf16_f32 v49, v49, v45
	s_ashr_i32 s4, s36, 6
	v_cndmask_b32_e64 v42, v46, v48, s[46:47]
	ds_bpermute_b32 v45, v64, v42
	v_cndmask_b32_e64 v42, v47, v49, s[46:47]
	ds_bpermute_b32 v78, v64, v42
	v_lshl_add_u64 v[42:43], v[50:51], 0, v[56:57]
	s_add_i32 s4, s4, s93
	s_waitcnt lgkmcnt(0)
	v_cndmask_b32_e64 v44, v45, v46, s[46:47]
	v_cndmask_b32_e64 v45, v48, v45, s[46:47]
	global_store_dwordx2 v[42:43], v[44:45], off
	v_cndmask_b32_e64 v44, v74, v76, s[48:49]
	v_cndmask_b32_e64 v45, v75, v77, s[48:49]
	ds_bpermute_b32 v44, v65, v44
	ds_bpermute_b32 v45, v65, v45
	v_add_co_u32_e32 v42, vcc, s33, v42
	v_cndmask_b32_e64 v46, v78, v47, s[46:47]
	v_cndmask_b32_e64 v47, v49, v78, s[46:47]
	v_addc_co_u32_e32 v43, vcc, 0, v43, vcc
	global_store_dwordx2 v[42:43], v[46:47], off
	s_waitcnt lgkmcnt(0)
	v_cndmask_b32_e64 v46, v44, v74, s[48:49]
	v_cndmask_b32_e64 v44, v76, v44, s[48:49]
	v_cndmask_b32_e64 v47, v45, v75, s[48:49]
	v_cndmask_b32_e64 v48, v77, v45, s[48:49]
	v_lshlrev_b32_e32 v45, 16, v44
	v_lshl_add_u64 v[42:43], v[54:55], 0, v[56:57]
	v_and_or_b32 v45, v46, s85, v45
	global_store_dword v[42:43], v45, off
	v_lshrrev_b32_e32 v45, 16, v46
	v_and_or_b32 v46, v44, s56, v45
	v_add_co_u32_e32 v44, vcc, s65, v42
	s_ashr_i32 s5, s4, 31
	s_nop 0
	v_addc_co_u32_e32 v45, vcc, 0, v43, vcc
	global_store_dword v[44:45], v46, off
	v_lshlrev_b32_e32 v44, 16, v48
	v_and_or_b32 v46, v47, s85, v44
	v_add_co_u32_e32 v44, vcc, s25, v42
	v_pk_mul_f32 v[32:33], v[32:33], v[72:73]
	s_nop 0
	v_addc_co_u32_e32 v45, vcc, 0, v43, vcc
	global_store_dword v[44:45], v46, off
	v_lshrrev_b32_e32 v44, 16, v47
	v_add_co_u32_e32 v42, vcc, s57, v42
	v_and_or_b32 v44, v48, s56, v44
	s_nop 0
	v_addc_co_u32_e32 v43, vcc, 0, v43, vcc
	global_store_dword v[42:43], v44, off
	v_mov_b32_e32 v45, s53
	v_or_b32_e32 v44, s52, v154
	v_lshlrev_b64 v[44:45], 1, v[44:45]
	v_pk_mul_f32 v[46:47], v[40:41], v[72:73]
	v_lshl_add_u64 v[48:49], v[52:53], 0, v[44:45]
	v_cvt_pk_bf16_f32 v40, v38, v39
	v_cvt_pk_bf16_f32 v41, v46, v47
	v_cvt_pk_bf16_f32 v42, v34, v35
	v_cvt_pk_bf16_f32 v43, v36, v37
	global_store_dwordx4 v[48:49], v[40:43], off sc1
	v_cvt_pk_bf16_f32 v38, v38, v34
	v_cvt_pk_bf16_f32 v39, v39, v35
	v_cvt_pk_bf16_f32 v46, v46, v36
	v_cvt_pk_bf16_f32 v47, v47, v37
	s_lshl_b64 s[52:53], s[4:5], 19
	v_cndmask_b32_e64 v34, v38, v46, s[46:47]
	ds_bpermute_b32 v37, v64, v34
	v_cndmask_b32_e64 v34, v39, v47, s[46:47]
	ds_bpermute_b32 v48, v64, v34
	v_lshl_add_u64 v[34:35], v[50:51], 0, v[44:45]
	v_pk_mul_f32 v[22:23], v[22:23], v[70:71]
	s_waitcnt lgkmcnt(0)
	v_cndmask_b32_e64 v36, v37, v38, s[46:47]
	v_cndmask_b32_e64 v37, v46, v37, s[46:47]
	global_store_dwordx2 v[34:35], v[36:37], off
	v_cndmask_b32_e64 v36, v40, v42, s[48:49]
	v_cndmask_b32_e64 v37, v41, v43, s[48:49]
	ds_bpermute_b32 v36, v65, v36
	ds_bpermute_b32 v37, v65, v37
	v_add_co_u32_e32 v34, vcc, s33, v34
	v_cndmask_b32_e64 v38, v48, v39, s[46:47]
	v_cndmask_b32_e64 v39, v47, v48, s[46:47]
	v_addc_co_u32_e32 v35, vcc, 0, v35, vcc
	global_store_dwordx2 v[34:35], v[38:39], off
	s_waitcnt lgkmcnt(0)
	v_cndmask_b32_e64 v38, v36, v40, s[48:49]
	v_cndmask_b32_e64 v36, v42, v36, s[48:49]
	v_cndmask_b32_e64 v39, v37, v41, s[48:49]
	v_cndmask_b32_e64 v40, v43, v37, s[48:49]
	v_lshlrev_b32_e32 v37, 16, v36
	v_lshl_add_u64 v[34:35], v[54:55], 0, v[44:45]
	v_and_or_b32 v37, v38, s85, v37
	global_store_dword v[34:35], v37, off
	v_lshrrev_b32_e32 v37, 16, v38
	v_and_or_b32 v38, v36, s56, v37
	v_add_co_u32_e32 v36, vcc, s65, v34
	v_pk_mul_f32 v[24:25], v[24:25], v[72:73]
	s_nop 0
	v_addc_co_u32_e32 v37, vcc, 0, v35, vcc
	global_store_dword v[36:37], v38, off
	v_lshlrev_b32_e32 v36, 16, v40
	v_and_or_b32 v38, v39, s85, v36
	v_add_co_u32_e32 v36, vcc, s25, v34
	v_pk_mul_f32 v[14:15], v[14:15], v[70:71]
	s_nop 0
	v_addc_co_u32_e32 v37, vcc, 0, v35, vcc
	global_store_dword v[36:37], v38, off
	v_lshrrev_b32_e32 v36, 16, v39
	v_add_co_u32_e32 v34, vcc, s57, v34
	v_and_or_b32 v36, v40, s56, v36
	s_nop 0
	v_addc_co_u32_e32 v35, vcc, 0, v35, vcc
	global_store_dword v[34:35], v36, off
	v_mov_b32_e32 v35, s53
	v_or_b32_e32 v34, s52, v146
	v_lshlrev_b64 v[34:35], 1, v[34:35]
	v_lshl_add_u64 v[40:41], s[42:43], 0, v[34:35]
	v_pk_mul_f32 v[36:37], v[28:29], v[68:69]
	v_pk_mul_f32 v[38:39], v[26:27], v[66:67]
	v_lshl_add_u64 v[40:41], v[40:41], 0, v[0:1]
	v_cvt_pk_bf16_f32 v26, v30, v31
	v_cvt_pk_bf16_f32 v27, v32, v33
	v_cvt_pk_bf16_f32 v28, v38, v39
	v_cvt_pk_bf16_f32 v29, v36, v37
	global_store_dwordx4 v[40:41], v[26:29], off sc1
	v_cvt_pk_bf16_f32 v0, v30, v38
	v_cvt_pk_bf16_f32 v38, v31, v39
	v_cvt_pk_bf16_f32 v36, v32, v36
	v_cvt_pk_bf16_f32 v37, v33, v37
	v_pk_mul_f32 v[16:17], v[16:17], v[72:73]
	v_cndmask_b32_e64 v30, v0, v36, s[46:47]
	ds_bpermute_b32 v33, v64, v30
	v_cndmask_b32_e64 v31, v38, v37, s[46:47]
	ds_bpermute_b32 v39, v64, v31
	v_lshl_add_u64 v[30:31], s[76:77], 0, v[34:35]
	v_lshl_add_u64 v[30:31], v[30:31], 0, v[58:59]
	v_lshl_add_u64 v[30:31], v[30:31], 0, v[94:95]
	s_waitcnt lgkmcnt(0)
;     __device__ __forceinline__ void operator()(const f32x4 (&acc)[2][2][4][2], const Unit& u, int wr, int wc, int fr, int fq, int ui) const {
;     ...
;             if (sect == 0) {
;                 const int b_ = tok >> 13, t0 = tok & (SEQ - 1);
; #pragma unroll
;                 for (int ai = 0; ai < 2; ++ai)
; #pragma unroll
;                     for (int m = 0; m < 4; ++m) {
;                         const int ch = ch0 + ai * 128 + m * 16;
;                         const size_t bhb = (size_t)(b_ * 8 + (ch >> 6)) * (SEQ * 64) + (size_t)(ch & 63) * 8;
;                         const f32x4 v0 = acc[ai][bj][m][0] * rs0, v1 = acc[ai][bj][m][1] * rs1;
;                         u32x4 w; w.x = cvt_pk_bf16(v0[0], v0[1]); w.y = cvt_pk_bf16(v0[2], v0[3]); w.z = cvt_pk_bf16(v1[0], v1[1]); w.w = cvt_pk_bf16(v1[2], v1[3]);
;                         *(u32x4*)(Vt1 + bhb + (size_t)(t0 >> 3) * 512) = w;
;                         { const unsigned a0 = cvt_pk_bf16(v0[0], v1[0]), a1 = cvt_pk_bf16(v0[1], v1[1]), a2 = cvt_pk_bf16(v0[2], v1[2]), a3 = cvt_pk_bf16(v0[3], v1[3]);
;                           const bool odd = fq & 1;
;                           const unsigned s0 = odd ? a0 : a2, s1 = odd ? a1 : a3;
;                           const unsigned r0 = (unsigned)__shfl_xor((int)s0, 16), r1 = (unsigned)__shfl_xor((int)s1, 16);
;                           const int n = (t0 & ~15) >> 2, rb = odd ? 2 : 0;
;                           bf16_t* p4 = Vt4 + bhb + (size_t)(rb * 256 + (n >> 3)) * 512 + (n & 7);
;                           u32x2 q0, q1; q0.x = odd ? r0 : a0; q0.y = odd ? a2 : r0; q1.x = odd ? r1 : a1; q1.y = odd ? a3 : r1;
;                           *(u32x2*)p4 = q0; *(u32x2*)(p4 + (size_t)256 * 512) = q1; }
;                         { const bool hi = fq & 2;
;                           const unsigned s0 = hi ? w.x : w.z, s1 = hi ? w.y : w.w;
;                           const unsigned r0 = (unsigned)__shfl_xor((int)s0, 32), r1 = (unsigned)__shfl_xor((int)s1, 32);
;                           const unsigned lo0 = hi ? r0 : w.x, lo1 = hi ? r1 : w.y, hi0 = hi ? w.z : r0, hi1 = hi ? w.w : r1;
;                           const int n = (t0 & ~31) >> 4, rb = (t0 & 8) + (hi ? 4 : 0);
;                           bf16_t* p16 = Vt16 + bhb + (size_t)(rb * 64 + (n >> 3)) * 512 + (n & 7);
	v_cndmask_b32_e64 v32, v33, v0, s[46:47]
	v_cndmask_b32_e64 v33, v36, v33, s[46:47]
	global_store_dwordx2 v[30:31], v[32:33], off
	v_cndmask_b32_e64 v0, v26, v28, s[48:49]
	v_cndmask_b32_e64 v32, v27, v29, s[48:49]
	ds_bpermute_b32 v0, v65, v0
	ds_bpermute_b32 v32, v65, v32
	v_add_co_u32_e32 v30, vcc, s33, v30
	v_cndmask_b32_e64 v36, v39, v38, s[46:47]
	v_cndmask_b32_e64 v37, v37, v39, s[46:47]
	v_addc_co_u32_e32 v31, vcc, 0, v31, vcc
	global_store_dwordx2 v[30:31], v[36:37], off
	s_waitcnt lgkmcnt(0)
	v_cndmask_b32_e64 v30, v0, v26, s[48:49]
	v_cndmask_b32_e64 v31, v32, v27, s[48:49]
	v_cndmask_b32_e64 v0, v28, v0, s[48:49]
	v_lshl_add_u64 v[26:27], s[78:79], 0, v[34:35]
	v_lshl_add_u64 v[26:27], v[26:27], 0, v[60:61]
	v_lshlrev_b32_e32 v28, 16, v0
	v_lshl_add_u64 v[26:27], v[26:27], 0, v[62:63]
	v_and_or_b32 v28, v30, s85, v28
	global_store_dword v[26:27], v28, off
	v_lshrrev_b32_e32 v28, 16, v30
	v_and_or_b32 v0, v0, s56, v28
	v_add_co_u32_e32 v28, vcc, s65, v26
	v_cndmask_b32_e64 v32, v29, v32, s[48:49]
	s_nop 0
	v_addc_co_u32_e32 v29, vcc, 0, v27, vcc
	global_store_dword v[28:29], v0, off
	v_lshlrev_b32_e32 v0, 16, v32
	v_add_co_u32_e32 v28, vcc, s25, v26
	v_and_or_b32 v0, v31, s85, v0
	s_nop 0
	v_addc_co_u32_e32 v29, vcc, 0, v27, vcc
	global_store_dword v[28:29], v0, off
	v_lshrrev_b32_e32 v0, 16, v31
	v_add_co_u32_e32 v26, vcc, s57, v26
	v_and_or_b32 v0, v32, s56, v0
	s_nop 0
	v_addc_co_u32_e32 v27, vcc, 0, v27, vcc
	global_store_dword v[26:27], v0, off
	v_mov_b32_e32 v27, s53
	v_or_b32_e32 v26, s52, v150
	v_lshlrev_b64 v[26:27], 1, v[26:27]
	v_pk_mul_f32 v[28:29], v[20:21], v[68:69]
	v_pk_mul_f32 v[30:31], v[18:19], v[66:67]
	v_lshl_add_u64 v[32:33], v[52:53], 0, v[26:27]
	v_cvt_pk_bf16_f32 v18, v22, v23
	v_cvt_pk_bf16_f32 v19, v24, v25
	v_cvt_pk_bf16_f32 v20, v30, v31
	v_cvt_pk_bf16_f32 v21, v28, v29
	global_store_dwordx4 v[32:33], v[18:21], off sc1
	v_cvt_pk_bf16_f32 v0, v22, v30
	v_cvt_pk_bf16_f32 v30, v23, v31
	v_cvt_pk_bf16_f32 v28, v24, v28
	v_cvt_pk_bf16_f32 v29, v25, v29
	v_pk_mul_f32 v[6:7], v[6:7], v[70:71]
	v_cndmask_b32_e64 v22, v0, v28, s[46:47]
	ds_bpermute_b32 v25, v64, v22
	v_cndmask_b32_e64 v22, v30, v29, s[46:47]
	ds_bpermute_b32 v31, v64, v22
	v_lshl_add_u64 v[22:23], v[50:51], 0, v[26:27]
	v_pk_mul_f32 v[8:9], v[8:9], v[72:73]
	s_waitcnt lgkmcnt(0)
	v_cndmask_b32_e64 v24, v25, v0, s[46:47]
	v_cndmask_b32_e64 v0, v18, v20, s[48:49]
	v_cndmask_b32_e64 v25, v28, v25, s[46:47]
	ds_bpermute_b32 v0, v65, v0
	global_store_dwordx2 v[22:23], v[24:25], off
	v_cndmask_b32_e64 v24, v19, v21, s[48:49]
	ds_bpermute_b32 v24, v65, v24
	v_add_co_u32_e32 v22, vcc, s33, v22
	v_cndmask_b32_e64 v28, v31, v30, s[46:47]
	v_cndmask_b32_e64 v29, v29, v31, s[46:47]
	v_addc_co_u32_e32 v23, vcc, 0, v23, vcc
	global_store_dwordx2 v[22:23], v[28:29], off
	s_waitcnt lgkmcnt(0)
	v_cndmask_b32_e64 v22, v0, v18, s[48:49]
	v_cndmask_b32_e64 v0, v20, v0, s[48:49]
	v_lshlrev_b32_e32 v20, 16, v0
	v_cndmask_b32_e64 v23, v24, v19, s[48:49]
	v_lshl_add_u64 v[18:19], v[54:55], 0, v[26:27]
	v_and_or_b32 v20, v22, s85, v20
	global_store_dword v[18:19], v20, off
	v_lshrrev_b32_e32 v20, 16, v22
	v_and_or_b32 v0, v0, s56, v20
	v_add_co_u32_e32 v20, vcc, s65, v18
	v_cndmask_b32_e64 v24, v21, v24, s[48:49]
	s_nop 0
	v_addc_co_u32_e32 v21, vcc, 0, v19, vcc
	global_store_dword v[20:21], v0, off
	v_lshlrev_b32_e32 v0, 16, v24
	v_add_co_u32_e32 v20, vcc, s25, v18
	v_and_or_b32 v0, v23, s85, v0
	s_nop 0
	v_addc_co_u32_e32 v21, vcc, 0, v19, vcc
	global_store_dword v[20:21], v0, off
	v_lshrrev_b32_e32 v0, 16, v23
	v_add_co_u32_e32 v18, vcc, s57, v18
	v_and_or_b32 v0, v24, s56, v0
	s_nop 0
	v_addc_co_u32_e32 v19, vcc, 0, v19, vcc
	global_store_dword v[18:19], v0, off
	v_mov_b32_e32 v19, s53
	v_or_b32_e32 v18, s52, v152
	v_lshlrev_b64 v[18:19], 1, v[18:19]
	v_pk_mul_f32 v[20:21], v[12:13], v[68:69]
	v_pk_mul_f32 v[22:23], v[10:11], v[66:67]
	v_lshl_add_u64 v[24:25], v[52:53], 0, v[18:19]
	v_cvt_pk_bf16_f32 v10, v14, v15
	v_cvt_pk_bf16_f32 v11, v16, v17
	v_cvt_pk_bf16_f32 v12, v22, v23
	v_cvt_pk_bf16_f32 v13, v20, v21
	global_store_dwordx4 v[24:25], v[10:13], off sc1
	v_cvt_pk_bf16_f32 v0, v14, v22
	v_cvt_pk_bf16_f32 v22, v15, v23
	v_cvt_pk_bf16_f32 v20, v16, v20
	v_cvt_pk_bf16_f32 v21, v17, v21
	s_nop 0
	v_cndmask_b32_e64 v14, v0, v20, s[46:47]
	ds_bpermute_b32 v17, v64, v14
	v_cndmask_b32_e64 v14, v22, v21, s[46:47]
	ds_bpermute_b32 v23, v64, v14
	v_lshl_add_u64 v[14:15], v[50:51], 0, v[18:19]
	s_waitcnt lgkmcnt(0)
;     __device__ __forceinline__ void operator()(const f32x4 (&acc)[2][2][4][2], const Unit& u, int wr, int wc, int fr, int fq, int ui) const {
;     ...
;             if (sect == 0) {
;                 const int b_ = tok >> 13, t0 = tok & (SEQ - 1);
; #pragma unroll
;                 for (int ai = 0; ai < 2; ++ai)
; #pragma unroll
;                     for (int m = 0; m < 4; ++m) {
;                         const int ch = ch0 + ai * 128 + m * 16;
;                         const size_t bhb = (size_t)(b_ * 8 + (ch >> 6)) * (SEQ * 64) + (size_t)(ch & 63) * 8;
;                         const f32x4 v0 = acc[ai][bj][m][0] * rs0, v1 = acc[ai][bj][m][1] * rs1;
;                         u32x4 w; w.x = cvt_pk_bf16(v0[0], v0[1]); w.y = cvt_pk_bf16(v0[2], v0[3]); w.z = cvt_pk_bf16(v1[0], v1[1]); w.w = cvt_pk_bf16(v1[2], v1[3]);
;                         *(u32x4*)(Vt1 + bhb + (size_t)(t0 >> 3) * 512) = w;
;                         { const unsigned a0 = cvt_pk_bf16(v0[0], v1[0]), a1 = cvt_pk_bf16(v0[1], v1[1]), a2 = cvt_pk_bf16(v0[2], v1[2]), a3 = cvt_pk_bf16(v0[3], v1[3]);
;                           const bool odd = fq & 1;
;                           const unsigned s0 = odd ? a0 : a2, s1 = odd ? a1 : a3;
;                           const unsigned r0 = (unsigned)__shfl_xor((int)s0, 16), r1 = (unsigned)__shfl_xor((int)s1, 16);
;                           const int n = (t0 & ~15) >> 2, rb = odd ? 2 : 0;
;                           bf16_t* p4 = Vt4 + bhb + (size_t)(rb * 256 + (n >> 3)) * 512 + (n & 7);
;                           u32x2 q0, q1; q0.x = odd ? r0 : a0; q0.y = odd ? a2 : r0; q1.x = odd ? r1 : a1; q1.y = odd ? a3 : r1;
;                           *(u32x2*)p4 = q0; *(u32x2*)(p4 + (size_t)256 * 512) = q1; }
;                         { const bool hi = fq & 2;
;                           const unsigned s0 = hi ? w.x : w.z, s1 = hi ? w.y : w.w;
;                           const unsigned r0 = (unsigned)__shfl_xor((int)s0, 32), r1 = (unsigned)__shfl_xor((int)s1, 32);
;                           const unsigned lo0 = hi ? r0 : w.x, lo1 = hi ? r1 : w.y, hi0 = hi ? w.z : r0, hi1 = hi ? w.w : r1;
;                           const int n = (t0 & ~31) >> 4, rb = (t0 & 8) + (hi ? 4 : 0);
;                           bf16_t* p16 = Vt16 + bhb + (size_t)(rb * 64 + (n >> 3)) * 512 + (n & 7);
	v_cndmask_b32_e64 v16, v17, v0, s[46:47]
	v_cndmask_b32_e64 v0, v10, v12, s[48:49]
	v_cndmask_b32_e64 v17, v20, v17, s[46:47]
	ds_bpermute_b32 v0, v65, v0
	global_store_dwordx2 v[14:15], v[16:17], off
	v_cndmask_b32_e64 v16, v11, v13, s[48:49]
	ds_bpermute_b32 v16, v65, v16
	v_add_co_u32_e32 v14, vcc, s33, v14
	v_cndmask_b32_e64 v20, v23, v22, s[46:47]
	v_cndmask_b32_e64 v21, v21, v23, s[46:47]
	v_addc_co_u32_e32 v15, vcc, 0, v15, vcc
	global_store_dwordx2 v[14:15], v[20:21], off
	s_waitcnt lgkmcnt(0)
	v_cndmask_b32_e64 v14, v0, v10, s[48:49]
	v_cndmask_b32_e64 v0, v12, v0, s[48:49]
	v_lshlrev_b32_e32 v12, 16, v0
	v_cndmask_b32_e64 v15, v16, v11, s[48:49]
	v_lshl_add_u64 v[10:11], v[54:55], 0, v[18:19]
	v_and_or_b32 v12, v14, s85, v12
	global_store_dword v[10:11], v12, off
	v_lshrrev_b32_e32 v12, 16, v14
	v_and_or_b32 v0, v0, s56, v12
	v_add_co_u32_e32 v12, vcc, s65, v10
	v_cndmask_b32_e64 v16, v13, v16, s[48:49]
	s_nop 0
	v_addc_co_u32_e32 v13, vcc, 0, v11, vcc
	global_store_dword v[12:13], v0, off
	v_lshlrev_b32_e32 v0, 16, v16
	v_add_co_u32_e32 v12, vcc, s25, v10
	v_and_or_b32 v0, v15, s85, v0
	s_nop 0
	v_addc_co_u32_e32 v13, vcc, 0, v11, vcc
	global_store_dword v[12:13], v0, off
	v_lshrrev_b32_e32 v0, 16, v15
	v_add_co_u32_e32 v10, vcc, s57, v10
	v_and_or_b32 v0, v16, s56, v0
	s_nop 0
	v_addc_co_u32_e32 v11, vcc, 0, v11, vcc
	global_store_dword v[10:11], v0, off
	v_mov_b32_e32 v11, s53
	v_or_b32_e32 v10, s52, v154
	v_lshlrev_b64 v[10:11], 1, v[10:11]
	v_pk_mul_f32 v[12:13], v[4:5], v[68:69]
	v_pk_mul_f32 v[14:15], v[2:3], v[66:67]
	v_lshl_add_u64 v[16:17], v[52:53], 0, v[10:11]
	v_cvt_pk_bf16_f32 v2, v6, v7
	v_cvt_pk_bf16_f32 v3, v8, v9
	v_cvt_pk_bf16_f32 v4, v14, v15
	v_cvt_pk_bf16_f32 v5, v12, v13
	global_store_dwordx4 v[16:17], v[2:5], off sc1
	v_cvt_pk_bf16_f32 v0, v6, v14
	v_cvt_pk_bf16_f32 v14, v7, v15
	v_cvt_pk_bf16_f32 v12, v8, v12
	v_cvt_pk_bf16_f32 v13, v9, v13
	s_nop 0
	v_cndmask_b32_e64 v6, v0, v12, s[46:47]
	ds_bpermute_b32 v9, v64, v6
	v_cndmask_b32_e64 v6, v14, v13, s[46:47]
	ds_bpermute_b32 v15, v64, v6
	v_lshl_add_u64 v[6:7], v[50:51], 0, v[10:11]
	s_waitcnt lgkmcnt(0)
	v_cndmask_b32_e64 v8, v9, v0, s[46:47]
	v_cndmask_b32_e64 v0, v2, v4, s[48:49]
	v_cndmask_b32_e64 v9, v12, v9, s[46:47]
	ds_bpermute_b32 v0, v65, v0
	global_store_dwordx2 v[6:7], v[8:9], off
	v_cndmask_b32_e64 v8, v3, v5, s[48:49]
	ds_bpermute_b32 v8, v65, v8
	v_add_co_u32_e32 v6, vcc, s33, v6
	v_cndmask_b32_e64 v12, v15, v14, s[46:47]
	v_cndmask_b32_e64 v13, v13, v15, s[46:47]
	v_addc_co_u32_e32 v7, vcc, 0, v7, vcc
	global_store_dwordx2 v[6:7], v[12:13], off
	s_waitcnt lgkmcnt(0)
	v_cndmask_b32_e64 v6, v0, v2, s[48:49]
	v_cndmask_b32_e64 v0, v4, v0, s[48:49]
	v_lshlrev_b32_e32 v4, 16, v0
	v_cndmask_b32_e64 v7, v8, v3, s[48:49]
	v_lshl_add_u64 v[2:3], v[54:55], 0, v[10:11]
	v_and_or_b32 v4, v6, s85, v4
	global_store_dword v[2:3], v4, off
	v_lshrrev_b32_e32 v4, 16, v6
	v_and_or_b32 v0, v0, s56, v4
	v_add_co_u32_e32 v4, vcc, 0x10000, v2
	v_cndmask_b32_e64 v8, v5, v8, s[48:49]
	s_nop 0
	v_addc_co_u32_e32 v5, vcc, 0, v3, vcc
	global_store_dword v[4:5], v0, off
	v_lshlrev_b32_e32 v0, 16, v8
	v_add_co_u32_e32 v4, vcc, 0x20000, v2
	v_and_or_b32 v0, v7, s85, v0
	s_nop 0
	v_addc_co_u32_e32 v5, vcc, 0, v3, vcc
	global_store_dword v[4:5], v0, off
	v_lshrrev_b32_e32 v0, 16, v7
	v_add_co_u32_e32 v2, vcc, 0x30000, v2
	v_and_or_b32 v0, v8, s56, v0
	s_nop 0
	v_addc_co_u32_e32 v3, vcc, 0, v3, vcc
	global_store_dword v[2:3], v0, off
	s_andn2_b64 vcc, exec, s[50:51]
	s_mov_b64 s[50:51], -1
	s_cbranch_vccnz .LBB0_835
